# mixer items (gMLP, pool, attention): s_setprio 1/0 around each MFMA cluster, as the GEMM loops already do
# speedup vs baseline: 1.0005x; 1.0005x over previous
.LBB0_1221:
	ds_read_b64_tr_b16 v[4:5], v32
	ds_read_b64_tr_b16 v[8:9], v32 offset:32
	ds_read_b64_tr_b16 v[12:13], v32 offset:64
	ds_read_b64_tr_b16 v[16:17], v32 offset:96
	ds_read_b64_tr_b16 v[6:7], v32 offset:1152
	ds_read_b64_tr_b16 v[10:11], v32 offset:1184
	ds_read_b64_tr_b16 v[14:15], v32 offset:1216
	ds_read_b64_tr_b16 v[18:19], v32 offset:1248
	ds_read_b64_tr_b16 v[34:35], v32 offset:128
	ds_read_b64_tr_b16 v[42:43], v32 offset:160
	ds_read_b64_tr_b16 v[92:93], v32 offset:192
	ds_read_b64_tr_b16 v[96:97], v32 offset:224
	ds_read_b64_tr_b16 v[36:37], v32 offset:1280
	ds_read_b64_tr_b16 v[44:45], v32 offset:1312
	ds_read_b64_tr_b16 v[94:95], v32 offset:1344
	ds_read_b64_tr_b16 v[98:99], v32 offset:1376
	s_waitcnt vmcnt(20) lgkmcnt(11)
	s_setprio 1
	v_mfma_f32_16x16x32_bf16 v[28:31], v[4:7], v[50:53], 0
	s_waitcnt lgkmcnt(10)
	v_mfma_f32_16x16x32_bf16 v[24:27], v[8:11], v[50:53], 0
	s_waitcnt lgkmcnt(9)
	v_mfma_f32_16x16x32_bf16 v[20:23], v[12:15], v[50:53], 0
	s_waitcnt lgkmcnt(8)
	v_mfma_f32_16x16x32_bf16 v[16:19], v[16:19], v[50:53], 0
	s_waitcnt lgkmcnt(3)
	v_mfma_f32_16x16x32_bf16 v[12:15], v[34:37], v[50:53], 0
	s_waitcnt lgkmcnt(2)
	v_mfma_f32_16x16x32_bf16 v[8:11], v[42:45], v[50:53], 0
	s_waitcnt lgkmcnt(1)
	v_mfma_f32_16x16x32_bf16 v[4:7], v[92:95], v[50:53], 0
	s_waitcnt lgkmcnt(0)
	v_mfma_f32_16x16x32_bf16 v[42:45], v[96:99], v[50:53], 0
	s_setprio 0
	s_nop 7
	v_mov_b32_e32 v34, v42
	v_mov_b32_e32 v35, v43
	v_mov_b32_e32 v36, v44
	v_mov_b32_e32 v37, v45
	s_cmp_lt_i32 s8, 1
	s_cbranch_scc1 .LBB0_1219
.LBB0_1222:
	ds_read_b64_tr_b16 v[34:35], v32 offset:9216
	s_waitcnt vmcnt(20)
	ds_read_b64_tr_b16 v[50:51], v32 offset:9248
	ds_read_b64_tr_b16 v[92:93], v32 offset:9280
	ds_read_b64_tr_b16 v[96:97], v32 offset:9312
	ds_read_b64_tr_b16 v[36:37], v32 offset:10368
	ds_read_b64_tr_b16 v[52:53], v32 offset:10400
	ds_read_b64_tr_b16 v[94:95], v32 offset:10432
	ds_read_b64_tr_b16 v[98:99], v32 offset:10464
	ds_read_b64_tr_b16 v[100:101], v32 offset:9344
	ds_read_b64_tr_b16 v[104:105], v32 offset:9376
	ds_read_b64_tr_b16 v[108:109], v32 offset:9408
	ds_read_b64_tr_b16 v[112:113], v32 offset:9440
	ds_read_b64_tr_b16 v[102:103], v32 offset:10496
	ds_read_b64_tr_b16 v[106:107], v32 offset:10528
	ds_read_b64_tr_b16 v[110:111], v32 offset:10560
	ds_read_b64_tr_b16 v[114:115], v32 offset:10592
	s_waitcnt vmcnt(19) lgkmcnt(11)
	s_setprio 1
	v_mfma_f32_16x16x32_bf16 v[28:31], v[34:37], v[46:49], v[28:31]
	s_waitcnt lgkmcnt(10)
	v_mfma_f32_16x16x32_bf16 v[24:27], v[50:53], v[46:49], v[24:27]
	s_waitcnt lgkmcnt(9)
	v_mfma_f32_16x16x32_bf16 v[20:23], v[92:95], v[46:49], v[20:23]
	s_waitcnt lgkmcnt(8)
	v_mfma_f32_16x16x32_bf16 v[16:19], v[96:99], v[46:49], v[16:19]
	s_waitcnt lgkmcnt(3)
	v_mfma_f32_16x16x32_bf16 v[12:15], v[100:103], v[46:49], v[12:15]
	s_waitcnt lgkmcnt(2)
	v_mfma_f32_16x16x32_bf16 v[8:11], v[104:107], v[46:49], v[8:11]
	s_waitcnt lgkmcnt(1)
	v_mfma_f32_16x16x32_bf16 v[4:7], v[108:111], v[46:49], v[4:7]
	s_waitcnt lgkmcnt(0)
	v_mfma_f32_16x16x32_bf16 v[34:37], v[112:115], v[46:49], v[42:45]
	s_setprio 0
	s_cmp_lt_i32 s8, 2
	s_cbranch_scc1 .LBB0_1220
.LBB0_1223:
	s_nop 0
	ds_read_b64_tr_b16 v[42:43], v32 offset:18432
	s_waitcnt vmcnt(19)
	ds_read_b64_tr_b16 v[46:47], v32 offset:18464
	ds_read_b64_tr_b16 v[50:51], v32 offset:18496
	ds_read_b64_tr_b16 v[92:93], v32 offset:18528
	ds_read_b64_tr_b16 v[44:45], v32 offset:19584
	ds_read_b64_tr_b16 v[48:49], v32 offset:19616
	ds_read_b64_tr_b16 v[52:53], v32 offset:19648
	ds_read_b64_tr_b16 v[94:95], v32 offset:19680
	ds_read_b64_tr_b16 v[96:97], v32 offset:18560
	ds_read_b64_tr_b16 v[100:101], v32 offset:18592
	ds_read_b64_tr_b16 v[104:105], v32 offset:18624
	ds_read_b64_tr_b16 v[108:109], v32 offset:18656
	ds_read_b64_tr_b16 v[98:99], v32 offset:19712
	ds_read_b64_tr_b16 v[102:103], v32 offset:19744
	ds_read_b64_tr_b16 v[106:107], v32 offset:19776
	ds_read_b64_tr_b16 v[110:111], v32 offset:19808
	s_waitcnt vmcnt(18) lgkmcnt(11)
	s_setprio 1
	v_mfma_f32_16x16x32_bf16 v[28:31], v[42:45], v[38:41], v[28:31]
	s_waitcnt lgkmcnt(10)
	v_mfma_f32_16x16x32_bf16 v[24:27], v[46:49], v[38:41], v[24:27]
	s_waitcnt lgkmcnt(9)
	v_mfma_f32_16x16x32_bf16 v[20:23], v[50:53], v[38:41], v[20:23]
	s_waitcnt lgkmcnt(8)
	v_mfma_f32_16x16x32_bf16 v[16:19], v[92:95], v[38:41], v[16:19]
	s_waitcnt lgkmcnt(3)
	v_mfma_f32_16x16x32_bf16 v[12:15], v[96:99], v[38:41], v[12:15]
	s_waitcnt lgkmcnt(2)
	v_mfma_f32_16x16x32_bf16 v[8:11], v[100:103], v[38:41], v[8:11]
	s_waitcnt lgkmcnt(1)
	v_mfma_f32_16x16x32_bf16 v[4:7], v[104:107], v[38:41], v[4:7]
	s_waitcnt lgkmcnt(0)
	v_mfma_f32_16x16x32_bf16 v[34:37], v[108:111], v[38:41], v[34:37]
	s_setprio 0
	s_cmp_lt_i32 s8, 3
	s_cbranch_scc1 .LBB0_1176
.LBB0_1224:
	s_waitcnt vmcnt(18)
	ds_read_b64_tr_b16 v[38:39], v32 offset:27648
	ds_read_b64_tr_b16 v[42:43], v32 offset:27680
	ds_read_b64_tr_b16 v[46:47], v32 offset:27712
	ds_read_b64_tr_b16 v[50:51], v32 offset:27744
	ds_read_b64_tr_b16 v[40:41], v32 offset:28800
	ds_read_b64_tr_b16 v[44:45], v32 offset:28832
	ds_read_b64_tr_b16 v[48:49], v32 offset:28864
	ds_read_b64_tr_b16 v[52:53], v32 offset:28896
	ds_read_b64_tr_b16 v[92:93], v32 offset:27776
	ds_read_b64_tr_b16 v[96:97], v32 offset:27808
	ds_read_b64_tr_b16 v[100:101], v32 offset:27840
	ds_read_b64_tr_b16 v[104:105], v32 offset:27872
	ds_read_b64_tr_b16 v[94:95], v32 offset:28928
	ds_read_b64_tr_b16 v[98:99], v32 offset:28960
	ds_read_b64_tr_b16 v[102:103], v32 offset:28992
	ds_read_b64_tr_b16 v[106:107], v32 offset:29024
	s_waitcnt vmcnt(17) lgkmcnt(11)
	s_setprio 1
	v_mfma_f32_16x16x32_bf16 v[28:31], v[38:41], v[0:3], v[28:31]
	s_waitcnt lgkmcnt(10)
	v_mfma_f32_16x16x32_bf16 v[24:27], v[42:45], v[0:3], v[24:27]
	s_waitcnt lgkmcnt(9)
	v_mfma_f32_16x16x32_bf16 v[20:23], v[46:49], v[0:3], v[20:23]
	s_waitcnt lgkmcnt(8)
	v_mfma_f32_16x16x32_bf16 v[16:19], v[50:53], v[0:3], v[16:19]
	s_waitcnt lgkmcnt(3)
	v_mfma_f32_16x16x32_bf16 v[12:15], v[92:95], v[0:3], v[12:15]
	s_waitcnt lgkmcnt(2)
	v_mfma_f32_16x16x32_bf16 v[8:11], v[96:99], v[0:3], v[8:11]
	s_waitcnt lgkmcnt(1)
	v_mfma_f32_16x16x32_bf16 v[4:7], v[100:103], v[0:3], v[4:7]
	s_waitcnt lgkmcnt(0)
	v_mfma_f32_16x16x32_bf16 v[34:37], v[104:107], v[0:3], v[34:37]
	s_setprio 0
	s_branch .LBB0_1176

.Lpf_ret_k3:
	global_load_dwordx2 v[96:97], v[94:95], off
	global_load_dwordx2 v[92:93], v[78:79], off offset:32
	global_load_dwordx2 v[90:91], v[78:79], off offset:64
	global_load_dwordx2 v[88:89], v[78:79], off offset:96
	global_load_dwordx2 v[86:87], v[78:79], off offset:128
	global_load_dwordx2 v[84:85], v[78:79], off offset:160
	global_load_dwordx2 v[82:83], v[78:79], off offset:192
	global_load_dwordx2 v[80:81], v[78:79], off offset:224
	v_add_u32_e32 v32, 0, v106
	v_mad_u32_u24 v126, v108, s33, v32
	ds_read_b128 v[4:7], v126
	ds_read_b128 v[8:11], v126 offset:64
	ds_read_b128 v[12:15], v126 offset:128
	ds_read_b128 v[16:19], v126 offset:192
	ds_read_b128 v[20:23], v126 offset:4352
	ds_read_b128 v[24:27], v126 offset:4416
	ds_read_b128 v[28:31], v126 offset:4480
	ds_read_b128 v[34:37], v126 offset:4544
	s_waitcnt lgkmcnt(7)
	s_setprio 1
	v_mfma_f32_16x16x32_bf16 v[4:7], v[4:7], v[0:3], 0
	s_waitcnt lgkmcnt(6)
	v_mfma_f32_16x16x32_bf16 v[4:7], v[8:11], v[62:65], v[4:7]
	s_waitcnt lgkmcnt(5)
	v_mfma_f32_16x16x32_bf16 v[4:7], v[12:15], v[66:69], v[4:7]
	s_waitcnt lgkmcnt(4)
	v_mfma_f32_16x16x32_bf16 v[74:77], v[16:19], v[70:73], v[4:7]
	s_waitcnt lgkmcnt(3)
	v_mfma_f32_16x16x32_bf16 v[4:7], v[20:23], v[0:3], 0
	s_waitcnt lgkmcnt(2)
	v_mfma_f32_16x16x32_bf16 v[4:7], v[24:27], v[62:65], v[4:7]
	s_waitcnt lgkmcnt(1)
	v_mfma_f32_16x16x32_bf16 v[4:7], v[28:31], v[66:69], v[4:7]
	s_waitcnt lgkmcnt(0)
	v_mfma_f32_16x16x32_bf16 v[58:61], v[34:37], v[70:73], v[4:7]
	s_setprio 0
	v_or_b32_e32 v20, 48, v98
	v_mad_u32_u24 v34, v20, s33, v32
	s_nop 3
	ds_read_b128 v[4:7], v126 offset:8704
	ds_read_b128 v[8:11], v126 offset:8768
	ds_read_b128 v[12:15], v126 offset:8832
	ds_read_b128 v[16:19], v126 offset:8896
	ds_read_b128 v[20:23], v34
	ds_read_b128 v[24:27], v34 offset:64
	ds_read_b128 v[28:31], v34 offset:128
	ds_read_b128 v[34:37], v34 offset:192
	s_waitcnt lgkmcnt(7)
	s_setprio 1
	v_mfma_f32_16x16x32_bf16 v[4:7], v[4:7], v[0:3], 0
	s_waitcnt lgkmcnt(6)
	v_mfma_f32_16x16x32_bf16 v[4:7], v[8:11], v[62:65], v[4:7]
	s_waitcnt lgkmcnt(5)
	v_mfma_f32_16x16x32_bf16 v[4:7], v[12:15], v[66:69], v[4:7]
	s_waitcnt lgkmcnt(4)
	v_mfma_f32_16x16x32_bf16 v[54:57], v[16:19], v[70:73], v[4:7]
	s_waitcnt lgkmcnt(3)
	v_mfma_f32_16x16x32_bf16 v[4:7], v[20:23], v[0:3], 0
	s_waitcnt lgkmcnt(2)
	v_mfma_f32_16x16x32_bf16 v[4:7], v[24:27], v[62:65], v[4:7]
	s_waitcnt lgkmcnt(1)
	v_mfma_f32_16x16x32_bf16 v[4:7], v[28:31], v[66:69], v[4:7]
	s_waitcnt lgkmcnt(0)
	v_mfma_f32_16x16x32_bf16 v[50:53], v[34:37], v[70:73], v[4:7]
	s_setprio 0
	s_nop 5
	ds_read_b128 v[4:7], v126 offset:17408
	ds_read_b128 v[8:11], v126 offset:17472
	ds_read_b128 v[12:15], v126 offset:17536
	ds_read_b128 v[16:19], v126 offset:17600
	ds_read_b128 v[20:23], v126 offset:21760
	ds_read_b128 v[24:27], v126 offset:21824
	ds_read_b128 v[28:31], v126 offset:21888
	ds_read_b128 v[34:37], v126 offset:21952
	s_waitcnt lgkmcnt(7)
	s_setprio 1
	v_mfma_f32_16x16x32_bf16 v[4:7], v[4:7], v[0:3], 0
	s_waitcnt lgkmcnt(6)
	v_mfma_f32_16x16x32_bf16 v[4:7], v[8:11], v[62:65], v[4:7]
	s_waitcnt lgkmcnt(5)
	v_mfma_f32_16x16x32_bf16 v[4:7], v[12:15], v[66:69], v[4:7]
	s_waitcnt lgkmcnt(4)
	v_mfma_f32_16x16x32_bf16 v[46:49], v[16:19], v[70:73], v[4:7]
	s_waitcnt lgkmcnt(3)
	v_mfma_f32_16x16x32_bf16 v[4:7], v[20:23], v[0:3], 0
	s_waitcnt lgkmcnt(2)
	v_mfma_f32_16x16x32_bf16 v[4:7], v[24:27], v[62:65], v[4:7]
	s_waitcnt lgkmcnt(1)
	v_mfma_f32_16x16x32_bf16 v[4:7], v[28:31], v[66:69], v[4:7]
	s_waitcnt lgkmcnt(0)
	v_mfma_f32_16x16x32_bf16 v[42:45], v[34:37], v[70:73], v[4:7]
	s_setprio 0
	v_or_b32_e32 v20, 0x70, v98
	v_mad_u32_u24 v34, v20, s33, v32
	s_nop 3
	ds_read_b128 v[4:7], v126 offset:26112
	ds_read_b128 v[8:11], v126 offset:26176
	ds_read_b128 v[12:15], v126 offset:26240
	ds_read_b128 v[16:19], v126 offset:26304
	ds_read_b128 v[20:23], v34
	ds_read_b128 v[24:27], v34 offset:64
	ds_read_b128 v[28:31], v34 offset:128
	ds_read_b128 v[34:37], v34 offset:192
	s_waitcnt lgkmcnt(7)
	s_setprio 1
	v_mfma_f32_16x16x32_bf16 v[4:7], v[4:7], v[0:3], 0
	s_waitcnt lgkmcnt(6)
	v_mfma_f32_16x16x32_bf16 v[4:7], v[8:11], v[62:65], v[4:7]
	s_waitcnt lgkmcnt(5)
	v_mfma_f32_16x16x32_bf16 v[4:7], v[12:15], v[66:69], v[4:7]
	s_waitcnt lgkmcnt(4)
	v_mfma_f32_16x16x32_bf16 v[38:41], v[16:19], v[70:73], v[4:7]
	s_waitcnt lgkmcnt(3)
	v_mfma_f32_16x16x32_bf16 v[4:7], v[20:23], v[0:3], 0
	s_waitcnt lgkmcnt(2)
	v_mfma_f32_16x16x32_bf16 v[4:7], v[24:27], v[62:65], v[4:7]
	s_waitcnt lgkmcnt(1)
	v_mfma_f32_16x16x32_bf16 v[4:7], v[28:31], v[66:69], v[4:7]
	s_waitcnt lgkmcnt(0)
	v_mfma_f32_16x16x32_bf16 v[34:37], v[34:37], v[70:73], v[4:7]
	s_setprio 0
	s_nop 5
	ds_read_b128 v[4:7], v126 offset:34816
	ds_read_b128 v[8:11], v126 offset:34880
	ds_read_b128 v[12:15], v126 offset:34944
	ds_read_b128 v[16:19], v126 offset:35008
	ds_read_b128 v[20:23], v126 offset:39168
	ds_read_b128 v[24:27], v126 offset:39232
	ds_read_b128 v[106:109], v126 offset:39296
	ds_read_b128 v[110:113], v126 offset:39360
	s_waitcnt lgkmcnt(7)
	s_setprio 1
	v_mfma_f32_16x16x32_bf16 v[4:7], v[4:7], v[0:3], 0
	s_waitcnt lgkmcnt(6)
	v_mfma_f32_16x16x32_bf16 v[4:7], v[8:11], v[62:65], v[4:7]
	s_waitcnt lgkmcnt(5)
	v_mfma_f32_16x16x32_bf16 v[4:7], v[12:15], v[66:69], v[4:7]
	s_waitcnt lgkmcnt(4)
	v_mfma_f32_16x16x32_bf16 v[28:31], v[16:19], v[70:73], v[4:7]
	s_waitcnt lgkmcnt(3)
	v_mfma_f32_16x16x32_bf16 v[4:7], v[20:23], v[0:3], 0
	s_waitcnt lgkmcnt(2)
	v_mfma_f32_16x16x32_bf16 v[4:7], v[24:27], v[62:65], v[4:7]
	s_waitcnt lgkmcnt(1)
	v_mfma_f32_16x16x32_bf16 v[4:7], v[106:109], v[66:69], v[4:7]
	s_waitcnt lgkmcnt(0)
	v_mfma_f32_16x16x32_bf16 v[24:27], v[110:113], v[70:73], v[4:7]
	s_setprio 0
	v_or_b32_e32 v20, 0xb0, v98
	v_mad_u32_u24 v20, v20, s33, v32
	s_nop 3
	ds_read_b128 v[4:7], v126 offset:43520
	ds_read_b128 v[8:11], v126 offset:43584
	ds_read_b128 v[12:15], v126 offset:43648
	ds_read_b128 v[16:19], v126 offset:43712
	ds_read_b128 v[106:109], v20
	ds_read_b128 v[110:113], v20 offset:64
	ds_read_b128 v[114:117], v20 offset:128
	ds_read_b128 v[118:121], v20 offset:192
	s_waitcnt lgkmcnt(7)
	s_setprio 1
	v_mfma_f32_16x16x32_bf16 v[4:7], v[4:7], v[0:3], 0
	s_waitcnt lgkmcnt(6)
	v_mfma_f32_16x16x32_bf16 v[4:7], v[8:11], v[62:65], v[4:7]
	s_waitcnt lgkmcnt(5)
	v_mfma_f32_16x16x32_bf16 v[4:7], v[12:15], v[66:69], v[4:7]
	s_waitcnt lgkmcnt(4)
	v_mfma_f32_16x16x32_bf16 v[20:23], v[16:19], v[70:73], v[4:7]
	s_waitcnt lgkmcnt(3)
	v_mfma_f32_16x16x32_bf16 v[4:7], v[106:109], v[0:3], 0
	s_waitcnt lgkmcnt(2)
	v_mfma_f32_16x16x32_bf16 v[4:7], v[110:113], v[62:65], v[4:7]
	s_waitcnt lgkmcnt(1)
	v_mfma_f32_16x16x32_bf16 v[4:7], v[114:117], v[66:69], v[4:7]
	s_waitcnt lgkmcnt(0)
	v_mfma_f32_16x16x32_bf16 v[16:19], v[118:121], v[70:73], v[4:7]
	s_setprio 0
	s_nop 5
	ds_read_b128 v[4:7], v126 offset:52224
	ds_read_b128 v[8:11], v126 offset:52288
	ds_read_b128 v[12:15], v126 offset:52352
	ds_read_b128 v[106:109], v126 offset:52416
	ds_read_b128 v[110:113], v126 offset:56576
	ds_read_b128 v[114:117], v126 offset:56640
	ds_read_b128 v[118:121], v126 offset:56704
	ds_read_b128 v[122:125], v126 offset:56768
	s_waitcnt lgkmcnt(7)
	s_setprio 1
	v_mfma_f32_16x16x32_bf16 v[4:7], v[4:7], v[0:3], 0
	s_waitcnt lgkmcnt(6)
	v_mfma_f32_16x16x32_bf16 v[4:7], v[8:11], v[62:65], v[4:7]
	s_waitcnt lgkmcnt(5)
	v_mfma_f32_16x16x32_bf16 v[4:7], v[12:15], v[66:69], v[4:7]
	s_waitcnt lgkmcnt(4)
	v_mfma_f32_16x16x32_bf16 v[12:15], v[106:109], v[70:73], v[4:7]
	s_waitcnt lgkmcnt(3)
	v_mfma_f32_16x16x32_bf16 v[4:7], v[110:113], v[0:3], 0
	s_waitcnt lgkmcnt(2)
	v_mfma_f32_16x16x32_bf16 v[4:7], v[114:117], v[62:65], v[4:7]
	s_waitcnt lgkmcnt(1)
	v_mfma_f32_16x16x32_bf16 v[4:7], v[118:121], v[66:69], v[4:7]
	s_waitcnt lgkmcnt(0)
	v_mfma_f32_16x16x32_bf16 v[8:11], v[122:125], v[70:73], v[4:7]
	s_setprio 0
	v_or_b32_e32 v118, 0xf0, v98
	v_mad_u32_u24 v32, v118, s33, v32
	s_nop 3
	ds_read_b128 v[4:7], v126 offset:60928
	ds_read_b128 v[106:109], v126 offset:60992
	ds_read_b128 v[110:113], v126 offset:61056
	ds_read_b128 v[114:117], v126 offset:61120
	ds_read_b128 v[118:121], v32
	ds_read_b128 v[122:125], v32 offset:64
	ds_read_b128 v[126:129], v32 offset:128
	ds_read_b128 v[130:133], v32 offset:192
	s_waitcnt lgkmcnt(7)
	s_setprio 1
	v_mfma_f32_16x16x32_bf16 v[4:7], v[4:7], v[0:3], 0
	s_waitcnt lgkmcnt(3)
	v_mfma_f32_16x16x32_bf16 v[0:3], v[118:121], v[0:3], 0
	v_mfma_f32_16x16x32_bf16 v[4:7], v[106:109], v[62:65], v[4:7]
	s_waitcnt lgkmcnt(2)
	v_mfma_f32_16x16x32_bf16 v[0:3], v[122:125], v[62:65], v[0:3]
	v_mfma_f32_16x16x32_bf16 v[4:7], v[110:113], v[66:69], v[4:7]
	s_waitcnt lgkmcnt(1)
	v_mfma_f32_16x16x32_bf16 v[0:3], v[126:129], v[66:69], v[0:3]
	v_mfma_f32_16x16x32_bf16 v[4:7], v[114:117], v[70:73], v[4:7]
	s_waitcnt lgkmcnt(0)
	v_mfma_f32_16x16x32_bf16 v[0:3], v[130:133], v[70:73], v[0:3]
	s_setprio 0
	v_max_f32_e32 v32, v74, v75
	v_max_f32_e32 v62, v76, v77
	s_mov_b32 s8, 0xff61b1e6
	v_max3_f32 v32, v32, v62, s8
	v_max_f32_e32 v62, v58, v59
	v_max_f32_e32 v63, v60, v61
	v_max3_f32 v32, v62, v63, v32
	v_max_f32_e32 v62, v54, v55
	v_max_f32_e32 v63, v56, v57
	v_max3_f32 v32, v62, v63, v32
	v_max_f32_e32 v62, v50, v51
	v_max_f32_e32 v63, v52, v53
	v_max3_f32 v32, v62, v63, v32
	v_max_f32_e32 v62, v46, v47
	v_max_f32_e32 v63, v48, v49
	v_max3_f32 v32, v62, v63, v32
	v_max_f32_e32 v62, v42, v43
	v_max_f32_e32 v63, v44, v45
	v_max3_f32 v32, v62, v63, v32
	v_max_f32_e32 v62, v38, v39
	v_max_f32_e32 v63, v40, v41
	v_max3_f32 v32, v62, v63, v32
	v_max_f32_e32 v62, v34, v35
	v_max_f32_e32 v63, v36, v37
	v_max3_f32 v32, v62, v63, v32
	v_max_f32_e32 v62, v28, v29
	v_max_f32_e32 v63, v30, v31
	v_max3_f32 v32, v62, v63, v32
	v_max_f32_e32 v62, v24, v25
	v_max_f32_e32 v63, v26, v27
	v_max3_f32 v32, v62, v63, v32
	v_max_f32_e32 v62, v20, v21
	v_max_f32_e32 v63, v22, v23
	v_max3_f32 v32, v62, v63, v32
	v_max_f32_e32 v62, v16, v17
	v_max_f32_e32 v63, v18, v19
	v_max3_f32 v32, v62, v63, v32
	v_max_f32_e32 v62, v12, v13
	v_max_f32_e32 v63, v14, v15
	v_max3_f32 v32, v62, v63, v32
	v_max_f32_e32 v62, v8, v9
	v_max_f32_e32 v63, v10, v11
	v_max3_f32 v32, v62, v63, v32
	v_max_f32_e32 v62, v4, v5
	v_max_f32_e32 v63, v6, v7
	v_max3_f32 v32, v62, v63, v32
	v_max_f32_e32 v62, v0, v1
	v_max_f32_e32 v63, v2, v3
	v_max3_f32 v32, v62, v63, v32
	ds_bpermute_b32 v62, v100, v32
	s_waitcnt lgkmcnt(0)
	v_max_f32_e32 v32, v32, v62
	ds_bpermute_b32 v62, v101, v32
	s_waitcnt lgkmcnt(0)
	v_max_f32_e32 v66, v32, v62
	v_sub_f32_e32 v32, v74, v66
	v_exp_f32_e32 v62, v32
	v_sub_f32_e32 v63, v75, v66
	v_exp_f32_e32 v63, v63
	v_sub_f32_e32 v64, v76, v66
	v_exp_f32_e32 v64, v64
	v_sub_f32_e32 v65, v77, v66
	v_exp_f32_e32 v65, v65
	v_sub_f32_e32 v58, v58, v66
	v_add_f32_e32 v32, 0, v62
	v_exp_f32_e32 v67, v58
	v_sub_f32_e32 v58, v59, v66
	v_add_f32_e32 v32, v63, v32
	v_exp_f32_e32 v68, v58
	v_sub_f32_e32 v58, v60, v66
	v_add_f32_e32 v32, v64, v32
	v_exp_f32_e32 v60, v58
	v_sub_f32_e32 v58, v61, v66
	v_add_f32_e32 v32, v65, v32
	v_exp_f32_e32 v61, v58
	v_sub_f32_e32 v54, v54, v66
	v_add_f32_e32 v32, v67, v32
	v_exp_f32_e32 v54, v54
	v_sub_f32_e32 v55, v55, v66
	v_add_f32_e32 v32, v68, v32
	v_exp_f32_e32 v55, v55
	v_sub_f32_e32 v56, v56, v66
	v_add_f32_e32 v32, v60, v32
	v_exp_f32_e32 v56, v56
	v_sub_f32_e32 v57, v57, v66
	v_add_f32_e32 v32, v61, v32
	v_exp_f32_e32 v57, v57
	v_sub_f32_e32 v50, v50, v66
	v_add_f32_e32 v32, v54, v32
	v_exp_f32_e32 v58, v50
	v_sub_f32_e32 v50, v51, v66
	v_add_f32_e32 v32, v55, v32
	v_exp_f32_e32 v59, v50
	v_sub_f32_e32 v50, v52, v66
	v_add_f32_e32 v32, v56, v32
	v_exp_f32_e32 v52, v50
	v_sub_f32_e32 v50, v53, v66
	v_add_f32_e32 v32, v57, v32
	v_exp_f32_e32 v53, v50
	v_sub_f32_e32 v46, v46, v66
	v_add_f32_e32 v32, v58, v32
	v_exp_f32_e32 v46, v46
	v_sub_f32_e32 v47, v47, v66
	v_add_f32_e32 v32, v59, v32
	v_exp_f32_e32 v47, v47
	v_sub_f32_e32 v48, v48, v66
	v_add_f32_e32 v32, v52, v32
	v_exp_f32_e32 v48, v48
	v_sub_f32_e32 v49, v49, v66
	v_add_f32_e32 v32, v53, v32
	v_exp_f32_e32 v49, v49
	v_sub_f32_e32 v42, v42, v66
	v_add_f32_e32 v32, v46, v32
	v_exp_f32_e32 v50, v42
	v_sub_f32_e32 v42, v43, v66
	v_add_f32_e32 v32, v47, v32
	v_exp_f32_e32 v51, v42
	v_sub_f32_e32 v42, v44, v66
	v_add_f32_e32 v32, v48, v32
	v_exp_f32_e32 v44, v42
	v_sub_f32_e32 v42, v45, v66
	v_add_f32_e32 v32, v49, v32
	v_exp_f32_e32 v45, v42
	v_sub_f32_e32 v38, v38, v66
	v_add_f32_e32 v32, v50, v32
	v_exp_f32_e32 v38, v38
	v_sub_f32_e32 v39, v39, v66
	v_add_f32_e32 v32, v51, v32
	v_exp_f32_e32 v39, v39
	v_sub_f32_e32 v40, v40, v66
	v_add_f32_e32 v32, v44, v32
	v_exp_f32_e32 v40, v40
	v_sub_f32_e32 v41, v41, v66
	v_add_f32_e32 v32, v45, v32
	v_exp_f32_e32 v41, v41
	v_sub_f32_e32 v34, v34, v66
	v_add_f32_e32 v32, v38, v32
	v_exp_f32_e32 v42, v34
	v_sub_f32_e32 v34, v35, v66
	v_add_f32_e32 v32, v39, v32
	v_exp_f32_e32 v43, v34
	v_sub_f32_e32 v34, v36, v66
	v_add_f32_e32 v32, v40, v32
	v_exp_f32_e32 v36, v34
	v_sub_f32_e32 v34, v37, v66
	v_add_f32_e32 v32, v41, v32
	v_exp_f32_e32 v37, v34
	v_sub_f32_e32 v28, v28, v66
	v_add_f32_e32 v32, v42, v32
	v_exp_f32_e32 v28, v28
	v_sub_f32_e32 v29, v29, v66
	v_add_f32_e32 v32, v43, v32
	v_exp_f32_e32 v29, v29
	v_sub_f32_e32 v30, v30, v66
	v_add_f32_e32 v32, v36, v32
	v_exp_f32_e32 v30, v30
	v_sub_f32_e32 v31, v31, v66
	v_add_f32_e32 v32, v37, v32
	v_exp_f32_e32 v31, v31
	v_add_f32_e32 v32, v28, v32
	v_add_f32_e32 v32, v29, v32
	v_add_f32_e32 v32, v30, v32
	v_sub_f32_e32 v24, v24, v66
	v_add_f32_e32 v34, v31, v32
	v_exp_f32_e32 v32, v24
	v_sub_f32_e32 v25, v25, v66
	v_sub_f32_e32 v20, v20, v66
	v_exp_f32_e32 v20, v20
	v_add_f32_e32 v24, v32, v34
	v_exp_f32_e32 v34, v25
	v_sub_f32_e32 v25, v26, v66
	v_exp_f32_e32 v35, v25
	v_sub_f32_e32 v25, v27, v66
	v_exp_f32_e32 v27, v25
	v_sub_f32_e32 v21, v21, v66
	v_add_f32_e32 v24, v34, v24
	v_exp_f32_e32 v21, v21
	v_sub_f32_e32 v22, v22, v66
	v_add_f32_e32 v24, v35, v24
	v_exp_f32_e32 v22, v22
	v_sub_f32_e32 v23, v23, v66
	v_add_f32_e32 v24, v27, v24
	v_exp_f32_e32 v23, v23
	v_add_f32_e32 v24, v20, v24
	v_add_f32_e32 v24, v21, v24
	v_add_f32_e32 v24, v22, v24
	v_sub_f32_e32 v16, v16, v66
	v_add_f32_e32 v25, v23, v24
	v_exp_f32_e32 v24, v16
	v_sub_f32_e32 v17, v17, v66
	v_sub_f32_e32 v12, v12, v66
	v_exp_f32_e32 v12, v12
	v_add_f32_e32 v16, v24, v25
	v_exp_f32_e32 v25, v17
	v_sub_f32_e32 v17, v18, v66
	v_exp_f32_e32 v26, v17
	v_sub_f32_e32 v17, v19, v66
	v_exp_f32_e32 v19, v17
	v_sub_f32_e32 v13, v13, v66
	v_add_f32_e32 v16, v25, v16
	v_exp_f32_e32 v13, v13
	v_sub_f32_e32 v14, v14, v66
	v_add_f32_e32 v16, v26, v16
	v_exp_f32_e32 v14, v14
	v_sub_f32_e32 v15, v15, v66
	v_add_f32_e32 v16, v19, v16
	v_exp_f32_e32 v15, v15
	v_add_f32_e32 v16, v12, v16
	v_add_f32_e32 v16, v13, v16
	v_add_f32_e32 v16, v14, v16
	v_sub_f32_e32 v8, v8, v66
	v_add_f32_e32 v17, v15, v16
	v_exp_f32_e32 v16, v8
	v_sub_f32_e32 v9, v9, v66
	v_sub_f32_e32 v4, v4, v66
	v_exp_f32_e32 v4, v4
	v_add_f32_e32 v8, v16, v17
	v_exp_f32_e32 v17, v9
	v_sub_f32_e32 v9, v10, v66
	v_exp_f32_e32 v18, v9
	v_sub_f32_e32 v9, v11, v66
	v_exp_f32_e32 v11, v9
	v_sub_f32_e32 v5, v5, v66
	v_add_f32_e32 v8, v17, v8
	v_exp_f32_e32 v5, v5
	v_sub_f32_e32 v6, v6, v66
	v_add_f32_e32 v8, v18, v8
	v_exp_f32_e32 v6, v6
	v_sub_f32_e32 v7, v7, v66
	v_add_f32_e32 v8, v11, v8
	v_exp_f32_e32 v7, v7
	v_add_f32_e32 v8, v4, v8
	v_add_f32_e32 v8, v5, v8
	v_add_f32_e32 v8, v6, v8
	v_sub_f32_e32 v0, v0, v66
	v_add_f32_e32 v9, v7, v8
	v_exp_f32_e32 v8, v0
	v_sub_f32_e32 v1, v1, v66
	v_cvt_pk_bf16_f32 v62, v62, v63
	v_cvt_pk_bf16_f32 v63, v64, v65
	v_add_f32_e32 v0, v8, v9
	v_exp_f32_e32 v9, v1
	v_sub_f32_e32 v1, v2, v66
	v_exp_f32_e32 v10, v1
	v_sub_f32_e32 v1, v3, v66
	v_lshlrev_b32_e32 v66, 3, v98
	v_mul_u32_u24_e32 v2, 0x120, v105
	v_and_b32_e32 v66, 24, v66
	v_add3_u32 v2, s27, v2, v66
	v_cvt_pk_bf16_f32 v64, v67, v68
	ds_read_b64_tr_b16 v[68:69], v2 offset:4608
	ds_read_b64_tr_b16 v[66:67], v2
	ds_read_b64_tr_b16 v[70:71], v2 offset:32
	ds_read_b64_tr_b16 v[72:73], v2 offset:4640
	ds_read_b64_tr_b16 v[74:75], v2 offset:64
	ds_read_b64_tr_b16 v[76:77], v2 offset:4672
	ds_read_b64_tr_b16 v[106:107], v2 offset:96
	ds_read_b64_tr_b16 v[108:109], v2 offset:4704
	ds_read_b64_tr_b16 v[110:111], v2 offset:128
	ds_read_b64_tr_b16 v[112:113], v2 offset:4736
	ds_read_b64_tr_b16 v[114:115], v2 offset:160
	ds_read_b64_tr_b16 v[116:117], v2 offset:4768
	ds_read_b64_tr_b16 v[118:119], v2 offset:192
	ds_read_b64_tr_b16 v[120:121], v2 offset:4800
	ds_read_b64_tr_b16 v[122:123], v2 offset:224
	ds_read_b64_tr_b16 v[124:125], v2 offset:4832
	v_exp_f32_e32 v3, v1
	v_add_f32_e32 v0, v9, v0
	v_add_f32_e32 v0, v10, v0
	v_cvt_pk_bf16_f32 v65, v60, v61
	v_add_f32_e32 v0, v3, v0
	ds_bpermute_b32 v1, v100, v0
	s_waitcnt lgkmcnt(0)
	v_add_f32_e32 v0, v0, v1
	ds_bpermute_b32 v1, v101, v0
	s_setprio 1
	v_mfma_f32_16x16x32_bf16 v[66:69], v[66:69], v[62:65], 0
	v_mfma_f32_16x16x32_bf16 v[70:73], v[70:73], v[62:65], 0
	v_mfma_f32_16x16x32_bf16 v[74:77], v[74:77], v[62:65], 0
	v_mfma_f32_16x16x32_bf16 v[106:109], v[106:109], v[62:65], 0
	v_mfma_f32_16x16x32_bf16 v[110:113], v[110:113], v[62:65], 0
	v_mfma_f32_16x16x32_bf16 v[114:117], v[114:117], v[62:65], 0
	v_mfma_f32_16x16x32_bf16 v[118:121], v[118:121], v[62:65], 0
	v_mfma_f32_16x16x32_bf16 v[60:63], v[122:125], v[62:65], 0
	s_setprio 0
	ds_read_b64_tr_b16 v[124:125], v2 offset:13824
	ds_read_b64_tr_b16 v[122:123], v2 offset:9216
	ds_read_b64_tr_b16 v[126:127], v2 offset:9248
	ds_read_b64_tr_b16 v[128:129], v2 offset:13856
	ds_read_b64_tr_b16 v[130:131], v2 offset:9280
	ds_read_b64_tr_b16 v[132:133], v2 offset:13888
	ds_read_b64_tr_b16 v[134:135], v2 offset:9312
	ds_read_b64_tr_b16 v[136:137], v2 offset:13920
	ds_read_b64_tr_b16 v[138:139], v2 offset:9344
	ds_read_b64_tr_b16 v[140:141], v2 offset:13952
	ds_read_b64_tr_b16 v[142:143], v2 offset:9376
	ds_read_b64_tr_b16 v[144:145], v2 offset:13984
	ds_read_b64_tr_b16 v[146:147], v2 offset:9408
	ds_read_b64_tr_b16 v[148:149], v2 offset:14016
	ds_read_b64_tr_b16 v[150:151], v2 offset:9440
	ds_read_b64_tr_b16 v[152:153], v2 offset:14048
	v_cvt_pk_bf16_f32 v54, v54, v55
	v_cvt_pk_bf16_f32 v55, v56, v57
	v_cvt_pk_bf16_f32 v56, v58, v59
	v_cvt_pk_bf16_f32 v57, v52, v53
	s_waitcnt lgkmcnt(14)
	s_setprio 1
	v_mfma_f32_16x16x32_bf16 v[64:67], v[122:125], v[54:57], v[66:69]
	s_waitcnt lgkmcnt(12)
	v_mfma_f32_16x16x32_bf16 v[68:71], v[126:129], v[54:57], v[70:73]
	s_waitcnt lgkmcnt(10)
	v_mfma_f32_16x16x32_bf16 v[72:75], v[130:133], v[54:57], v[74:77]
	s_waitcnt lgkmcnt(8)
	v_mfma_f32_16x16x32_bf16 v[106:109], v[134:137], v[54:57], v[106:109]
	s_waitcnt lgkmcnt(6)
	v_mfma_f32_16x16x32_bf16 v[110:113], v[138:141], v[54:57], v[110:113]
	s_waitcnt lgkmcnt(4)
	v_mfma_f32_16x16x32_bf16 v[114:117], v[142:145], v[54:57], v[114:117]
	s_waitcnt lgkmcnt(2)
	v_mfma_f32_16x16x32_bf16 v[118:121], v[146:149], v[54:57], v[118:121]
	s_waitcnt lgkmcnt(0)
	v_mfma_f32_16x16x32_bf16 v[52:55], v[150:153], v[54:57], v[60:63]
	s_setprio 0
	ds_read_b64_tr_b16 v[58:59], v2 offset:23040
	ds_read_b64_tr_b16 v[56:57], v2 offset:18432
	s_nop 0
	ds_read_b64_tr_b16 v[60:61], v2 offset:18464
	ds_read_b64_tr_b16 v[62:63], v2 offset:23072
	ds_read_b64_tr_b16 v[122:123], v2 offset:18496
	ds_read_b64_tr_b16 v[124:125], v2 offset:23104
	ds_read_b64_tr_b16 v[126:127], v2 offset:18528
	ds_read_b64_tr_b16 v[128:129], v2 offset:23136
	ds_read_b64_tr_b16 v[130:131], v2 offset:18560
	ds_read_b64_tr_b16 v[132:133], v2 offset:23168
	ds_read_b64_tr_b16 v[134:135], v2 offset:18592
	ds_read_b64_tr_b16 v[136:137], v2 offset:23200
	ds_read_b64_tr_b16 v[138:139], v2 offset:18624
	ds_read_b64_tr_b16 v[140:141], v2 offset:23232
	ds_read_b64_tr_b16 v[142:143], v2 offset:18656
	ds_read_b64_tr_b16 v[144:145], v2 offset:23264
	v_cvt_pk_bf16_f32 v46, v46, v47
	v_cvt_pk_bf16_f32 v47, v48, v49
	v_cvt_pk_bf16_f32 v48, v50, v51
	v_cvt_pk_bf16_f32 v49, v44, v45
	s_waitcnt lgkmcnt(14)
	s_setprio 1
	v_mfma_f32_16x16x32_bf16 v[56:59], v[56:59], v[46:49], v[64:67]
	s_waitcnt lgkmcnt(12)
	v_mfma_f32_16x16x32_bf16 v[60:63], v[60:63], v[46:49], v[68:71]
	s_waitcnt lgkmcnt(10)
	v_mfma_f32_16x16x32_bf16 v[64:67], v[122:125], v[46:49], v[72:75]
	s_waitcnt lgkmcnt(8)
	v_mfma_f32_16x16x32_bf16 v[68:71], v[126:129], v[46:49], v[106:109]
	s_waitcnt lgkmcnt(6)
	v_mfma_f32_16x16x32_bf16 v[72:75], v[130:133], v[46:49], v[110:113]
	s_waitcnt lgkmcnt(4)
	v_mfma_f32_16x16x32_bf16 v[106:109], v[134:137], v[46:49], v[114:117]
	s_waitcnt lgkmcnt(2)
	v_mfma_f32_16x16x32_bf16 v[110:113], v[138:141], v[46:49], v[118:121]
	s_waitcnt lgkmcnt(0)
	v_mfma_f32_16x16x32_bf16 v[44:47], v[142:145], v[46:49], v[52:55]
	s_setprio 0
	ds_read_b64_tr_b16 v[50:51], v2 offset:32256
	ds_read_b64_tr_b16 v[48:49], v2 offset:27648
	s_nop 0
	ds_read_b64_tr_b16 v[52:53], v2 offset:27680
	ds_read_b64_tr_b16 v[54:55], v2 offset:32288
	ds_read_b64_tr_b16 v[114:115], v2 offset:27712
	ds_read_b64_tr_b16 v[116:117], v2 offset:32320
	ds_read_b64_tr_b16 v[118:119], v2 offset:27744
	ds_read_b64_tr_b16 v[120:121], v2 offset:32352
	ds_read_b64_tr_b16 v[122:123], v2 offset:27776
	ds_read_b64_tr_b16 v[124:125], v2 offset:32384
	ds_read_b64_tr_b16 v[126:127], v2 offset:27808
	ds_read_b64_tr_b16 v[128:129], v2 offset:32416
	ds_read_b64_tr_b16 v[130:131], v2 offset:27840
	ds_read_b64_tr_b16 v[132:133], v2 offset:32448
	ds_read_b64_tr_b16 v[134:135], v2 offset:27872
	ds_read_b64_tr_b16 v[136:137], v2 offset:32480
	v_cvt_pk_bf16_f32 v38, v38, v39
	v_cvt_pk_bf16_f32 v39, v40, v41
	v_cvt_pk_bf16_f32 v40, v42, v43
	v_cvt_pk_bf16_f32 v41, v36, v37
	s_waitcnt lgkmcnt(14)
	s_setprio 1
	v_mfma_f32_16x16x32_bf16 v[48:51], v[48:51], v[38:41], v[56:59]
	s_waitcnt lgkmcnt(12)
	v_mfma_f32_16x16x32_bf16 v[52:55], v[52:55], v[38:41], v[60:63]
	s_waitcnt lgkmcnt(10)
	v_mfma_f32_16x16x32_bf16 v[56:59], v[114:117], v[38:41], v[64:67]
	s_waitcnt lgkmcnt(8)
	v_mfma_f32_16x16x32_bf16 v[60:63], v[118:121], v[38:41], v[68:71]
	s_waitcnt lgkmcnt(6)
	v_mfma_f32_16x16x32_bf16 v[64:67], v[122:125], v[38:41], v[72:75]
	s_waitcnt lgkmcnt(4)
	v_mfma_f32_16x16x32_bf16 v[68:71], v[126:129], v[38:41], v[106:109]
	s_waitcnt lgkmcnt(2)
	v_mfma_f32_16x16x32_bf16 v[72:75], v[130:133], v[38:41], v[110:113]
	s_waitcnt lgkmcnt(0)
	v_mfma_f32_16x16x32_bf16 v[36:39], v[134:137], v[38:41], v[44:47]
	s_setprio 0
	ds_read_b64_tr_b16 v[42:43], v2 offset:41472
	ds_read_b64_tr_b16 v[40:41], v2 offset:36864
	s_nop 0
	ds_read_b64_tr_b16 v[44:45], v2 offset:36896
	ds_read_b64_tr_b16 v[46:47], v2 offset:41504
	ds_read_b64_tr_b16 v[106:107], v2 offset:36928
	ds_read_b64_tr_b16 v[108:109], v2 offset:41536
	ds_read_b64_tr_b16 v[110:111], v2 offset:36960
	ds_read_b64_tr_b16 v[112:113], v2 offset:41568
	ds_read_b64_tr_b16 v[114:115], v2 offset:36992
	ds_read_b64_tr_b16 v[116:117], v2 offset:41600
	ds_read_b64_tr_b16 v[118:119], v2 offset:37024
	ds_read_b64_tr_b16 v[120:121], v2 offset:41632
	ds_read_b64_tr_b16 v[122:123], v2 offset:37056
	ds_read_b64_tr_b16 v[124:125], v2 offset:41664
	ds_read_b64_tr_b16 v[126:127], v2 offset:37088
	ds_read_b64_tr_b16 v[128:129], v2 offset:41696
	v_cvt_pk_bf16_f32 v28, v28, v29
	v_cvt_pk_bf16_f32 v29, v30, v31
	v_cvt_pk_bf16_f32 v30, v32, v34
	v_cvt_pk_bf16_f32 v31, v35, v27
	s_waitcnt lgkmcnt(14)
	s_setprio 1
	v_mfma_f32_16x16x32_bf16 v[40:43], v[40:43], v[28:31], v[48:51]
	s_waitcnt lgkmcnt(12)
	v_mfma_f32_16x16x32_bf16 v[44:47], v[44:47], v[28:31], v[52:55]
	s_waitcnt lgkmcnt(10)
	v_mfma_f32_16x16x32_bf16 v[48:51], v[106:109], v[28:31], v[56:59]
	s_waitcnt lgkmcnt(8)
	v_mfma_f32_16x16x32_bf16 v[52:55], v[110:113], v[28:31], v[60:63]
	s_waitcnt lgkmcnt(6)
	v_mfma_f32_16x16x32_bf16 v[56:59], v[114:117], v[28:31], v[64:67]
	s_waitcnt lgkmcnt(4)
	v_mfma_f32_16x16x32_bf16 v[60:63], v[118:121], v[28:31], v[68:71]
	s_waitcnt lgkmcnt(2)
	v_mfma_f32_16x16x32_bf16 v[64:67], v[122:125], v[28:31], v[72:75]
	s_waitcnt lgkmcnt(0)
	v_mfma_f32_16x16x32_bf16 v[28:31], v[126:129], v[28:31], v[36:39]
	s_setprio 0
	v_cvt_pk_bf16_f32 v20, v20, v21
	v_cvt_pk_bf16_f32 v21, v22, v23
	v_cvt_pk_bf16_f32 v22, v24, v25
	v_cvt_pk_bf16_f32 v23, v26, v19
	ds_read_b64_tr_b16 v[26:27], v2 offset:50688
	ds_read_b64_tr_b16 v[24:25], v2 offset:46080
	ds_read_b64_tr_b16 v[34:35], v2 offset:46112
	ds_read_b64_tr_b16 v[36:37], v2 offset:50720
	ds_read_b64_tr_b16 v[68:69], v2 offset:46144
	ds_read_b64_tr_b16 v[70:71], v2 offset:50752
	ds_read_b64_tr_b16 v[72:73], v2 offset:46176
	ds_read_b64_tr_b16 v[74:75], v2 offset:50784
	ds_read_b64_tr_b16 v[106:107], v2 offset:46208
	ds_read_b64_tr_b16 v[108:109], v2 offset:50816
	ds_read_b64_tr_b16 v[110:111], v2 offset:46240
	ds_read_b64_tr_b16 v[112:113], v2 offset:50848
	ds_read_b64_tr_b16 v[114:115], v2 offset:46272
	ds_read_b64_tr_b16 v[116:117], v2 offset:50880
	ds_read_b64_tr_b16 v[118:119], v2 offset:46304
	ds_read_b64_tr_b16 v[120:121], v2 offset:50912
	s_waitcnt lgkmcnt(14)
	s_setprio 1
	v_mfma_f32_16x16x32_bf16 v[24:27], v[24:27], v[20:23], v[40:43]
	s_waitcnt lgkmcnt(12)
	v_mfma_f32_16x16x32_bf16 v[34:37], v[34:37], v[20:23], v[44:47]
	s_waitcnt lgkmcnt(10)
	v_mfma_f32_16x16x32_bf16 v[38:41], v[68:71], v[20:23], v[48:51]
	s_waitcnt lgkmcnt(8)
	v_mfma_f32_16x16x32_bf16 v[42:45], v[72:75], v[20:23], v[52:55]
	s_waitcnt lgkmcnt(6)
	v_mfma_f32_16x16x32_bf16 v[46:49], v[106:109], v[20:23], v[56:59]
	s_waitcnt lgkmcnt(4)
	v_mfma_f32_16x16x32_bf16 v[50:53], v[110:113], v[20:23], v[60:63]
	s_waitcnt lgkmcnt(2)
	v_mfma_f32_16x16x32_bf16 v[54:57], v[114:117], v[20:23], v[64:67]
	s_waitcnt lgkmcnt(0)
	v_mfma_f32_16x16x32_bf16 v[20:23], v[118:121], v[20:23], v[28:31]
	s_setprio 0
	v_cvt_pk_bf16_f32 v12, v12, v13
	v_cvt_pk_bf16_f32 v13, v14, v15
	v_cvt_pk_bf16_f32 v14, v16, v17
	v_cvt_pk_bf16_f32 v15, v18, v11
	ds_read_b64_tr_b16 v[18:19], v2 offset:59904
	ds_read_b64_tr_b16 v[16:17], v2 offset:55296
	s_nop 0
	ds_read_b64_tr_b16 v[28:29], v2 offset:55328
	ds_read_b64_tr_b16 v[30:31], v2 offset:59936
	ds_read_b64_tr_b16 v[58:59], v2 offset:55360
	ds_read_b64_tr_b16 v[60:61], v2 offset:59968
	ds_read_b64_tr_b16 v[62:63], v2 offset:55392
	ds_read_b64_tr_b16 v[64:65], v2 offset:60000
	ds_read_b64_tr_b16 v[66:67], v2 offset:55424
	ds_read_b64_tr_b16 v[68:69], v2 offset:60032
	ds_read_b64_tr_b16 v[70:71], v2 offset:55456
	ds_read_b64_tr_b16 v[72:73], v2 offset:60064
	ds_read_b64_tr_b16 v[74:75], v2 offset:55488
	ds_read_b64_tr_b16 v[76:77], v2 offset:60096
	ds_read_b64_tr_b16 v[106:107], v2 offset:55520
	ds_read_b64_tr_b16 v[108:109], v2 offset:60128
	s_waitcnt lgkmcnt(14)
	s_setprio 1
	v_mfma_f32_16x16x32_bf16 v[16:19], v[16:19], v[12:15], v[24:27]
	s_waitcnt lgkmcnt(12)
	v_mfma_f32_16x16x32_bf16 v[24:27], v[28:31], v[12:15], v[34:37]
	s_waitcnt lgkmcnt(10)
	v_mfma_f32_16x16x32_bf16 v[28:31], v[58:61], v[12:15], v[38:41]
	s_waitcnt lgkmcnt(8)
	v_mfma_f32_16x16x32_bf16 v[34:37], v[62:65], v[12:15], v[42:45]
	s_waitcnt lgkmcnt(6)
	v_mfma_f32_16x16x32_bf16 v[38:41], v[66:69], v[12:15], v[46:49]
	s_waitcnt lgkmcnt(4)
	v_mfma_f32_16x16x32_bf16 v[42:45], v[70:73], v[12:15], v[50:53]
	s_waitcnt lgkmcnt(2)
	v_mfma_f32_16x16x32_bf16 v[46:49], v[74:77], v[12:15], v[54:57]
	s_waitcnt lgkmcnt(0)
	v_mfma_f32_16x16x32_bf16 v[12:15], v[106:109], v[12:15], v[20:23]
	s_setprio 0
	v_cvt_pk_bf16_f32 v4, v4, v5
	v_cvt_pk_bf16_f32 v5, v6, v7
	v_cvt_pk_bf16_f32 v7, v10, v3
	v_add_u32_e32 v3, 0x10e00, v2
	v_cvt_pk_bf16_f32 v6, v8, v9
	ds_read_b64_tr_b16 v[10:11], v3
	ds_read_b64_tr_b16 v[8:9], v2 offset:64512
	ds_read_b64_tr_b16 v[20:21], v2 offset:64544
	v_add_u32_e32 v3, 0x10e20, v2
	ds_read_b64_tr_b16 v[22:23], v3
	ds_read_b64_tr_b16 v[50:51], v2 offset:64576
	v_add_u32_e32 v3, 0x10e40, v2
	ds_read_b64_tr_b16 v[52:53], v3
	ds_read_b64_tr_b16 v[54:55], v2 offset:64608
	v_add_u32_e32 v3, 0x10e60, v2
	ds_read_b64_tr_b16 v[56:57], v3
	ds_read_b64_tr_b16 v[58:59], v2 offset:64640
	v_add_u32_e32 v3, 0x10e80, v2
	ds_read_b64_tr_b16 v[60:61], v3
	ds_read_b64_tr_b16 v[62:63], v2 offset:64672
	v_add_u32_e32 v3, 0x10ea0, v2
	ds_read_b64_tr_b16 v[64:65], v3
	ds_read_b64_tr_b16 v[66:67], v2 offset:64704
	v_add_u32_e32 v3, 0x10ec0, v2
	ds_read_b64_tr_b16 v[68:69], v3
	ds_read_b64_tr_b16 v[70:71], v2 offset:64736
	v_add_u32_e32 v2, 0x10ee0, v2
	ds_read_b64_tr_b16 v[72:73], v2
	s_waitcnt lgkmcnt(14)
	s_setprio 1
	v_mfma_f32_16x16x32_bf16 v[8:11], v[8:11], v[4:7], v[16:19]
	s_waitcnt lgkmcnt(12)
	v_mfma_f32_16x16x32_bf16 v[16:19], v[20:23], v[4:7], v[24:27]
	s_waitcnt lgkmcnt(10)
	v_mfma_f32_16x16x32_bf16 v[20:23], v[50:53], v[4:7], v[28:31]
	s_waitcnt lgkmcnt(8)
	v_mfma_f32_16x16x32_bf16 v[24:27], v[54:57], v[4:7], v[34:37]
	s_waitcnt lgkmcnt(6)
	v_mfma_f32_16x16x32_bf16 v[28:31], v[58:61], v[4:7], v[38:41]
	s_waitcnt lgkmcnt(4)
	v_mfma_f32_16x16x32_bf16 v[34:37], v[62:65], v[4:7], v[42:45]
	s_waitcnt lgkmcnt(2)
	v_mfma_f32_16x16x32_bf16 v[38:41], v[66:69], v[4:7], v[46:49]
	s_waitcnt lgkmcnt(0)
	v_mfma_f32_16x16x32_bf16 v[2:5], v[70:73], v[4:7], v[12:15]
	s_setprio 0
	v_add_f32_e32 v0, v0, v1
	v_rcp_f32_e32 v6, v0
	s_waitcnt vmcnt(7)
	v_lshlrev_b32_e32 v0, 16, v96
	v_and_b32_e32 v1, 0xffff0000, v96
	s_mov_b64 s[10:11], 0
	v_mul_f32_e32 v7, v6, v8
	v_mul_f32_e32 v8, v6, v9
	v_mul_f32_e32 v0, v7, v0
	v_mul_f32_e32 v1, v8, v1
	v_cvt_pk_bf16_f32 v0, v0, v1
	v_mul_f32_e32 v1, v6, v10
	v_lshlrev_b32_e32 v7, 16, v97
	v_mul_f32_e32 v1, v1, v7
	v_mul_f32_e32 v7, v6, v11
	v_and_b32_e32 v8, 0xffff0000, v97
	v_mul_f32_e32 v7, v7, v8
	v_cvt_pk_bf16_f32 v1, v1, v7
	global_store_dwordx2 v[94:95], v[0:1], off
	v_mul_f32_e32 v0, v6, v16
	s_waitcnt vmcnt(7)
	v_lshlrev_b32_e32 v1, 16, v92
	v_mul_f32_e32 v0, v0, v1
	v_mul_f32_e32 v1, v6, v17
	v_and_b32_e32 v7, 0xffff0000, v92
	v_mul_f32_e32 v1, v1, v7
	v_cvt_pk_bf16_f32 v0, v0, v1
	v_mul_f32_e32 v1, v6, v18
	v_lshlrev_b32_e32 v7, 16, v93
	v_mul_f32_e32 v1, v1, v7
	v_mul_f32_e32 v7, v6, v19
	v_and_b32_e32 v8, 0xffff0000, v93
	v_mul_f32_e32 v7, v7, v8
	v_cvt_pk_bf16_f32 v1, v1, v7
	global_store_dwordx2 v[78:79], v[0:1], off offset:32
	v_mul_f32_e32 v0, v6, v20
	s_waitcnt vmcnt(7)
	v_lshlrev_b32_e32 v1, 16, v90
	v_mul_f32_e32 v0, v0, v1
	v_mul_f32_e32 v1, v6, v21
	v_and_b32_e32 v7, 0xffff0000, v90
	v_mul_f32_e32 v1, v1, v7
	v_cvt_pk_bf16_f32 v0, v0, v1
	v_mul_f32_e32 v1, v6, v22
	v_lshlrev_b32_e32 v7, 16, v91
	v_mul_f32_e32 v1, v1, v7
	v_mul_f32_e32 v7, v6, v23
	v_and_b32_e32 v8, 0xffff0000, v91
	v_mul_f32_e32 v7, v7, v8
	v_cvt_pk_bf16_f32 v1, v1, v7
	global_store_dwordx2 v[78:79], v[0:1], off offset:64
	v_mul_f32_e32 v0, v6, v24
	s_waitcnt vmcnt(7)
	v_lshlrev_b32_e32 v1, 16, v88
	v_mul_f32_e32 v0, v0, v1
	v_mul_f32_e32 v1, v6, v25
	v_and_b32_e32 v7, 0xffff0000, v88
	v_mul_f32_e32 v1, v1, v7
	v_cvt_pk_bf16_f32 v0, v0, v1
	v_mul_f32_e32 v1, v6, v26
	v_lshlrev_b32_e32 v7, 16, v89
	v_mul_f32_e32 v1, v1, v7
	v_mul_f32_e32 v7, v6, v27
	v_and_b32_e32 v8, 0xffff0000, v89
	v_mul_f32_e32 v7, v7, v8
	v_cvt_pk_bf16_f32 v1, v1, v7
	global_store_dwordx2 v[78:79], v[0:1], off offset:96
	v_mul_f32_e32 v0, v6, v28
	s_waitcnt vmcnt(7)
	v_lshlrev_b32_e32 v1, 16, v86
	v_mul_f32_e32 v0, v0, v1
	v_mul_f32_e32 v1, v6, v29
	v_and_b32_e32 v7, 0xffff0000, v86
	v_mul_f32_e32 v1, v1, v7
	v_cvt_pk_bf16_f32 v0, v0, v1
	v_mul_f32_e32 v1, v6, v30
	v_lshlrev_b32_e32 v7, 16, v87
	v_mul_f32_e32 v1, v1, v7
	v_mul_f32_e32 v7, v6, v31
	v_and_b32_e32 v8, 0xffff0000, v87
	v_mul_f32_e32 v7, v7, v8
	v_cvt_pk_bf16_f32 v1, v1, v7
	global_store_dwordx2 v[78:79], v[0:1], off offset:128
	v_mul_f32_e32 v0, v6, v34
	s_waitcnt vmcnt(7)
	v_lshlrev_b32_e32 v1, 16, v84
	v_mul_f32_e32 v0, v0, v1
	v_mul_f32_e32 v1, v6, v35
	v_and_b32_e32 v7, 0xffff0000, v84
	v_mul_f32_e32 v1, v1, v7
	v_cvt_pk_bf16_f32 v0, v0, v1
	v_mul_f32_e32 v1, v6, v36
	v_lshlrev_b32_e32 v7, 16, v85
	v_mul_f32_e32 v1, v1, v7
	v_mul_f32_e32 v7, v6, v37
	v_and_b32_e32 v8, 0xffff0000, v85
	v_mul_f32_e32 v7, v7, v8
	v_cvt_pk_bf16_f32 v1, v1, v7
	global_store_dwordx2 v[78:79], v[0:1], off offset:160
	v_mul_f32_e32 v0, v6, v38
	s_waitcnt vmcnt(7)
	v_lshlrev_b32_e32 v1, 16, v82
	v_mul_f32_e32 v0, v0, v1
	v_mul_f32_e32 v1, v6, v39
	v_and_b32_e32 v7, 0xffff0000, v82
	v_mul_f32_e32 v1, v1, v7
	v_cvt_pk_bf16_f32 v0, v0, v1
	v_mul_f32_e32 v1, v6, v40
	v_lshlrev_b32_e32 v7, 16, v83
	v_mul_f32_e32 v1, v1, v7
	v_mul_f32_e32 v7, v6, v41
	v_and_b32_e32 v8, 0xffff0000, v83
	v_mul_f32_e32 v7, v7, v8
	v_cvt_pk_bf16_f32 v1, v1, v7
	global_store_dwordx2 v[78:79], v[0:1], off offset:192
	v_mul_f32_e32 v0, v6, v2
	s_waitcnt vmcnt(7)
	v_lshlrev_b32_e32 v1, 16, v80
	v_mul_f32_e32 v0, v0, v1
	v_mul_f32_e32 v1, v6, v3
	v_and_b32_e32 v2, 0xffff0000, v80
	v_mul_f32_e32 v1, v1, v2
	v_cvt_pk_bf16_f32 v0, v0, v1
	v_mul_f32_e32 v1, v6, v4
	v_lshlrev_b32_e32 v2, 16, v81
	v_mul_f32_e32 v1, v1, v2
	v_mul_f32_e32 v2, v6, v5
	v_and_b32_e32 v3, 0xffff0000, v81
	v_mul_f32_e32 v2, v2, v3
	v_cvt_pk_bf16_f32 v1, v1, v2
	global_store_dwordx2 v[78:79], v[0:1], off offset:224
	s_barrier

.Lpf_ret_k2:
	s_cmp_lg_u32 s49, 0
	s_cbranch_scc1 .LBB0_1279
	ds_read_b128 v[2:5], v83
	ds_read_b128 v[6:9], v83 offset:64
	ds_read_b128 v[10:13], v83 offset:128
	ds_read_b128 v[34:37], v83 offset:192
	ds_read_b128 v[38:41], v83 offset:4352
	ds_read_b128 v[42:45], v83 offset:4416
	ds_read_b128 v[46:49], v83 offset:4480
	ds_read_b128 v[50:53], v83 offset:4544
	s_waitcnt lgkmcnt(7)
	s_setprio 1
	v_mfma_f32_16x16x32_bf16 v[2:5], v[2:5], v[16:19], 0
	s_waitcnt lgkmcnt(6)
	v_mfma_f32_16x16x32_bf16 v[2:5], v[6:9], v[20:23], v[2:5]
	s_waitcnt lgkmcnt(5)
	v_mfma_f32_16x16x32_bf16 v[2:5], v[10:13], v[24:27], v[2:5]
	s_waitcnt lgkmcnt(4)
	v_mfma_f32_16x16x32_bf16 v[12:15], v[34:37], v[28:31], v[2:5]
	s_waitcnt lgkmcnt(3)
	v_mfma_f32_16x16x32_bf16 v[2:5], v[38:41], v[16:19], 0
	s_waitcnt lgkmcnt(2)
	v_mfma_f32_16x16x32_bf16 v[2:5], v[42:45], v[20:23], v[2:5]
	s_waitcnt lgkmcnt(1)
	v_mfma_f32_16x16x32_bf16 v[2:5], v[46:49], v[24:27], v[2:5]
	s_waitcnt lgkmcnt(0)
	v_mfma_f32_16x16x32_bf16 v[8:11], v[50:53], v[28:31], v[2:5]
	s_setprio 0
.LBB0_1279:
	s_add_i32 s8, s73, -4
	s_cmp_gt_u32 s8, -11
	s_cselect_b64 s[34:35], -1, 0
	s_cmp_lt_u32 s8, -10
	v_mov_b32_e32 v1, 0
	s_nop 0
	v_mov_b32_e32 v2, 0
	v_mov_b32_e32 v3, 0
	v_mov_b32_e32 v42, 0
	v_mov_b32_e32 v43, 0
	v_mov_b32_e32 v44, 0
	v_mov_b32_e32 v45, 0
	s_cbranch_scc1 .LBB0_1281
	v_or_b32_e32 v42, 48, v98
	v_mad_u32_u24 v42, v42, s33, v82
	ds_read_b128 v[0:3], v83 offset:8704
	ds_read_b128 v[4:7], v83 offset:8768
	ds_read_b128 v[34:37], v83 offset:8832
	ds_read_b128 v[38:41], v83 offset:8896
	ds_read_b128 v[46:49], v42
	ds_read_b128 v[50:53], v42 offset:64
	ds_read_b128 v[54:57], v42 offset:128
	ds_read_b128 v[58:61], v42 offset:192
	s_waitcnt lgkmcnt(7)
	s_setprio 1
	v_mfma_f32_16x16x32_bf16 v[0:3], v[0:3], v[16:19], 0
	s_waitcnt lgkmcnt(6)
	v_mfma_f32_16x16x32_bf16 v[0:3], v[4:7], v[20:23], v[0:3]
	s_waitcnt lgkmcnt(5)
	v_mfma_f32_16x16x32_bf16 v[0:3], v[34:37], v[24:27], v[0:3]
	s_waitcnt lgkmcnt(4)
	v_mfma_f32_16x16x32_bf16 v[42:45], v[38:41], v[28:31], v[0:3]
	s_waitcnt lgkmcnt(3)
	v_mfma_f32_16x16x32_bf16 v[0:3], v[46:49], v[16:19], 0
	s_waitcnt lgkmcnt(2)
	v_mfma_f32_16x16x32_bf16 v[0:3], v[50:53], v[20:23], v[0:3]
	s_waitcnt lgkmcnt(1)
	v_mfma_f32_16x16x32_bf16 v[0:3], v[54:57], v[24:27], v[0:3]
	s_waitcnt lgkmcnt(0)
	v_mfma_f32_16x16x32_bf16 v[0:3], v[58:61], v[28:31], v[0:3]
	s_setprio 0
.LBB0_1281:
	s_add_i32 s8, s73, -6
	s_cmp_gt_u32 s8, -11
	v_mov_b32_e32 v4, 0
	s_cselect_b64 s[30:31], -1, 0
	s_cmp_lt_u32 s8, -10
	v_mov_b32_e32 v38, 0
	v_mov_b32_e32 v39, 0
	v_mov_b32_e32 v40, 0
	v_mov_b32_e32 v41, 0
	v_mov_b32_e32 v46, 0
	v_mov_b32_e32 v47, 0
	v_mov_b32_e32 v48, 0
	v_mov_b32_e32 v49, 0
	s_cbranch_scc1 .LBB0_1283
	ds_read_b128 v[34:37], v83 offset:17408
	ds_read_b128 v[38:41], v83 offset:17472
	ds_read_b128 v[46:49], v83 offset:17536
	ds_read_b128 v[50:53], v83 offset:17600
	ds_read_b128 v[54:57], v83 offset:21760
	ds_read_b128 v[58:61], v83 offset:21824
	ds_read_b128 v[62:65], v83 offset:21888
	ds_read_b128 v[66:69], v83 offset:21952
	s_waitcnt lgkmcnt(7)
	s_setprio 1
	v_mfma_f32_16x16x32_bf16 v[34:37], v[34:37], v[16:19], 0
	s_waitcnt lgkmcnt(6)
	v_mfma_f32_16x16x32_bf16 v[34:37], v[38:41], v[20:23], v[34:37]
	s_waitcnt lgkmcnt(5)
	v_mfma_f32_16x16x32_bf16 v[34:37], v[46:49], v[24:27], v[34:37]
	s_waitcnt lgkmcnt(4)
	v_mfma_f32_16x16x32_bf16 v[46:49], v[50:53], v[28:31], v[34:37]
	s_waitcnt lgkmcnt(3)
	v_mfma_f32_16x16x32_bf16 v[34:37], v[54:57], v[16:19], 0
	s_waitcnt lgkmcnt(2)
	v_mfma_f32_16x16x32_bf16 v[34:37], v[58:61], v[20:23], v[34:37]
	s_waitcnt lgkmcnt(1)
	v_mfma_f32_16x16x32_bf16 v[34:37], v[62:65], v[24:27], v[34:37]
	s_waitcnt lgkmcnt(0)
	v_mfma_f32_16x16x32_bf16 v[38:41], v[66:69], v[28:31], v[34:37]
	s_setprio 0
.LBB0_1283:
	s_add_i32 s8, s73, -8
	s_cmp_gt_u32 s8, -11
	s_cselect_b64 s[20:21], -1, 0
	s_cmp_lt_u32 s8, -10
	v_mov_b32_e32 v5, 0
	v_mov_b32_e32 v6, 0
	v_mov_b32_e32 v7, 0
	v_mov_b32_e32 v58, 0
	v_mov_b32_e32 v59, 0
	v_mov_b32_e32 v60, 0
	v_mov_b32_e32 v61, 0
	s_cbranch_scc1 .LBB0_1285
	v_or_b32_e32 v58, 0x70, v98
	v_mad_u32_u24 v58, v58, s33, v82
	ds_read_b128 v[4:7], v83 offset:26112
	ds_read_b128 v[34:37], v83 offset:26176
	ds_read_b128 v[50:53], v83 offset:26240
	ds_read_b128 v[54:57], v83 offset:26304
	ds_read_b128 v[62:65], v58
	ds_read_b128 v[66:69], v58 offset:64
	ds_read_b128 v[70:73], v58 offset:128
	ds_read_b128 v[74:77], v58 offset:192
	s_waitcnt lgkmcnt(7)
	s_setprio 1
	v_mfma_f32_16x16x32_bf16 v[4:7], v[4:7], v[16:19], 0
	s_waitcnt lgkmcnt(6)
	v_mfma_f32_16x16x32_bf16 v[4:7], v[34:37], v[20:23], v[4:7]
	s_waitcnt lgkmcnt(5)
	v_mfma_f32_16x16x32_bf16 v[4:7], v[50:53], v[24:27], v[4:7]
	s_waitcnt lgkmcnt(4)
	v_mfma_f32_16x16x32_bf16 v[58:61], v[54:57], v[28:31], v[4:7]
	s_waitcnt lgkmcnt(3)
	v_mfma_f32_16x16x32_bf16 v[4:7], v[62:65], v[16:19], 0
	s_waitcnt lgkmcnt(2)
	v_mfma_f32_16x16x32_bf16 v[4:7], v[66:69], v[20:23], v[4:7]
	s_waitcnt lgkmcnt(1)
	v_mfma_f32_16x16x32_bf16 v[4:7], v[70:73], v[24:27], v[4:7]
	s_waitcnt lgkmcnt(0)
	v_mfma_f32_16x16x32_bf16 v[4:7], v[74:77], v[28:31], v[4:7]
	s_setprio 0
.LBB0_1285:
	s_cmp_lt_u32 s73, 10
	v_mov_b32_e32 v34, 0
	s_cselect_b64 s[18:19], -1, 0
	s_cmp_gt_u32 s73, 9
	v_mov_b32_e32 v54, 0
	v_mov_b32_e32 v55, 0
	v_mov_b32_e32 v56, 0
	v_mov_b32_e32 v57, 0
	v_mov_b32_e32 v62, 0
	v_mov_b32_e32 v63, 0
	v_mov_b32_e32 v64, 0
	v_mov_b32_e32 v65, 0
	s_cbranch_scc1 .LBB0_1287
	ds_read_b128 v[50:53], v83 offset:34816
	ds_read_b128 v[54:57], v83 offset:34880
	ds_read_b128 v[62:65], v83 offset:34944
	ds_read_b128 v[66:69], v83 offset:35008
	ds_read_b128 v[70:73], v83 offset:39168
	ds_read_b128 v[74:77], v83 offset:39232
	ds_read_b128 v[78:81], v83 offset:39296
	ds_read_b128 v[84:87], v83 offset:39360
	s_waitcnt lgkmcnt(7)
	s_setprio 1
	v_mfma_f32_16x16x32_bf16 v[50:53], v[50:53], v[16:19], 0
	s_waitcnt lgkmcnt(6)
	v_mfma_f32_16x16x32_bf16 v[50:53], v[54:57], v[20:23], v[50:53]
	s_waitcnt lgkmcnt(5)
	v_mfma_f32_16x16x32_bf16 v[50:53], v[62:65], v[24:27], v[50:53]
	s_waitcnt lgkmcnt(4)
	v_mfma_f32_16x16x32_bf16 v[62:65], v[66:69], v[28:31], v[50:53]
	s_waitcnt lgkmcnt(3)
	v_mfma_f32_16x16x32_bf16 v[50:53], v[70:73], v[16:19], 0
	s_waitcnt lgkmcnt(2)
	v_mfma_f32_16x16x32_bf16 v[50:53], v[74:77], v[20:23], v[50:53]
	s_waitcnt lgkmcnt(1)
	v_mfma_f32_16x16x32_bf16 v[50:53], v[78:81], v[24:27], v[50:53]
	s_waitcnt lgkmcnt(0)
	v_mfma_f32_16x16x32_bf16 v[54:57], v[84:87], v[28:31], v[50:53]
	s_setprio 0
.LBB0_1287:
	s_add_i32 s8, s73, -12
	s_cmp_gt_u32 s8, -11
	s_cselect_b64 s[16:17], -1, 0
	s_cmp_lt_u32 s8, -10
	v_mov_b32_e32 v35, 0
	v_mov_b32_e32 v36, 0
	v_mov_b32_e32 v37, 0
	v_mov_b32_e32 v70, 0
	v_mov_b32_e32 v71, 0
	v_mov_b32_e32 v72, 0
	v_mov_b32_e32 v73, 0
	s_cbranch_scc1 .LBB0_1289
	v_or_b32_e32 v74, 0xb0, v98
	v_mad_u32_u24 v88, v74, s33, v82
	ds_read_b128 v[34:37], v83 offset:43520
	ds_read_b128 v[50:53], v83 offset:43584
	ds_read_b128 v[66:69], v83 offset:43648
	ds_read_b128 v[70:73], v83 offset:43712
	ds_read_b128 v[74:77], v88
	ds_read_b128 v[78:81], v88 offset:64
	ds_read_b128 v[84:87], v88 offset:128
	ds_read_b128 v[88:91], v88 offset:192
	s_waitcnt lgkmcnt(7)
	s_setprio 1
	v_mfma_f32_16x16x32_bf16 v[34:37], v[34:37], v[16:19], 0
	s_waitcnt lgkmcnt(6)
	v_mfma_f32_16x16x32_bf16 v[34:37], v[50:53], v[20:23], v[34:37]
	s_waitcnt lgkmcnt(5)
	v_mfma_f32_16x16x32_bf16 v[34:37], v[66:69], v[24:27], v[34:37]
	s_waitcnt lgkmcnt(4)
	v_mfma_f32_16x16x32_bf16 v[70:73], v[70:73], v[28:31], v[34:37]
	s_waitcnt lgkmcnt(3)
	v_mfma_f32_16x16x32_bf16 v[34:37], v[74:77], v[16:19], 0
	s_waitcnt lgkmcnt(2)
	v_mfma_f32_16x16x32_bf16 v[34:37], v[78:81], v[20:23], v[34:37]
	s_waitcnt lgkmcnt(1)
	v_mfma_f32_16x16x32_bf16 v[34:37], v[84:87], v[24:27], v[34:37]
	s_waitcnt lgkmcnt(0)
	v_mfma_f32_16x16x32_bf16 v[34:37], v[88:91], v[28:31], v[34:37]
	s_setprio 0
.LBB0_1289:
	s_add_i32 s8, s73, -14
	s_cmp_gt_u32 s8, -11
	v_mov_b32_e32 v50, 0
	s_cselect_b64 s[14:15], -1, 0
	s_cmp_lt_u32 s8, -10
	v_mov_b32_e32 v66, 0
	v_mov_b32_e32 v67, 0
	v_mov_b32_e32 v68, 0
	v_mov_b32_e32 v69, 0
	v_mov_b32_e32 v74, 0
	v_mov_b32_e32 v75, 0
	v_mov_b32_e32 v76, 0
	v_mov_b32_e32 v77, 0
	s_cbranch_scc1 .LBB0_1291
	ds_read_b128 v[66:69], v83 offset:52224
	ds_read_b128 v[74:77], v83 offset:52288
	ds_read_b128 v[78:81], v83 offset:52352
	ds_read_b128 v[84:87], v83 offset:52416
	ds_read_b128 v[88:91], v83 offset:56576
	ds_read_b128 v[92:95], v83 offset:56640
	ds_read_b128 v[102:105], v83 offset:56704
	ds_read_b128 v[106:109], v83 offset:56768
	s_waitcnt lgkmcnt(7)
	s_setprio 1
	v_mfma_f32_16x16x32_bf16 v[66:69], v[66:69], v[16:19], 0
	s_waitcnt lgkmcnt(6)
	v_mfma_f32_16x16x32_bf16 v[66:69], v[74:77], v[20:23], v[66:69]
	s_waitcnt lgkmcnt(5)
	v_mfma_f32_16x16x32_bf16 v[66:69], v[78:81], v[24:27], v[66:69]
	s_waitcnt lgkmcnt(4)
	v_mfma_f32_16x16x32_bf16 v[74:77], v[84:87], v[28:31], v[66:69]
	s_waitcnt lgkmcnt(3)
	v_mfma_f32_16x16x32_bf16 v[66:69], v[88:91], v[16:19], 0
	s_waitcnt lgkmcnt(2)
	v_mfma_f32_16x16x32_bf16 v[66:69], v[92:95], v[20:23], v[66:69]
	s_waitcnt lgkmcnt(1)
	v_mfma_f32_16x16x32_bf16 v[66:69], v[102:105], v[24:27], v[66:69]
	s_waitcnt lgkmcnt(0)
	v_mfma_f32_16x16x32_bf16 v[66:69], v[106:109], v[28:31], v[66:69]
	s_setprio 0
.LBB0_1291:
	s_add_i32 s8, s73, -16
	s_cmp_gt_u32 s8, -11
	s_cselect_b64 s[12:13], -1, 0
	s_cmp_lt_u32 s8, -10
	v_mov_b32_e32 v51, 0
	v_mov_b32_e32 v52, 0
	v_mov_b32_e32 v53, 0
	v_mov_b32_e32 v78, 0
	v_mov_b32_e32 v79, 0
	v_mov_b32_e32 v80, 0
	v_mov_b32_e32 v81, 0
	s_cbranch_scc1 .LBB0_1293
	ds_read_b128 v[50:53], v83 offset:60928
	ds_read_b128 v[78:81], v83 offset:60992
	ds_read_b128 v[84:87], v83 offset:61056
	ds_read_b128 v[88:91], v83 offset:61120
	v_or_b32_e32 v83, 0xf0, v98
	v_mad_u32_u24 v82, v83, s33, v82
	ds_read_b128 v[92:95], v82
	ds_read_b128 v[102:105], v82 offset:64
	ds_read_b128 v[106:109], v82 offset:128
	ds_read_b128 v[110:113], v82 offset:192
	s_waitcnt lgkmcnt(7)
	s_setprio 1
	v_mfma_f32_16x16x32_bf16 v[50:53], v[50:53], v[16:19], 0
	s_waitcnt lgkmcnt(3)
	v_mfma_f32_16x16x32_bf16 v[16:19], v[92:95], v[16:19], 0
	v_mfma_f32_16x16x32_bf16 v[50:53], v[78:81], v[20:23], v[50:53]
	s_waitcnt lgkmcnt(2)
	v_mfma_f32_16x16x32_bf16 v[16:19], v[102:105], v[20:23], v[16:19]
	v_mfma_f32_16x16x32_bf16 v[50:53], v[84:87], v[24:27], v[50:53]
	s_waitcnt lgkmcnt(1)
	v_mfma_f32_16x16x32_bf16 v[16:19], v[106:109], v[24:27], v[16:19]
	v_mfma_f32_16x16x32_bf16 v[78:81], v[88:91], v[28:31], v[50:53]
	s_waitcnt lgkmcnt(0)
	v_mfma_f32_16x16x32_bf16 v[50:53], v[110:113], v[28:31], v[16:19]
	s_setprio 0
.LBB0_1293:
	v_lshl_or_b32 v82, s73, 4, v32
	v_readlane_b32 s8, v252, 57
	s_nop 0
	v_max_i32_e32 v16, 0x80, v82
	v_readlane_b32 s9, v252, 58
	v_lshrrev_b32_e32 v18, 2, v98
	v_add_u32_e32 v17, 0x80, v82
	v_cndmask_b32_e64 v16, v82, v16, s[8:9]
	v_and_b32_e32 v83, 12, v18
	v_sub_u32_e32 v17, v17, v16
	v_sub_u32_e32 v16, v16, v83
	v_sub_u32_e32 v18, 0, v16
	v_sub_u32_e32 v222, 1, v16
	v_sub_u32_e32 v250, 2, v16
	v_cmp_gt_u32_e32 vcc, v18, v17
	v_cmp_gt_u32_e64 s[8:9], v222, v17
	v_cmp_gt_u32_e64 s[10:11], v250, v17
	v_cndmask_b32_e32 v12, v12, v225, vcc
	v_cndmask_b32_e64 v13, v13, v225, s[8:9]
	v_cndmask_b32_e64 v14, v14, v225, s[10:11]
	v_sub_u32_e32 v18, 3, v16
	v_sub_u32_e32 v222, 16, v16
	v_sub_u32_e32 v250, 17, v16
	v_cmp_gt_u32_e32 vcc, v18, v17
	v_cmp_gt_u32_e64 s[8:9], v222, v17
	v_cmp_gt_u32_e64 s[10:11], v250, v17
	v_cndmask_b32_e32 v15, v15, v225, vcc
	v_cndmask_b32_e64 v8, v8, v225, s[8:9]
	v_cndmask_b32_e64 v9, v9, v225, s[10:11]
	v_sub_u32_e32 v18, 18, v16
	v_sub_u32_e32 v222, 19, v16
	v_sub_u32_e32 v250, 32, v16
	v_cmp_gt_u32_e32 vcc, v18, v17
	v_cmp_gt_u32_e64 s[8:9], v222, v17
	v_cmp_gt_u32_e64 s[10:11], v250, v17
	v_cndmask_b32_e32 v10, v10, v225, vcc
	v_cndmask_b32_e64 v11, v11, v225, s[8:9]
	v_cndmask_b32_e64 v19, v42, v225, s[10:11]
	v_sub_u32_e32 v18, 33, v16
	v_sub_u32_e32 v222, 34, v16
	v_sub_u32_e32 v250, 35, v16
	v_cmp_gt_u32_e32 vcc, v18, v17
	v_cmp_gt_u32_e64 s[8:9], v222, v17
	v_cmp_gt_u32_e64 s[10:11], v250, v17
	v_cndmask_b32_e32 v20, v43, v225, vcc
	v_cndmask_b32_e64 v21, v44, v225, s[8:9]
	v_cndmask_b32_e64 v22, v45, v225, s[10:11]
	v_sub_u32_e32 v18, 48, v16
	v_sub_u32_e32 v222, 49, v16
	v_sub_u32_e32 v250, 50, v16
	v_cmp_gt_u32_e32 vcc, v18, v17
	v_cmp_gt_u32_e64 s[8:9], v222, v17
	v_cmp_gt_u32_e64 s[10:11], v250, v17
	v_cndmask_b32_e32 v0, v0, v225, vcc
	v_cndmask_b32_e64 v1, v1, v225, s[8:9]
	v_cndmask_b32_e64 v2, v2, v225, s[10:11]
	v_sub_u32_e32 v18, 51, v16
	v_sub_u32_e32 v222, 64, v16
	v_sub_u32_e32 v250, 0x41, v16
	v_cmp_gt_u32_e32 vcc, v18, v17
	v_cmp_gt_u32_e64 s[8:9], v222, v17
	v_cmp_gt_u32_e64 s[10:11], v250, v17
	v_cndmask_b32_e32 v3, v3, v225, vcc
	v_cndmask_b32_e64 v23, v46, v225, s[8:9]
	v_cndmask_b32_e64 v24, v47, v225, s[10:11]
	v_sub_u32_e32 v18, 0x42, v16
	v_sub_u32_e32 v222, 0x43, v16
	v_sub_u32_e32 v250, 0x50, v16
	v_cmp_gt_u32_e32 vcc, v18, v17
	v_cmp_gt_u32_e64 s[8:9], v222, v17
	v_cmp_gt_u32_e64 s[10:11], v250, v17
	v_cndmask_b32_e32 v25, v48, v225, vcc
	v_cndmask_b32_e64 v26, v49, v225, s[8:9]
	v_cndmask_b32_e64 v27, v38, v225, s[10:11]
	v_sub_u32_e32 v18, 0x51, v16
	v_sub_u32_e32 v222, 0x52, v16
	v_sub_u32_e32 v250, 0x53, v16
	v_cmp_gt_u32_e32 vcc, v18, v17
	v_cmp_gt_u32_e64 s[8:9], v222, v17
	v_cmp_gt_u32_e64 s[10:11], v250, v17
	v_cndmask_b32_e32 v28, v39, v225, vcc
	v_cndmask_b32_e64 v29, v40, v225, s[8:9]
	v_cndmask_b32_e64 v30, v41, v225, s[10:11]
	v_sub_u32_e32 v18, 0x60, v16
	v_sub_u32_e32 v222, 0x61, v16
	v_sub_u32_e32 v250, 0x62, v16
	v_cmp_gt_u32_e32 vcc, v18, v17
	v_cmp_gt_u32_e64 s[8:9], v222, v17
	v_cmp_gt_u32_e64 s[10:11], v250, v17
	v_cndmask_b32_e32 v31, v58, v225, vcc
	v_cndmask_b32_e64 v39, v59, v225, s[8:9]
	v_cndmask_b32_e64 v40, v60, v225, s[10:11]
	v_sub_u32_e32 v18, 0x63, v16
	v_sub_u32_e32 v222, 0x70, v16
	v_sub_u32_e32 v250, 0x71, v16
	v_cmp_gt_u32_e32 vcc, v18, v17
	v_cmp_gt_u32_e64 s[8:9], v222, v17
	v_cmp_gt_u32_e64 s[10:11], v250, v17
	v_cndmask_b32_e32 v41, v61, v225, vcc
	v_cndmask_b32_e64 v4, v4, v225, s[8:9]
	v_cndmask_b32_e64 v5, v5, v225, s[10:11]
	v_sub_u32_e32 v18, 0x72, v16
	v_sub_u32_e32 v222, 0x73, v16
	v_sub_u32_e32 v250, 0x80, v16
	v_cmp_gt_u32_e32 vcc, v18, v17
	v_cmp_gt_u32_e64 s[8:9], v222, v17
	v_cmp_gt_u32_e64 s[10:11], v250, v17
	v_cndmask_b32_e32 v6, v6, v225, vcc
	v_cndmask_b32_e64 v7, v7, v225, s[8:9]
	v_cndmask_b32_e64 v42, v62, v225, s[10:11]
	v_sub_u32_e32 v18, 0x81, v16
	v_sub_u32_e32 v222, 0x82, v16
	v_sub_u32_e32 v250, 0x83, v16
	v_cmp_gt_u32_e32 vcc, v18, v17
	v_cmp_gt_u32_e64 s[8:9], v222, v17
	v_cmp_gt_u32_e64 s[10:11], v250, v17
	v_cndmask_b32_e32 v43, v63, v225, vcc
	v_cndmask_b32_e64 v44, v64, v225, s[8:9]
	v_cndmask_b32_e64 v45, v65, v225, s[10:11]
	v_sub_u32_e32 v18, 0x90, v16
	v_sub_u32_e32 v222, 0x91, v16
	v_sub_u32_e32 v250, 0x92, v16
	v_cmp_gt_u32_e32 vcc, v18, v17
	v_cmp_gt_u32_e64 s[8:9], v222, v17
	v_cmp_gt_u32_e64 s[10:11], v250, v17
	v_cndmask_b32_e32 v46, v54, v225, vcc
	v_cndmask_b32_e64 v47, v55, v225, s[8:9]
	v_cndmask_b32_e64 v48, v56, v225, s[10:11]
	v_sub_u32_e32 v18, 0x93, v16
	v_sub_u32_e32 v222, 0xa0, v16
	v_sub_u32_e32 v250, 0xa1, v16
	v_cmp_gt_u32_e32 vcc, v18, v17
	v_cmp_gt_u32_e64 s[8:9], v222, v17
	v_cmp_gt_u32_e64 s[10:11], v250, v17
	v_cndmask_b32_e32 v49, v57, v225, vcc
	v_cndmask_b32_e64 v54, v70, v225, s[8:9]
	v_cndmask_b32_e64 v55, v71, v225, s[10:11]
	v_sub_u32_e32 v18, 0xa2, v16
	v_sub_u32_e32 v222, 0xa3, v16
	v_sub_u32_e32 v250, 0xb0, v16
	v_cmp_gt_u32_e32 vcc, v18, v17
	v_cmp_gt_u32_e64 s[8:9], v222, v17
	v_cmp_gt_u32_e64 s[10:11], v250, v17
	v_cndmask_b32_e32 v56, v72, v225, vcc
	v_cndmask_b32_e64 v57, v73, v225, s[8:9]
	v_cndmask_b32_e64 v34, v34, v225, s[10:11]
	v_sub_u32_e32 v18, 0xb1, v16
	v_sub_u32_e32 v222, 0xb2, v16
	v_sub_u32_e32 v250, 0xb3, v16
	v_cmp_gt_u32_e32 vcc, v18, v17
	v_cmp_gt_u32_e64 s[8:9], v222, v17
	v_cmp_gt_u32_e64 s[10:11], v250, v17
	v_cndmask_b32_e32 v35, v35, v225, vcc
	v_cndmask_b32_e64 v62, v36, v225, s[8:9]
	v_cndmask_b32_e64 v64, v37, v225, s[10:11]
	v_sub_u32_e32 v18, 0xc0, v16
	v_sub_u32_e32 v222, 0xc1, v16
	v_sub_u32_e32 v250, 0xc2, v16
	v_cmp_gt_u32_e32 vcc, v18, v17
	v_cmp_gt_u32_e64 s[8:9], v222, v17
	v_cmp_gt_u32_e64 s[10:11], v250, v17
	v_cndmask_b32_e32 v102, v74, v225, vcc
	v_cndmask_b32_e64 v103, v75, v225, s[8:9]
	v_cndmask_b32_e64 v104, v76, v225, s[10:11]
	v_sub_u32_e32 v18, 0xc3, v16
	v_sub_u32_e32 v222, 0xd0, v16
	v_sub_u32_e32 v250, 0xd1, v16
	v_cmp_gt_u32_e32 vcc, v18, v17
	v_cmp_gt_u32_e64 s[8:9], v222, v17
	v_cmp_gt_u32_e64 s[10:11], v250, v17
	v_cndmask_b32_e32 v105, v77, v225, vcc
	v_cndmask_b32_e64 v106, v66, v225, s[8:9]
	v_cndmask_b32_e64 v107, v67, v225, s[10:11]
	v_sub_u32_e32 v18, 0xd2, v16
	v_sub_u32_e32 v222, 0xd3, v16
	v_sub_u32_e32 v250, 0xe0, v16
	v_cmp_gt_u32_e32 vcc, v18, v17
	v_cmp_gt_u32_e64 s[8:9], v222, v17
	v_cmp_gt_u32_e64 s[10:11], v250, v17
	v_cndmask_b32_e32 v108, v68, v225, vcc
	v_cndmask_b32_e64 v109, v69, v225, s[8:9]
	v_cndmask_b32_e64 v110, v78, v225, s[10:11]
	v_sub_u32_e32 v18, 0xe1, v16
	v_sub_u32_e32 v222, 0xe2, v16
	v_sub_u32_e32 v250, 0xe3, v16
	v_cmp_gt_u32_e32 vcc, v18, v17
	v_cmp_gt_u32_e64 s[8:9], v222, v17
	v_cmp_gt_u32_e64 s[10:11], v250, v17
	v_cndmask_b32_e32 v111, v79, v225, vcc
	v_cndmask_b32_e64 v112, v80, v225, s[8:9]
	v_cndmask_b32_e64 v113, v81, v225, s[10:11]
	v_sub_u32_e32 v18, 0xf0, v16
	v_sub_u32_e32 v222, 0xf1, v16
	v_sub_u32_e32 v250, 0xf2, v16
	v_cmp_gt_u32_e32 vcc, v18, v17
	v_cmp_gt_u32_e64 s[8:9], v222, v17
	v_cmp_gt_u32_e64 s[10:11], v250, v17
	v_cndmask_b32_e32 v114, v50, v225, vcc
	v_cndmask_b32_e64 v115, v51, v225, s[8:9]
	v_cndmask_b32_e64 v116, v52, v225, s[10:11]
	v_sub_u32_e32 v18, 0xf3, v16
	v_cmp_gt_u32_e32 vcc, v18, v17
	s_nop 1
	v_cndmask_b32_e32 v16, v53, v225, vcc
	v_max_f32_e32 v17, v12, v13
	v_max_f32_e32 v18, v14, v15
	s_mov_b32 s8, 0xff61b1e6
	v_max3_f32 v17, v17, v18, s8
	v_max_f32_e32 v18, v8, v9
	v_max_f32_e32 v36, v10, v11
	v_max3_f32 v17, v18, v36, v17
	v_max_f32_e32 v18, v19, v20
	v_max_f32_e32 v36, v21, v22
	v_max3_f32 v17, v18, v36, v17
	v_max_f32_e32 v18, v0, v1
	v_max_f32_e32 v36, v2, v3
	v_max3_f32 v17, v18, v36, v17
	v_max_f32_e32 v18, v23, v24
	v_max_f32_e32 v36, v25, v26
	v_max3_f32 v17, v18, v36, v17
	v_max_f32_e32 v18, v27, v28
	v_max_f32_e32 v36, v29, v30
	v_max3_f32 v17, v18, v36, v17
	v_max_f32_e32 v18, v31, v39
	v_max_f32_e32 v36, v40, v41
	v_max3_f32 v17, v18, v36, v17
	v_max_f32_e32 v18, v4, v5
	v_max_f32_e32 v36, v6, v7
	v_max3_f32 v17, v18, v36, v17
	v_max_f32_e32 v18, v42, v43
	v_max_f32_e32 v36, v44, v45
	v_max3_f32 v17, v18, v36, v17
	v_max_f32_e32 v18, v46, v47
	v_max_f32_e32 v36, v48, v49
	v_max3_f32 v17, v18, v36, v17
	v_max_f32_e32 v18, v54, v55
	v_max_f32_e32 v36, v56, v57
	v_max3_f32 v17, v18, v36, v17
	v_max_f32_e32 v18, v34, v35
	v_max_f32_e32 v36, v62, v64
	v_max3_f32 v17, v18, v36, v17
	v_max_f32_e32 v18, v102, v103
	v_max_f32_e32 v36, v104, v105
	v_max3_f32 v17, v18, v36, v17
	v_max_f32_e32 v18, v106, v107
	v_max_f32_e32 v36, v108, v109
	v_max3_f32 v17, v18, v36, v17
	v_max_f32_e32 v18, v110, v111
	v_max_f32_e32 v36, v112, v113
	v_max3_f32 v17, v18, v36, v17
	v_max_f32_e32 v18, v114, v115
	v_max_f32_e32 v36, v116, v16
	v_max3_f32 v17, v18, v36, v17
	ds_bpermute_b32 v18, v100, v17
	s_andn2_b64 vcc, exec, s[44:45]
	s_waitcnt lgkmcnt(0)
	v_max_f32_e32 v17, v17, v18
	ds_bpermute_b32 v18, v101, v17
	s_waitcnt lgkmcnt(0)
	v_max_f32_e32 v38, v17, v18
	v_sub_f32_e32 v12, v12, v38
	v_exp_f32_e32 v12, v12
	v_sub_f32_e32 v13, v13, v38
	v_exp_f32_e32 v13, v13
	v_sub_f32_e32 v14, v14, v38
	v_exp_f32_e32 v14, v14
	v_sub_f32_e32 v15, v15, v38
	v_exp_f32_e32 v15, v15
	v_sub_f32_e32 v8, v8, v38
	v_add_f32_e32 v17, 0, v12
	v_exp_f32_e32 v8, v8
	v_sub_f32_e32 v9, v9, v38
	v_add_f32_e32 v17, v13, v17
	v_exp_f32_e32 v9, v9
	v_sub_f32_e32 v10, v10, v38
	v_add_f32_e32 v17, v14, v17
	v_exp_f32_e32 v10, v10
	v_sub_f32_e32 v11, v11, v38
	v_add_f32_e32 v17, v15, v17
	v_exp_f32_e32 v11, v11
	v_sub_f32_e32 v18, v19, v38
	v_add_f32_e32 v17, v8, v17
	v_exp_f32_e32 v36, v18
	v_sub_f32_e32 v18, v20, v38
	v_add_f32_e32 v17, v9, v17
	v_exp_f32_e32 v37, v18
	v_sub_f32_e32 v18, v21, v38
	v_add_f32_e32 v17, v10, v17
	v_exp_f32_e32 v92, v18
	v_sub_f32_e32 v18, v22, v38
	v_add_f32_e32 v17, v11, v17
	v_exp_f32_e32 v93, v18
	v_sub_f32_e32 v0, v0, v38
	v_add_f32_e32 v17, v36, v17
	v_exp_f32_e32 v95, v0
	v_sub_f32_e32 v0, v1, v38
	v_add_f32_e32 v17, v37, v17
	v_exp_f32_e32 v97, v0
	v_sub_f32_e32 v0, v2, v38
	v_add_f32_e32 v17, v92, v17
	v_exp_f32_e32 v94, v0
	v_sub_f32_e32 v0, v3, v38
	v_add_f32_e32 v17, v93, v17
	v_exp_f32_e32 v96, v0
	v_sub_f32_e32 v1, v23, v38
	v_add_f32_e32 v0, v95, v17
	v_exp_f32_e32 v84, v1
	v_sub_f32_e32 v1, v24, v38
	v_add_f32_e32 v0, v97, v0
	v_exp_f32_e32 v85, v1
	v_sub_f32_e32 v1, v25, v38
	v_add_f32_e32 v0, v94, v0
	v_exp_f32_e32 v86, v1
	v_sub_f32_e32 v1, v26, v38
	v_add_f32_e32 v0, v96, v0
	v_exp_f32_e32 v87, v1
	v_sub_f32_e32 v1, v27, v38
	v_add_f32_e32 v0, v84, v0
	v_exp_f32_e32 v89, v1
	v_sub_f32_e32 v1, v28, v38
	v_add_f32_e32 v0, v85, v0
	v_exp_f32_e32 v91, v1
	v_sub_f32_e32 v1, v29, v38
	v_add_f32_e32 v0, v86, v0
	v_exp_f32_e32 v88, v1
	v_sub_f32_e32 v1, v30, v38
	v_add_f32_e32 v0, v87, v0
	v_exp_f32_e32 v90, v1
	v_sub_f32_e32 v1, v31, v38
	v_add_f32_e32 v0, v89, v0
	v_exp_f32_e32 v74, v1
	v_sub_f32_e32 v1, v39, v38
	v_add_f32_e32 v0, v91, v0
	v_exp_f32_e32 v75, v1
	v_sub_f32_e32 v1, v40, v38
	v_add_f32_e32 v0, v88, v0
	v_exp_f32_e32 v76, v1
	v_sub_f32_e32 v1, v41, v38
	v_add_f32_e32 v0, v90, v0
	v_exp_f32_e32 v77, v1
	v_sub_f32_e32 v1, v4, v38
	v_add_f32_e32 v0, v74, v0
	v_exp_f32_e32 v79, v1
	v_sub_f32_e32 v1, v5, v38
	v_add_f32_e32 v0, v75, v0
	v_exp_f32_e32 v81, v1
	v_sub_f32_e32 v1, v6, v38
	v_add_f32_e32 v0, v76, v0
	v_exp_f32_e32 v78, v1
	v_sub_f32_e32 v1, v7, v38
	v_add_f32_e32 v0, v77, v0
	v_exp_f32_e32 v80, v1
	v_sub_f32_e32 v1, v42, v38
	v_add_f32_e32 v0, v79, v0
	v_exp_f32_e32 v66, v1
	v_sub_f32_e32 v1, v43, v38
	v_add_f32_e32 v0, v81, v0
	v_exp_f32_e32 v67, v1
	v_sub_f32_e32 v1, v44, v38
	v_add_f32_e32 v0, v78, v0
	v_exp_f32_e32 v68, v1
	v_sub_f32_e32 v1, v45, v38
	v_add_f32_e32 v0, v80, v0
	v_exp_f32_e32 v69, v1
	v_sub_f32_e32 v1, v46, v38
	v_add_f32_e32 v0, v66, v0
	v_exp_f32_e32 v71, v1
	v_sub_f32_e32 v1, v47, v38
	v_add_f32_e32 v0, v67, v0
	v_exp_f32_e32 v73, v1
	v_sub_f32_e32 v1, v48, v38
	v_add_f32_e32 v0, v68, v0
	v_exp_f32_e32 v70, v1
	v_sub_f32_e32 v1, v49, v38
	v_add_f32_e32 v0, v69, v0
	v_exp_f32_e32 v72, v1
	v_sub_f32_e32 v1, v54, v38
	v_add_f32_e32 v0, v71, v0
	v_exp_f32_e32 v58, v1
	v_sub_f32_e32 v1, v55, v38
	v_add_f32_e32 v0, v73, v0
	v_exp_f32_e32 v59, v1
	v_sub_f32_e32 v1, v56, v38
	v_add_f32_e32 v0, v70, v0
	v_exp_f32_e32 v60, v1
	v_sub_f32_e32 v1, v57, v38
	v_add_f32_e32 v0, v72, v0
	v_exp_f32_e32 v61, v1
	v_sub_f32_e32 v1, v34, v38
	v_add_f32_e32 v0, v58, v0
	v_exp_f32_e32 v63, v1
	v_sub_f32_e32 v1, v35, v38
	v_add_f32_e32 v0, v59, v0
	v_exp_f32_e32 v65, v1
	v_sub_f32_e32 v1, v62, v38
	v_add_f32_e32 v0, v60, v0
	v_exp_f32_e32 v62, v1
	v_sub_f32_e32 v1, v64, v38
	v_add_f32_e32 v0, v61, v0
	v_exp_f32_e32 v64, v1
	v_sub_f32_e32 v1, v102, v38
	v_add_f32_e32 v0, v63, v0
	v_exp_f32_e32 v50, v1
	v_sub_f32_e32 v1, v103, v38
	v_add_f32_e32 v0, v65, v0
	v_exp_f32_e32 v51, v1
	v_sub_f32_e32 v1, v104, v38
	v_add_f32_e32 v0, v62, v0
	v_exp_f32_e32 v52, v1
	v_sub_f32_e32 v1, v105, v38
	v_add_f32_e32 v0, v64, v0
	v_exp_f32_e32 v53, v1
	v_sub_f32_e32 v1, v106, v38
	v_add_f32_e32 v0, v50, v0
	v_exp_f32_e32 v55, v1
	v_sub_f32_e32 v1, v107, v38
	v_add_f32_e32 v0, v51, v0
	v_exp_f32_e32 v57, v1
	v_sub_f32_e32 v1, v108, v38
	v_add_f32_e32 v0, v52, v0
	v_exp_f32_e32 v54, v1
	v_sub_f32_e32 v1, v109, v38
	v_add_f32_e32 v0, v53, v0
	v_exp_f32_e32 v56, v1
	v_sub_f32_e32 v1, v110, v38
	v_add_f32_e32 v0, v55, v0
	v_exp_f32_e32 v42, v1
	v_sub_f32_e32 v1, v111, v38
	v_add_f32_e32 v0, v57, v0
	v_exp_f32_e32 v43, v1
	v_sub_f32_e32 v1, v112, v38
	v_add_f32_e32 v0, v54, v0
	v_exp_f32_e32 v44, v1
	v_sub_f32_e32 v1, v113, v38
	v_add_f32_e32 v0, v56, v0
	v_exp_f32_e32 v45, v1
	v_sub_f32_e32 v1, v114, v38
	v_add_f32_e32 v0, v42, v0
	v_exp_f32_e32 v47, v1
	v_sub_f32_e32 v1, v115, v38
	v_add_f32_e32 v0, v43, v0
	v_exp_f32_e32 v49, v1
	v_sub_f32_e32 v1, v116, v38
	v_add_f32_e32 v0, v44, v0
	v_exp_f32_e32 v46, v1
	v_sub_f32_e32 v1, v16, v38
	v_add_f32_e32 v0, v45, v0
	v_exp_f32_e32 v48, v1
	v_add_f32_e32 v0, v47, v0
	v_add_f32_e32 v0, v49, v0
	v_add_f32_e32 v0, v46, v0
	v_add_f32_e32 v0, v48, v0
	ds_bpermute_b32 v1, v100, v0
	v_cvt_pk_bf16_f32 v2, v8, v9
	v_cvt_pk_bf16_f32 v3, v10, v11
	s_waitcnt lgkmcnt(0)
	v_add_f32_e32 v39, v0, v1
	ds_bpermute_b32 v40, v101, v39
	v_lshrrev_b32_e32 v0, 2, v32
	v_or_b32_e32 v0, v83, v0
	v_lshlrev_b32_e32 v1, 3, v98
	v_mul_u32_u24_e32 v0, 0x120, v0
	v_and_b32_e32 v1, 24, v1
	v_add3_u32 v41, s27, v0, v1
	v_cvt_pk_bf16_f32 v0, v12, v13
	v_cvt_pk_bf16_f32 v1, v14, v15
	s_cbranch_vccnz .LBB0_1295
	ds_read_b64_tr_b16 v[4:5], v41
	ds_read_b64_tr_b16 v[8:9], v41 offset:32
	ds_read_b64_tr_b16 v[12:13], v41 offset:64
	ds_read_b64_tr_b16 v[16:17], v41 offset:96
	ds_read_b64_tr_b16 v[6:7], v41 offset:4608
	ds_read_b64_tr_b16 v[10:11], v41 offset:4640
	ds_read_b64_tr_b16 v[14:15], v41 offset:4672
	ds_read_b64_tr_b16 v[18:19], v41 offset:4704
	ds_read_b64_tr_b16 v[102:103], v41 offset:128
	ds_read_b64_tr_b16 v[106:107], v41 offset:160
	ds_read_b64_tr_b16 v[110:111], v41 offset:192
	ds_read_b64_tr_b16 v[114:115], v41 offset:224
	ds_read_b64_tr_b16 v[104:105], v41 offset:4736
	ds_read_b64_tr_b16 v[108:109], v41 offset:4768
	ds_read_b64_tr_b16 v[112:113], v41 offset:4800
	ds_read_b64_tr_b16 v[116:117], v41 offset:4832
	s_waitcnt lgkmcnt(11)
	s_setprio 1
	v_mfma_f32_16x16x32_bf16 v[28:31], v[4:7], v[0:3], 0
	s_waitcnt lgkmcnt(10)
	v_mfma_f32_16x16x32_bf16 v[24:27], v[8:11], v[0:3], 0
	s_waitcnt lgkmcnt(9)
	v_mfma_f32_16x16x32_bf16 v[20:23], v[12:15], v[0:3], 0
	s_waitcnt lgkmcnt(8)
	v_mfma_f32_16x16x32_bf16 v[16:19], v[16:19], v[0:3], 0
	s_waitcnt lgkmcnt(3)
	v_mfma_f32_16x16x32_bf16 v[12:15], v[102:105], v[0:3], 0
	s_waitcnt lgkmcnt(2)
	v_mfma_f32_16x16x32_bf16 v[8:11], v[106:109], v[0:3], 0
	s_waitcnt lgkmcnt(1)
	v_mfma_f32_16x16x32_bf16 v[4:7], v[110:113], v[0:3], 0
	s_waitcnt lgkmcnt(0)
	v_mfma_f32_16x16x32_bf16 v[0:3], v[114:117], v[0:3], 0
	s_setprio 0
	s_branch .LBB0_1296

.LBB0_1296:
	s_andn2_b64 vcc, exec, s[34:35]
	v_cvt_pk_bf16_f32 v34, v36, v37
	v_cvt_pk_bf16_f32 v35, v92, v93
	v_cvt_pk_bf16_f32 v36, v95, v97
	v_cvt_pk_bf16_f32 v37, v94, v96
	s_cbranch_vccnz .LBB0_1298
	ds_read_b64_tr_b16 v[92:93], v41 offset:9216
	ds_read_b64_tr_b16 v[102:103], v41 offset:9248
	ds_read_b64_tr_b16 v[106:107], v41 offset:9280
	ds_read_b64_tr_b16 v[110:111], v41 offset:9312
	ds_read_b64_tr_b16 v[94:95], v41 offset:13824
	ds_read_b64_tr_b16 v[104:105], v41 offset:13856
	ds_read_b64_tr_b16 v[108:109], v41 offset:13888
	ds_read_b64_tr_b16 v[112:113], v41 offset:13920
	ds_read_b64_tr_b16 v[114:115], v41 offset:9344
	ds_read_b64_tr_b16 v[118:119], v41 offset:9376
	ds_read_b64_tr_b16 v[122:123], v41 offset:9408
	ds_read_b64_tr_b16 v[126:127], v41 offset:9440
	ds_read_b64_tr_b16 v[116:117], v41 offset:13952
	ds_read_b64_tr_b16 v[120:121], v41 offset:13984
	ds_read_b64_tr_b16 v[124:125], v41 offset:14016
	ds_read_b64_tr_b16 v[128:129], v41 offset:14048
	s_waitcnt lgkmcnt(11)
	s_setprio 1
	v_mfma_f32_16x16x32_bf16 v[28:31], v[92:95], v[34:37], v[28:31]
	s_waitcnt lgkmcnt(10)
	v_mfma_f32_16x16x32_bf16 v[24:27], v[102:105], v[34:37], v[24:27]
	s_waitcnt lgkmcnt(9)
	v_mfma_f32_16x16x32_bf16 v[20:23], v[106:109], v[34:37], v[20:23]
	s_waitcnt lgkmcnt(8)
	v_mfma_f32_16x16x32_bf16 v[16:19], v[110:113], v[34:37], v[16:19]
	s_waitcnt lgkmcnt(3)
	v_mfma_f32_16x16x32_bf16 v[12:15], v[114:117], v[34:37], v[12:15]
	s_waitcnt lgkmcnt(2)
	v_mfma_f32_16x16x32_bf16 v[8:11], v[118:121], v[34:37], v[8:11]
	s_waitcnt lgkmcnt(1)
	v_mfma_f32_16x16x32_bf16 v[4:7], v[122:125], v[34:37], v[4:7]
	s_waitcnt lgkmcnt(0)
	v_mfma_f32_16x16x32_bf16 v[0:3], v[126:129], v[34:37], v[0:3]
	s_setprio 0
.LBB0_1298:
	s_andn2_b64 vcc, exec, s[30:31]
	v_cvt_pk_bf16_f32 v34, v84, v85
	v_cvt_pk_bf16_f32 v35, v86, v87
	v_cvt_pk_bf16_f32 v36, v89, v91
	v_cvt_pk_bf16_f32 v37, v88, v90
	s_cbranch_vccnz .LBB0_1300
	ds_read_b64_tr_b16 v[84:85], v41 offset:18432
	ds_read_b64_tr_b16 v[88:89], v41 offset:18464
	ds_read_b64_tr_b16 v[92:93], v41 offset:18496
	ds_read_b64_tr_b16 v[102:103], v41 offset:18528
	ds_read_b64_tr_b16 v[86:87], v41 offset:23040
	ds_read_b64_tr_b16 v[90:91], v41 offset:23072
	ds_read_b64_tr_b16 v[94:95], v41 offset:23104
	ds_read_b64_tr_b16 v[104:105], v41 offset:23136
	ds_read_b64_tr_b16 v[106:107], v41 offset:18560
	ds_read_b64_tr_b16 v[110:111], v41 offset:18592
	ds_read_b64_tr_b16 v[114:115], v41 offset:18624
	ds_read_b64_tr_b16 v[118:119], v41 offset:18656
	ds_read_b64_tr_b16 v[108:109], v41 offset:23168
	ds_read_b64_tr_b16 v[112:113], v41 offset:23200
	ds_read_b64_tr_b16 v[116:117], v41 offset:23232
	ds_read_b64_tr_b16 v[120:121], v41 offset:23264
	s_waitcnt lgkmcnt(11)
	s_setprio 1
	v_mfma_f32_16x16x32_bf16 v[28:31], v[84:87], v[34:37], v[28:31]
	s_waitcnt lgkmcnt(10)
	v_mfma_f32_16x16x32_bf16 v[24:27], v[88:91], v[34:37], v[24:27]
	s_waitcnt lgkmcnt(9)
	v_mfma_f32_16x16x32_bf16 v[20:23], v[92:95], v[34:37], v[20:23]
	s_waitcnt lgkmcnt(8)
	v_mfma_f32_16x16x32_bf16 v[16:19], v[102:105], v[34:37], v[16:19]
	s_waitcnt lgkmcnt(3)
	v_mfma_f32_16x16x32_bf16 v[12:15], v[106:109], v[34:37], v[12:15]
	s_waitcnt lgkmcnt(2)
	v_mfma_f32_16x16x32_bf16 v[8:11], v[110:113], v[34:37], v[8:11]
	s_waitcnt lgkmcnt(1)
	v_mfma_f32_16x16x32_bf16 v[4:7], v[114:117], v[34:37], v[4:7]
	s_waitcnt lgkmcnt(0)
	v_mfma_f32_16x16x32_bf16 v[0:3], v[118:121], v[34:37], v[0:3]
	s_setprio 0
.LBB0_1300:
	s_andn2_b64 vcc, exec, s[20:21]
	v_cvt_pk_bf16_f32 v34, v74, v75
	v_cvt_pk_bf16_f32 v35, v76, v77
	v_cvt_pk_bf16_f32 v36, v79, v81
	v_cvt_pk_bf16_f32 v37, v78, v80
	s_cbranch_vccnz .LBB0_1302
	ds_read_b64_tr_b16 v[74:75], v41 offset:27648
	ds_read_b64_tr_b16 v[78:79], v41 offset:27680
	ds_read_b64_tr_b16 v[84:85], v41 offset:27712
	ds_read_b64_tr_b16 v[88:89], v41 offset:27744
	ds_read_b64_tr_b16 v[76:77], v41 offset:32256
	ds_read_b64_tr_b16 v[80:81], v41 offset:32288
	ds_read_b64_tr_b16 v[86:87], v41 offset:32320
	ds_read_b64_tr_b16 v[90:91], v41 offset:32352
	ds_read_b64_tr_b16 v[92:93], v41 offset:27776
	ds_read_b64_tr_b16 v[102:103], v41 offset:27808
	ds_read_b64_tr_b16 v[106:107], v41 offset:27840
	ds_read_b64_tr_b16 v[110:111], v41 offset:27872
	ds_read_b64_tr_b16 v[94:95], v41 offset:32384
	ds_read_b64_tr_b16 v[104:105], v41 offset:32416
	ds_read_b64_tr_b16 v[108:109], v41 offset:32448
	ds_read_b64_tr_b16 v[112:113], v41 offset:32480
	s_waitcnt lgkmcnt(11)
	s_setprio 1
	v_mfma_f32_16x16x32_bf16 v[28:31], v[74:77], v[34:37], v[28:31]
	s_waitcnt lgkmcnt(10)
	v_mfma_f32_16x16x32_bf16 v[24:27], v[78:81], v[34:37], v[24:27]
	s_waitcnt lgkmcnt(9)
	v_mfma_f32_16x16x32_bf16 v[20:23], v[84:87], v[34:37], v[20:23]
	s_waitcnt lgkmcnt(8)
	v_mfma_f32_16x16x32_bf16 v[16:19], v[88:91], v[34:37], v[16:19]
	s_waitcnt lgkmcnt(3)
	v_mfma_f32_16x16x32_bf16 v[12:15], v[92:95], v[34:37], v[12:15]
	s_waitcnt lgkmcnt(2)
	v_mfma_f32_16x16x32_bf16 v[8:11], v[102:105], v[34:37], v[8:11]
	s_waitcnt lgkmcnt(1)
	v_mfma_f32_16x16x32_bf16 v[4:7], v[106:109], v[34:37], v[4:7]
	s_waitcnt lgkmcnt(0)
	v_mfma_f32_16x16x32_bf16 v[0:3], v[110:113], v[34:37], v[0:3]
	s_setprio 0
.LBB0_1302:
	s_andn2_b64 vcc, exec, s[18:19]
	v_cvt_pk_bf16_f32 v34, v66, v67
	v_cvt_pk_bf16_f32 v35, v68, v69
	v_cvt_pk_bf16_f32 v36, v71, v73
	v_cvt_pk_bf16_f32 v37, v70, v72
	s_cbranch_vccnz .LBB0_1304
	ds_read_b64_tr_b16 v[66:67], v41 offset:36864
	ds_read_b64_tr_b16 v[70:71], v41 offset:36896
	ds_read_b64_tr_b16 v[74:75], v41 offset:36928
	ds_read_b64_tr_b16 v[78:79], v41 offset:36960
	ds_read_b64_tr_b16 v[68:69], v41 offset:41472
	ds_read_b64_tr_b16 v[72:73], v41 offset:41504
	ds_read_b64_tr_b16 v[76:77], v41 offset:41536
	ds_read_b64_tr_b16 v[80:81], v41 offset:41568
	ds_read_b64_tr_b16 v[84:85], v41 offset:36992
	ds_read_b64_tr_b16 v[88:89], v41 offset:37024
	ds_read_b64_tr_b16 v[92:93], v41 offset:37056
	ds_read_b64_tr_b16 v[102:103], v41 offset:37088
	ds_read_b64_tr_b16 v[86:87], v41 offset:41600
	ds_read_b64_tr_b16 v[90:91], v41 offset:41632
	ds_read_b64_tr_b16 v[94:95], v41 offset:41664
	ds_read_b64_tr_b16 v[104:105], v41 offset:41696
	s_waitcnt lgkmcnt(11)
	s_setprio 1
	v_mfma_f32_16x16x32_bf16 v[28:31], v[66:69], v[34:37], v[28:31]
	s_waitcnt lgkmcnt(10)
	v_mfma_f32_16x16x32_bf16 v[24:27], v[70:73], v[34:37], v[24:27]
	s_waitcnt lgkmcnt(9)
	v_mfma_f32_16x16x32_bf16 v[20:23], v[74:77], v[34:37], v[20:23]
	s_waitcnt lgkmcnt(8)
	v_mfma_f32_16x16x32_bf16 v[16:19], v[78:81], v[34:37], v[16:19]
	s_waitcnt lgkmcnt(3)
	v_mfma_f32_16x16x32_bf16 v[12:15], v[84:87], v[34:37], v[12:15]
	s_waitcnt lgkmcnt(2)
	v_mfma_f32_16x16x32_bf16 v[8:11], v[88:91], v[34:37], v[8:11]
	s_waitcnt lgkmcnt(1)
	v_mfma_f32_16x16x32_bf16 v[4:7], v[92:95], v[34:37], v[4:7]
	s_waitcnt lgkmcnt(0)
	v_mfma_f32_16x16x32_bf16 v[0:3], v[102:105], v[34:37], v[0:3]
	s_setprio 0
.LBB0_1304:
	s_andn2_b64 vcc, exec, s[16:17]
	v_cvt_pk_bf16_f32 v34, v58, v59
	v_cvt_pk_bf16_f32 v35, v60, v61
	v_cvt_pk_bf16_f32 v36, v63, v65
	v_cvt_pk_bf16_f32 v37, v62, v64
	s_cbranch_vccnz .LBB0_1306
	ds_read_b64_tr_b16 v[58:59], v41 offset:46080
	ds_read_b64_tr_b16 v[62:63], v41 offset:46112
	ds_read_b64_tr_b16 v[66:67], v41 offset:46144
	ds_read_b64_tr_b16 v[70:71], v41 offset:46176
	ds_read_b64_tr_b16 v[60:61], v41 offset:50688
	ds_read_b64_tr_b16 v[64:65], v41 offset:50720
	ds_read_b64_tr_b16 v[68:69], v41 offset:50752
	ds_read_b64_tr_b16 v[72:73], v41 offset:50784
	ds_read_b64_tr_b16 v[74:75], v41 offset:46208
	ds_read_b64_tr_b16 v[78:79], v41 offset:46240
	ds_read_b64_tr_b16 v[84:85], v41 offset:46272
	ds_read_b64_tr_b16 v[88:89], v41 offset:46304
	ds_read_b64_tr_b16 v[76:77], v41 offset:50816
	ds_read_b64_tr_b16 v[80:81], v41 offset:50848
	ds_read_b64_tr_b16 v[86:87], v41 offset:50880
	ds_read_b64_tr_b16 v[90:91], v41 offset:50912
	s_waitcnt lgkmcnt(11)
	s_setprio 1
	v_mfma_f32_16x16x32_bf16 v[28:31], v[58:61], v[34:37], v[28:31]
	s_waitcnt lgkmcnt(10)
	v_mfma_f32_16x16x32_bf16 v[24:27], v[62:65], v[34:37], v[24:27]
	s_waitcnt lgkmcnt(9)
	v_mfma_f32_16x16x32_bf16 v[20:23], v[66:69], v[34:37], v[20:23]
	s_waitcnt lgkmcnt(8)
	v_mfma_f32_16x16x32_bf16 v[16:19], v[70:73], v[34:37], v[16:19]
	s_waitcnt lgkmcnt(3)
	v_mfma_f32_16x16x32_bf16 v[12:15], v[74:77], v[34:37], v[12:15]
	s_waitcnt lgkmcnt(2)
	v_mfma_f32_16x16x32_bf16 v[8:11], v[78:81], v[34:37], v[8:11]
	s_waitcnt lgkmcnt(1)
	v_mfma_f32_16x16x32_bf16 v[4:7], v[84:87], v[34:37], v[4:7]
	s_waitcnt lgkmcnt(0)
	v_mfma_f32_16x16x32_bf16 v[0:3], v[88:91], v[34:37], v[0:3]
	s_setprio 0
.LBB0_1306:
	s_andn2_b64 vcc, exec, s[14:15]
	v_cvt_pk_bf16_f32 v34, v50, v51
	v_cvt_pk_bf16_f32 v35, v52, v53
	v_cvt_pk_bf16_f32 v36, v55, v57
	v_cvt_pk_bf16_f32 v37, v54, v56
	s_cbranch_vccnz .LBB0_1308
	ds_read_b64_tr_b16 v[50:51], v41 offset:55296
	ds_read_b64_tr_b16 v[54:55], v41 offset:55328
	ds_read_b64_tr_b16 v[58:59], v41 offset:55360
	ds_read_b64_tr_b16 v[62:63], v41 offset:55392
	ds_read_b64_tr_b16 v[52:53], v41 offset:59904
	ds_read_b64_tr_b16 v[56:57], v41 offset:59936
	ds_read_b64_tr_b16 v[60:61], v41 offset:59968
	ds_read_b64_tr_b16 v[64:65], v41 offset:60000
	ds_read_b64_tr_b16 v[66:67], v41 offset:55424
	ds_read_b64_tr_b16 v[70:71], v41 offset:55456
	ds_read_b64_tr_b16 v[74:75], v41 offset:55488
	ds_read_b64_tr_b16 v[78:79], v41 offset:55520
	ds_read_b64_tr_b16 v[68:69], v41 offset:60032
	ds_read_b64_tr_b16 v[72:73], v41 offset:60064
	ds_read_b64_tr_b16 v[76:77], v41 offset:60096
	ds_read_b64_tr_b16 v[80:81], v41 offset:60128
	s_waitcnt lgkmcnt(11)
	s_setprio 1
	v_mfma_f32_16x16x32_bf16 v[28:31], v[50:53], v[34:37], v[28:31]
	s_waitcnt lgkmcnt(10)
	v_mfma_f32_16x16x32_bf16 v[24:27], v[54:57], v[34:37], v[24:27]
	s_waitcnt lgkmcnt(9)
	v_mfma_f32_16x16x32_bf16 v[20:23], v[58:61], v[34:37], v[20:23]
	s_waitcnt lgkmcnt(8)
	v_mfma_f32_16x16x32_bf16 v[16:19], v[62:65], v[34:37], v[16:19]
	s_waitcnt lgkmcnt(3)
	v_mfma_f32_16x16x32_bf16 v[12:15], v[66:69], v[34:37], v[12:15]
	s_waitcnt lgkmcnt(2)
	v_mfma_f32_16x16x32_bf16 v[8:11], v[70:73], v[34:37], v[8:11]
	s_waitcnt lgkmcnt(1)
	v_mfma_f32_16x16x32_bf16 v[4:7], v[74:77], v[34:37], v[4:7]
	s_waitcnt lgkmcnt(0)
	v_mfma_f32_16x16x32_bf16 v[0:3], v[78:81], v[34:37], v[0:3]
	s_setprio 0
.LBB0_1308:
	s_andn2_b64 vcc, exec, s[12:13]
	v_cvt_pk_bf16_f32 v34, v42, v43
	v_cvt_pk_bf16_f32 v35, v44, v45
	v_cvt_pk_bf16_f32 v36, v47, v49
	v_cvt_pk_bf16_f32 v37, v46, v48
	s_cbranch_vccnz .LBB0_1310
	v_add_u32_e32 v32, 0x10e00, v41
	v_add_u32_e32 v48, 0x10e20, v41
	v_add_u32_e32 v52, 0x10e40, v41
	v_add_u32_e32 v56, 0x10e60, v41
	ds_read_b64_tr_b16 v[42:43], v41 offset:64512
	ds_read_b64_tr_b16 v[46:47], v41 offset:64544
	ds_read_b64_tr_b16 v[50:51], v41 offset:64576
	ds_read_b64_tr_b16 v[54:55], v41 offset:64608
	ds_read_b64_tr_b16 v[44:45], v32
	ds_read_b64_tr_b16 v[48:49], v48
	ds_read_b64_tr_b16 v[52:53], v52
	ds_read_b64_tr_b16 v[56:57], v56
	v_add_u32_e32 v32, 0x10e80, v41
	v_add_u32_e32 v64, 0x10ea0, v41
	v_add_u32_e32 v68, 0x10ec0, v41
	ds_read_b64_tr_b16 v[58:59], v41 offset:64640
	ds_read_b64_tr_b16 v[62:63], v41 offset:64672
	ds_read_b64_tr_b16 v[66:67], v41 offset:64704
	ds_read_b64_tr_b16 v[70:71], v41 offset:64736
	v_add_u32_e32 v41, 0x10ee0, v41
	ds_read_b64_tr_b16 v[60:61], v32
	ds_read_b64_tr_b16 v[64:65], v64
	ds_read_b64_tr_b16 v[68:69], v68
	ds_read_b64_tr_b16 v[72:73], v41
	s_waitcnt lgkmcnt(11)
	s_setprio 1
	v_mfma_f32_16x16x32_bf16 v[28:31], v[42:45], v[34:37], v[28:31]
	s_waitcnt lgkmcnt(10)
	v_mfma_f32_16x16x32_bf16 v[24:27], v[46:49], v[34:37], v[24:27]
	s_waitcnt lgkmcnt(9)
	v_mfma_f32_16x16x32_bf16 v[20:23], v[50:53], v[34:37], v[20:23]
	s_waitcnt lgkmcnt(8)
	v_mfma_f32_16x16x32_bf16 v[16:19], v[54:57], v[34:37], v[16:19]
	s_waitcnt lgkmcnt(3)
	v_mfma_f32_16x16x32_bf16 v[12:15], v[58:61], v[34:37], v[12:15]
	s_waitcnt lgkmcnt(2)
	v_mfma_f32_16x16x32_bf16 v[8:11], v[62:65], v[34:37], v[8:11]
	s_waitcnt lgkmcnt(1)
	v_mfma_f32_16x16x32_bf16 v[4:7], v[66:69], v[34:37], v[4:7]
	s_waitcnt lgkmcnt(0)
	v_mfma_f32_16x16x32_bf16 v[0:3], v[70:73], v[34:37], v[0:3]
	s_setprio 0

.LBB0_1331:
	v_lshl_or_b32 v82, s73, 4, v32
	v_readlane_b32 s8, v252, 61
	s_nop 0
	v_max_i32_e32 v16, 0x80, v82
	v_readlane_b32 s9, v252, 62
	v_lshrrev_b32_e32 v18, 2, v98
	v_add_u32_e32 v17, 0x80, v82
	v_cndmask_b32_e64 v16, v82, v16, s[8:9]
	v_and_b32_e32 v83, 12, v18
	v_sub_u32_e32 v17, v17, v16
	v_sub_u32_e32 v16, v16, v83
	v_sub_u32_e32 v18, 0, v16
	v_sub_u32_e32 v222, 1, v16
	v_sub_u32_e32 v250, 2, v16
	v_cmp_gt_u32_e32 vcc, v18, v17
	v_cmp_gt_u32_e64 s[8:9], v222, v17
	v_cmp_gt_u32_e64 s[10:11], v250, v17
	v_cndmask_b32_e32 v12, v12, v225, vcc
	v_cndmask_b32_e64 v13, v13, v225, s[8:9]
	v_cndmask_b32_e64 v14, v14, v225, s[10:11]
	v_sub_u32_e32 v18, 3, v16
	v_sub_u32_e32 v222, 16, v16
	v_sub_u32_e32 v250, 17, v16
	v_cmp_gt_u32_e32 vcc, v18, v17
	v_cmp_gt_u32_e64 s[8:9], v222, v17
	v_cmp_gt_u32_e64 s[10:11], v250, v17
	v_cndmask_b32_e32 v15, v15, v225, vcc
	v_cndmask_b32_e64 v8, v8, v225, s[8:9]
	v_cndmask_b32_e64 v9, v9, v225, s[10:11]
	v_sub_u32_e32 v18, 18, v16
	v_sub_u32_e32 v222, 19, v16
	v_sub_u32_e32 v250, 32, v16
	v_cmp_gt_u32_e32 vcc, v18, v17
	v_cmp_gt_u32_e64 s[8:9], v222, v17
	v_cmp_gt_u32_e64 s[10:11], v250, v17
	v_cndmask_b32_e32 v10, v10, v225, vcc
	v_cndmask_b32_e64 v11, v11, v225, s[8:9]
	v_cndmask_b32_e64 v19, v42, v225, s[10:11]
	v_sub_u32_e32 v18, 33, v16
	v_sub_u32_e32 v222, 34, v16
	v_sub_u32_e32 v250, 35, v16
	v_cmp_gt_u32_e32 vcc, v18, v17
	v_cmp_gt_u32_e64 s[8:9], v222, v17
	v_cmp_gt_u32_e64 s[10:11], v250, v17
	v_cndmask_b32_e32 v20, v43, v225, vcc
	v_cndmask_b32_e64 v21, v44, v225, s[8:9]
	v_cndmask_b32_e64 v22, v45, v225, s[10:11]
	v_sub_u32_e32 v18, 48, v16
	v_sub_u32_e32 v222, 49, v16
	v_sub_u32_e32 v250, 50, v16
	v_cmp_gt_u32_e32 vcc, v18, v17
	v_cmp_gt_u32_e64 s[8:9], v222, v17
	v_cmp_gt_u32_e64 s[10:11], v250, v17
	v_cndmask_b32_e32 v0, v0, v225, vcc
	v_cndmask_b32_e64 v1, v1, v225, s[8:9]
	v_cndmask_b32_e64 v2, v2, v225, s[10:11]
	v_sub_u32_e32 v18, 51, v16
	v_sub_u32_e32 v222, 64, v16
	v_sub_u32_e32 v250, 0x41, v16
	v_cmp_gt_u32_e32 vcc, v18, v17
	v_cmp_gt_u32_e64 s[8:9], v222, v17
	v_cmp_gt_u32_e64 s[10:11], v250, v17
	v_cndmask_b32_e32 v3, v3, v225, vcc
	v_cndmask_b32_e64 v23, v46, v225, s[8:9]
	v_cndmask_b32_e64 v24, v47, v225, s[10:11]
	v_sub_u32_e32 v18, 0x42, v16
	v_sub_u32_e32 v222, 0x43, v16
	v_sub_u32_e32 v250, 0x50, v16
	v_cmp_gt_u32_e32 vcc, v18, v17
	v_cmp_gt_u32_e64 s[8:9], v222, v17
	v_cmp_gt_u32_e64 s[10:11], v250, v17
	v_cndmask_b32_e32 v25, v48, v225, vcc
	v_cndmask_b32_e64 v26, v49, v225, s[8:9]
	v_cndmask_b32_e64 v27, v38, v225, s[10:11]
	v_sub_u32_e32 v18, 0x51, v16
	v_sub_u32_e32 v222, 0x52, v16
	v_sub_u32_e32 v250, 0x53, v16
	v_cmp_gt_u32_e32 vcc, v18, v17
	v_cmp_gt_u32_e64 s[8:9], v222, v17
	v_cmp_gt_u32_e64 s[10:11], v250, v17
	v_cndmask_b32_e32 v28, v39, v225, vcc
	v_cndmask_b32_e64 v29, v40, v225, s[8:9]
	v_cndmask_b32_e64 v30, v41, v225, s[10:11]
	v_sub_u32_e32 v18, 0x60, v16
	v_sub_u32_e32 v222, 0x61, v16
	v_sub_u32_e32 v250, 0x62, v16
	v_cmp_gt_u32_e32 vcc, v18, v17
	v_cmp_gt_u32_e64 s[8:9], v222, v17
	v_cmp_gt_u32_e64 s[10:11], v250, v17
	v_cndmask_b32_e32 v31, v58, v225, vcc
	v_cndmask_b32_e64 v39, v59, v225, s[8:9]
	v_cndmask_b32_e64 v40, v60, v225, s[10:11]
	v_sub_u32_e32 v18, 0x63, v16
	v_sub_u32_e32 v222, 0x70, v16
	v_sub_u32_e32 v250, 0x71, v16
	v_cmp_gt_u32_e32 vcc, v18, v17
	v_cmp_gt_u32_e64 s[8:9], v222, v17
	v_cmp_gt_u32_e64 s[10:11], v250, v17
	v_cndmask_b32_e32 v41, v61, v225, vcc
	v_cndmask_b32_e64 v4, v4, v225, s[8:9]
	v_cndmask_b32_e64 v5, v5, v225, s[10:11]
	v_sub_u32_e32 v18, 0x72, v16
	v_sub_u32_e32 v222, 0x73, v16
	v_sub_u32_e32 v250, 0x80, v16
	v_cmp_gt_u32_e32 vcc, v18, v17
	v_cmp_gt_u32_e64 s[8:9], v222, v17
	v_cmp_gt_u32_e64 s[10:11], v250, v17
	v_cndmask_b32_e32 v6, v6, v225, vcc
	v_cndmask_b32_e64 v7, v7, v225, s[8:9]
	v_cndmask_b32_e64 v42, v62, v225, s[10:11]
	v_sub_u32_e32 v18, 0x81, v16
	v_sub_u32_e32 v222, 0x82, v16
	v_sub_u32_e32 v250, 0x83, v16
	v_cmp_gt_u32_e32 vcc, v18, v17
	v_cmp_gt_u32_e64 s[8:9], v222, v17
	v_cmp_gt_u32_e64 s[10:11], v250, v17
	v_cndmask_b32_e32 v43, v63, v225, vcc
	v_cndmask_b32_e64 v44, v64, v225, s[8:9]
	v_cndmask_b32_e64 v45, v65, v225, s[10:11]
	v_sub_u32_e32 v18, 0x90, v16
	v_sub_u32_e32 v222, 0x91, v16
	v_sub_u32_e32 v250, 0x92, v16
	v_cmp_gt_u32_e32 vcc, v18, v17
	v_cmp_gt_u32_e64 s[8:9], v222, v17
	v_cmp_gt_u32_e64 s[10:11], v250, v17
	v_cndmask_b32_e32 v46, v54, v225, vcc
	v_cndmask_b32_e64 v47, v55, v225, s[8:9]
	v_cndmask_b32_e64 v48, v56, v225, s[10:11]
	v_sub_u32_e32 v18, 0x93, v16
	v_sub_u32_e32 v222, 0xa0, v16
	v_sub_u32_e32 v250, 0xa1, v16
	v_cmp_gt_u32_e32 vcc, v18, v17
	v_cmp_gt_u32_e64 s[8:9], v222, v17
	v_cmp_gt_u32_e64 s[10:11], v250, v17
	v_cndmask_b32_e32 v49, v57, v225, vcc
	v_cndmask_b32_e64 v54, v70, v225, s[8:9]
	v_cndmask_b32_e64 v55, v71, v225, s[10:11]
	v_sub_u32_e32 v18, 0xa2, v16
	v_sub_u32_e32 v222, 0xa3, v16
	v_sub_u32_e32 v250, 0xb0, v16
	v_cmp_gt_u32_e32 vcc, v18, v17
	v_cmp_gt_u32_e64 s[8:9], v222, v17
	v_cmp_gt_u32_e64 s[10:11], v250, v17
	v_cndmask_b32_e32 v56, v72, v225, vcc
	v_cndmask_b32_e64 v57, v73, v225, s[8:9]
	v_cndmask_b32_e64 v34, v34, v225, s[10:11]
	v_sub_u32_e32 v18, 0xb1, v16
	v_sub_u32_e32 v222, 0xb2, v16
	v_sub_u32_e32 v250, 0xb3, v16
	v_cmp_gt_u32_e32 vcc, v18, v17
	v_cmp_gt_u32_e64 s[8:9], v222, v17
	v_cmp_gt_u32_e64 s[10:11], v250, v17
	v_cndmask_b32_e32 v35, v35, v225, vcc
	v_cndmask_b32_e64 v62, v36, v225, s[8:9]
	v_cndmask_b32_e64 v64, v37, v225, s[10:11]
	v_sub_u32_e32 v18, 0xc0, v16
	v_sub_u32_e32 v222, 0xc1, v16
	v_sub_u32_e32 v250, 0xc2, v16
	v_cmp_gt_u32_e32 vcc, v18, v17
	v_cmp_gt_u32_e64 s[8:9], v222, v17
	v_cmp_gt_u32_e64 s[10:11], v250, v17
	v_cndmask_b32_e32 v102, v74, v225, vcc
	v_cndmask_b32_e64 v103, v75, v225, s[8:9]
	v_cndmask_b32_e64 v104, v76, v225, s[10:11]
	v_sub_u32_e32 v18, 0xc3, v16
	v_sub_u32_e32 v222, 0xd0, v16
	v_sub_u32_e32 v250, 0xd1, v16
	v_cmp_gt_u32_e32 vcc, v18, v17
	v_cmp_gt_u32_e64 s[8:9], v222, v17
	v_cmp_gt_u32_e64 s[10:11], v250, v17
	v_cndmask_b32_e32 v105, v77, v225, vcc
	v_cndmask_b32_e64 v106, v66, v225, s[8:9]
	v_cndmask_b32_e64 v107, v67, v225, s[10:11]
	v_sub_u32_e32 v18, 0xd2, v16
	v_sub_u32_e32 v222, 0xd3, v16
	v_sub_u32_e32 v250, 0xe0, v16
	v_cmp_gt_u32_e32 vcc, v18, v17
	v_cmp_gt_u32_e64 s[8:9], v222, v17
	v_cmp_gt_u32_e64 s[10:11], v250, v17
	v_cndmask_b32_e32 v108, v68, v225, vcc
	v_cndmask_b32_e64 v109, v69, v225, s[8:9]
	v_cndmask_b32_e64 v110, v78, v225, s[10:11]
	v_sub_u32_e32 v18, 0xe1, v16
	v_sub_u32_e32 v222, 0xe2, v16
	v_sub_u32_e32 v250, 0xe3, v16
	v_cmp_gt_u32_e32 vcc, v18, v17
	v_cmp_gt_u32_e64 s[8:9], v222, v17
	v_cmp_gt_u32_e64 s[10:11], v250, v17
	v_cndmask_b32_e32 v111, v79, v225, vcc
	v_cndmask_b32_e64 v112, v80, v225, s[8:9]
	v_cndmask_b32_e64 v113, v81, v225, s[10:11]
	v_sub_u32_e32 v18, 0xf0, v16
	v_sub_u32_e32 v222, 0xf1, v16
	v_sub_u32_e32 v250, 0xf2, v16
	v_cmp_gt_u32_e32 vcc, v18, v17
	v_cmp_gt_u32_e64 s[8:9], v222, v17
	v_cmp_gt_u32_e64 s[10:11], v250, v17
	v_cndmask_b32_e32 v114, v50, v225, vcc
	v_cndmask_b32_e64 v115, v51, v225, s[8:9]
	v_cndmask_b32_e64 v116, v52, v225, s[10:11]
	v_sub_u32_e32 v18, 0xf3, v16
	v_cmp_gt_u32_e32 vcc, v18, v17
	s_nop 1
	v_cndmask_b32_e32 v16, v53, v225, vcc
	v_max_f32_e32 v17, v12, v13
	v_max_f32_e32 v18, v14, v15
	s_mov_b32 s8, 0xff61b1e6
	v_max3_f32 v17, v17, v18, s8
	v_max_f32_e32 v18, v8, v9
	v_max_f32_e32 v36, v10, v11
	v_max3_f32 v17, v18, v36, v17
	v_max_f32_e32 v18, v19, v20
	v_max_f32_e32 v36, v21, v22
	v_max3_f32 v17, v18, v36, v17
	v_max_f32_e32 v18, v0, v1
	v_max_f32_e32 v36, v2, v3
	v_max3_f32 v17, v18, v36, v17
	v_max_f32_e32 v18, v23, v24
	v_max_f32_e32 v36, v25, v26
	v_max3_f32 v17, v18, v36, v17
	v_max_f32_e32 v18, v27, v28
	v_max_f32_e32 v36, v29, v30
	v_max3_f32 v17, v18, v36, v17
	v_max_f32_e32 v18, v31, v39
	v_max_f32_e32 v36, v40, v41
	v_max3_f32 v17, v18, v36, v17
	v_max_f32_e32 v18, v4, v5
	v_max_f32_e32 v36, v6, v7
	v_max3_f32 v17, v18, v36, v17
	v_max_f32_e32 v18, v42, v43
	v_max_f32_e32 v36, v44, v45
	v_max3_f32 v17, v18, v36, v17
	v_max_f32_e32 v18, v46, v47
	v_max_f32_e32 v36, v48, v49
	v_max3_f32 v17, v18, v36, v17
	v_max_f32_e32 v18, v54, v55
	v_max_f32_e32 v36, v56, v57
	v_max3_f32 v17, v18, v36, v17
	v_max_f32_e32 v18, v34, v35
	v_max_f32_e32 v36, v62, v64
	v_max3_f32 v17, v18, v36, v17
	v_max_f32_e32 v18, v102, v103
	v_max_f32_e32 v36, v104, v105
	v_max3_f32 v17, v18, v36, v17
	v_max_f32_e32 v18, v106, v107
	v_max_f32_e32 v36, v108, v109
	v_max3_f32 v17, v18, v36, v17
	v_max_f32_e32 v18, v110, v111
	v_max_f32_e32 v36, v112, v113
	v_max3_f32 v17, v18, v36, v17
	v_max_f32_e32 v18, v114, v115
	v_max_f32_e32 v36, v116, v16
	v_max3_f32 v17, v18, v36, v17
	ds_bpermute_b32 v18, v100, v17
	s_andn2_b64 vcc, exec, s[44:45]
	s_waitcnt lgkmcnt(0)
	v_max_f32_e32 v17, v17, v18
	ds_bpermute_b32 v18, v101, v17
	s_waitcnt lgkmcnt(0)
	v_max_f32_e32 v38, v17, v18
	v_sub_f32_e32 v12, v12, v38
	v_exp_f32_e32 v12, v12
	v_sub_f32_e32 v13, v13, v38
	v_exp_f32_e32 v13, v13
	v_sub_f32_e32 v14, v14, v38
	v_exp_f32_e32 v14, v14
	v_sub_f32_e32 v15, v15, v38
	v_exp_f32_e32 v15, v15
	v_sub_f32_e32 v8, v8, v38
	v_add_f32_e32 v17, 0, v12
	v_exp_f32_e32 v8, v8
	v_sub_f32_e32 v9, v9, v38
	v_add_f32_e32 v17, v13, v17
	v_exp_f32_e32 v9, v9
	v_sub_f32_e32 v10, v10, v38
	v_add_f32_e32 v17, v14, v17
	v_exp_f32_e32 v10, v10
	v_sub_f32_e32 v11, v11, v38
	v_add_f32_e32 v17, v15, v17
	v_exp_f32_e32 v11, v11
	v_sub_f32_e32 v18, v19, v38
	v_add_f32_e32 v17, v8, v17
	v_exp_f32_e32 v36, v18
	v_sub_f32_e32 v18, v20, v38
	v_add_f32_e32 v17, v9, v17
	v_exp_f32_e32 v37, v18
	v_sub_f32_e32 v18, v21, v38
	v_add_f32_e32 v17, v10, v17
	v_exp_f32_e32 v92, v18
	v_sub_f32_e32 v18, v22, v38
	v_add_f32_e32 v17, v11, v17
	v_exp_f32_e32 v93, v18
	v_sub_f32_e32 v0, v0, v38
	v_add_f32_e32 v17, v36, v17
	v_exp_f32_e32 v95, v0
	v_sub_f32_e32 v0, v1, v38
	v_add_f32_e32 v17, v37, v17
	v_exp_f32_e32 v97, v0
	v_sub_f32_e32 v0, v2, v38
	v_add_f32_e32 v17, v92, v17
	v_exp_f32_e32 v94, v0
	v_sub_f32_e32 v0, v3, v38
	v_add_f32_e32 v17, v93, v17
	v_exp_f32_e32 v96, v0
	v_sub_f32_e32 v1, v23, v38
	v_add_f32_e32 v0, v95, v17
	v_exp_f32_e32 v84, v1
	v_sub_f32_e32 v1, v24, v38
	v_add_f32_e32 v0, v97, v0
	v_exp_f32_e32 v85, v1
	v_sub_f32_e32 v1, v25, v38
	v_add_f32_e32 v0, v94, v0
	v_exp_f32_e32 v86, v1
	v_sub_f32_e32 v1, v26, v38
	v_add_f32_e32 v0, v96, v0
	v_exp_f32_e32 v87, v1
	v_sub_f32_e32 v1, v27, v38
	v_add_f32_e32 v0, v84, v0
	v_exp_f32_e32 v89, v1
	v_sub_f32_e32 v1, v28, v38
	v_add_f32_e32 v0, v85, v0
	v_exp_f32_e32 v91, v1
	v_sub_f32_e32 v1, v29, v38
	v_add_f32_e32 v0, v86, v0
	v_exp_f32_e32 v88, v1
	v_sub_f32_e32 v1, v30, v38
	v_add_f32_e32 v0, v87, v0
	v_exp_f32_e32 v90, v1
	v_sub_f32_e32 v1, v31, v38
	v_add_f32_e32 v0, v89, v0
	v_exp_f32_e32 v74, v1
	v_sub_f32_e32 v1, v39, v38
	v_add_f32_e32 v0, v91, v0
	v_exp_f32_e32 v75, v1
	v_sub_f32_e32 v1, v40, v38
	v_add_f32_e32 v0, v88, v0
	v_exp_f32_e32 v76, v1
	v_sub_f32_e32 v1, v41, v38
	v_add_f32_e32 v0, v90, v0
	v_exp_f32_e32 v77, v1
	v_sub_f32_e32 v1, v4, v38
	v_add_f32_e32 v0, v74, v0
	v_exp_f32_e32 v79, v1
	v_sub_f32_e32 v1, v5, v38
	v_add_f32_e32 v0, v75, v0
	v_exp_f32_e32 v81, v1
	v_sub_f32_e32 v1, v6, v38
	v_add_f32_e32 v0, v76, v0
	v_exp_f32_e32 v78, v1
	v_sub_f32_e32 v1, v7, v38
	v_add_f32_e32 v0, v77, v0
	v_exp_f32_e32 v80, v1
	v_sub_f32_e32 v1, v42, v38
	v_add_f32_e32 v0, v79, v0
	v_exp_f32_e32 v66, v1
	v_sub_f32_e32 v1, v43, v38
	v_add_f32_e32 v0, v81, v0
	v_exp_f32_e32 v67, v1
	v_sub_f32_e32 v1, v44, v38
	v_add_f32_e32 v0, v78, v0
	v_exp_f32_e32 v68, v1
	v_sub_f32_e32 v1, v45, v38
	v_add_f32_e32 v0, v80, v0
	v_exp_f32_e32 v69, v1
	v_sub_f32_e32 v1, v46, v38
	v_add_f32_e32 v0, v66, v0
	v_exp_f32_e32 v71, v1
	v_sub_f32_e32 v1, v47, v38
	v_add_f32_e32 v0, v67, v0
	v_exp_f32_e32 v73, v1
	v_sub_f32_e32 v1, v48, v38
	v_add_f32_e32 v0, v68, v0
	v_exp_f32_e32 v70, v1
	v_sub_f32_e32 v1, v49, v38
	v_add_f32_e32 v0, v69, v0
	v_exp_f32_e32 v72, v1
	v_sub_f32_e32 v1, v54, v38
	v_add_f32_e32 v0, v71, v0
	v_exp_f32_e32 v58, v1
	v_sub_f32_e32 v1, v55, v38
	v_add_f32_e32 v0, v73, v0
	v_exp_f32_e32 v59, v1
	v_sub_f32_e32 v1, v56, v38
	v_add_f32_e32 v0, v70, v0
	v_exp_f32_e32 v60, v1
	v_sub_f32_e32 v1, v57, v38
	v_add_f32_e32 v0, v72, v0
	v_exp_f32_e32 v61, v1
	v_sub_f32_e32 v1, v34, v38
	v_add_f32_e32 v0, v58, v0
	v_exp_f32_e32 v63, v1
	v_sub_f32_e32 v1, v35, v38
	v_add_f32_e32 v0, v59, v0
	v_exp_f32_e32 v65, v1
	v_sub_f32_e32 v1, v62, v38
	v_add_f32_e32 v0, v60, v0
	v_exp_f32_e32 v62, v1
	v_sub_f32_e32 v1, v64, v38
	v_add_f32_e32 v0, v61, v0
	v_exp_f32_e32 v64, v1
	v_sub_f32_e32 v1, v102, v38
	v_add_f32_e32 v0, v63, v0
	v_exp_f32_e32 v50, v1
	v_sub_f32_e32 v1, v103, v38
	v_add_f32_e32 v0, v65, v0
	v_exp_f32_e32 v51, v1
	v_sub_f32_e32 v1, v104, v38
	v_add_f32_e32 v0, v62, v0
	v_exp_f32_e32 v52, v1
	v_sub_f32_e32 v1, v105, v38
	v_add_f32_e32 v0, v64, v0
	v_exp_f32_e32 v53, v1
	v_sub_f32_e32 v1, v106, v38
	v_add_f32_e32 v0, v50, v0
	v_exp_f32_e32 v55, v1
	v_sub_f32_e32 v1, v107, v38
	v_add_f32_e32 v0, v51, v0
	v_exp_f32_e32 v57, v1
	v_sub_f32_e32 v1, v108, v38
	v_add_f32_e32 v0, v52, v0
	v_exp_f32_e32 v54, v1
	v_sub_f32_e32 v1, v109, v38
	v_add_f32_e32 v0, v53, v0
	v_exp_f32_e32 v56, v1
	v_sub_f32_e32 v1, v110, v38
	v_add_f32_e32 v0, v55, v0
	v_exp_f32_e32 v42, v1
	v_sub_f32_e32 v1, v111, v38
	v_add_f32_e32 v0, v57, v0
	v_exp_f32_e32 v43, v1
	v_sub_f32_e32 v1, v112, v38
	v_add_f32_e32 v0, v54, v0
	v_exp_f32_e32 v44, v1
	v_sub_f32_e32 v1, v113, v38
	v_add_f32_e32 v0, v56, v0
	v_exp_f32_e32 v45, v1
	v_sub_f32_e32 v1, v114, v38
	v_add_f32_e32 v0, v42, v0
	v_exp_f32_e32 v47, v1
	v_sub_f32_e32 v1, v115, v38
	v_add_f32_e32 v0, v43, v0
	v_exp_f32_e32 v49, v1
	v_sub_f32_e32 v1, v116, v38
	v_add_f32_e32 v0, v44, v0
	v_exp_f32_e32 v46, v1
	v_sub_f32_e32 v1, v16, v38
	v_add_f32_e32 v0, v45, v0
	v_exp_f32_e32 v48, v1
	v_add_f32_e32 v0, v47, v0
	v_add_f32_e32 v0, v49, v0
	v_add_f32_e32 v0, v46, v0
	v_add_f32_e32 v0, v48, v0
	ds_bpermute_b32 v1, v100, v0
	v_cvt_pk_bf16_f32 v2, v8, v9
	v_cvt_pk_bf16_f32 v3, v10, v11
	s_waitcnt lgkmcnt(0)
	v_add_f32_e32 v39, v0, v1
	ds_bpermute_b32 v40, v101, v39
	v_lshrrev_b32_e32 v0, 2, v32
	v_or_b32_e32 v0, v83, v0
	v_lshlrev_b32_e32 v1, 3, v98
	v_mul_u32_u24_e32 v0, 0x120, v0
	v_and_b32_e32 v1, 24, v1
	v_add3_u32 v41, s27, v0, v1
	v_cvt_pk_bf16_f32 v0, v12, v13
	v_cvt_pk_bf16_f32 v1, v14, v15
	s_cbranch_vccnz .LBB0_1333
	ds_read_b64_tr_b16 v[4:5], v41
	ds_read_b64_tr_b16 v[8:9], v41 offset:32
	ds_read_b64_tr_b16 v[12:13], v41 offset:64
	ds_read_b64_tr_b16 v[16:17], v41 offset:96
	ds_read_b64_tr_b16 v[6:7], v41 offset:4608
	ds_read_b64_tr_b16 v[10:11], v41 offset:4640
	ds_read_b64_tr_b16 v[14:15], v41 offset:4672
	ds_read_b64_tr_b16 v[18:19], v41 offset:4704
	ds_read_b64_tr_b16 v[102:103], v41 offset:128
	ds_read_b64_tr_b16 v[106:107], v41 offset:160
	ds_read_b64_tr_b16 v[110:111], v41 offset:192
	ds_read_b64_tr_b16 v[114:115], v41 offset:224
	ds_read_b64_tr_b16 v[104:105], v41 offset:4736
	ds_read_b64_tr_b16 v[108:109], v41 offset:4768
	ds_read_b64_tr_b16 v[112:113], v41 offset:4800
	ds_read_b64_tr_b16 v[116:117], v41 offset:4832
	s_waitcnt lgkmcnt(11)
	s_setprio 1
	v_mfma_f32_16x16x32_bf16 v[28:31], v[4:7], v[0:3], 0
	s_waitcnt lgkmcnt(10)
	v_mfma_f32_16x16x32_bf16 v[24:27], v[8:11], v[0:3], 0
	s_waitcnt lgkmcnt(9)
	v_mfma_f32_16x16x32_bf16 v[20:23], v[12:15], v[0:3], 0
	s_waitcnt lgkmcnt(8)
	v_mfma_f32_16x16x32_bf16 v[16:19], v[16:19], v[0:3], 0
	s_waitcnt lgkmcnt(3)
	v_mfma_f32_16x16x32_bf16 v[12:15], v[102:105], v[0:3], 0
	s_waitcnt lgkmcnt(2)
	v_mfma_f32_16x16x32_bf16 v[8:11], v[106:109], v[0:3], 0
	s_waitcnt lgkmcnt(1)
	v_mfma_f32_16x16x32_bf16 v[4:7], v[110:113], v[0:3], 0
	s_waitcnt lgkmcnt(0)
	v_mfma_f32_16x16x32_bf16 v[0:3], v[114:117], v[0:3], 0
	s_setprio 0
	s_branch .LBB0_1334

.LBB0_1355:
	s_add_i32 s8, s73, -4
	s_cmp_gt_u32 s8, -11
	s_cselect_b64 s[34:35], -1, 0
	s_cmp_lt_u32 s8, -10
	v_mov_b32_e32 v1, 0
	s_nop 0
	v_mov_b32_e32 v2, 0
	v_mov_b32_e32 v3, 0
	v_mov_b32_e32 v42, 0
	v_mov_b32_e32 v43, 0
	v_mov_b32_e32 v44, 0
	v_mov_b32_e32 v45, 0
	s_cbranch_scc1 .LBB0_1357
	v_or_b32_e32 v42, 48, v98
	v_mad_u32_u24 v42, v42, s33, v32
	ds_read_b128 v[0:3], v83 offset:8704
	ds_read_b128 v[4:7], v83 offset:8768
	ds_read_b128 v[34:37], v83 offset:8832
	ds_read_b128 v[38:41], v83 offset:8896
	ds_read_b128 v[46:49], v42
	ds_read_b128 v[50:53], v42 offset:64
	ds_read_b128 v[54:57], v42 offset:128
	ds_read_b128 v[58:61], v42 offset:192
	s_waitcnt lgkmcnt(7)
	s_setprio 1
	v_mfma_f32_16x16x32_bf16 v[0:3], v[0:3], v[16:19], 0
	s_waitcnt lgkmcnt(6)
	v_mfma_f32_16x16x32_bf16 v[0:3], v[4:7], v[20:23], v[0:3]
	s_waitcnt lgkmcnt(5)
	v_mfma_f32_16x16x32_bf16 v[0:3], v[34:37], v[24:27], v[0:3]
	s_waitcnt lgkmcnt(4)
	v_mfma_f32_16x16x32_bf16 v[42:45], v[38:41], v[28:31], v[0:3]
	s_waitcnt lgkmcnt(3)
	v_mfma_f32_16x16x32_bf16 v[0:3], v[46:49], v[16:19], 0
	s_waitcnt lgkmcnt(2)
	v_mfma_f32_16x16x32_bf16 v[0:3], v[50:53], v[20:23], v[0:3]
	s_waitcnt lgkmcnt(1)
	v_mfma_f32_16x16x32_bf16 v[0:3], v[54:57], v[24:27], v[0:3]
	s_waitcnt lgkmcnt(0)
	v_mfma_f32_16x16x32_bf16 v[0:3], v[58:61], v[28:31], v[0:3]
	s_setprio 0

.LBB0_1359:
	s_add_i32 s8, s73, -8
	s_cmp_gt_u32 s8, -11
	s_cselect_b64 s[20:21], -1, 0
	s_cmp_lt_u32 s8, -10
	v_mov_b32_e32 v5, 0
	v_mov_b32_e32 v6, 0
	v_mov_b32_e32 v7, 0
	v_mov_b32_e32 v58, 0
	v_mov_b32_e32 v59, 0
	v_mov_b32_e32 v60, 0
	v_mov_b32_e32 v61, 0
	s_cbranch_scc1 .LBB0_1361
	v_or_b32_e32 v58, 0x70, v98
	v_mad_u32_u24 v58, v58, s33, v32
	ds_read_b128 v[4:7], v83 offset:26112
	ds_read_b128 v[34:37], v83 offset:26176
	ds_read_b128 v[50:53], v83 offset:26240
	ds_read_b128 v[54:57], v83 offset:26304
	ds_read_b128 v[62:65], v58
	ds_read_b128 v[66:69], v58 offset:64
	ds_read_b128 v[70:73], v58 offset:128
	ds_read_b128 v[74:77], v58 offset:192
	s_waitcnt lgkmcnt(7)
	s_setprio 1
	v_mfma_f32_16x16x32_bf16 v[4:7], v[4:7], v[16:19], 0
	s_waitcnt lgkmcnt(6)
	v_mfma_f32_16x16x32_bf16 v[4:7], v[34:37], v[20:23], v[4:7]
	s_waitcnt lgkmcnt(5)
	v_mfma_f32_16x16x32_bf16 v[4:7], v[50:53], v[24:27], v[4:7]
	s_waitcnt lgkmcnt(4)
	v_mfma_f32_16x16x32_bf16 v[58:61], v[54:57], v[28:31], v[4:7]
	s_waitcnt lgkmcnt(3)
	v_mfma_f32_16x16x32_bf16 v[4:7], v[62:65], v[16:19], 0
	s_waitcnt lgkmcnt(2)
	v_mfma_f32_16x16x32_bf16 v[4:7], v[66:69], v[20:23], v[4:7]
	s_waitcnt lgkmcnt(1)
	v_mfma_f32_16x16x32_bf16 v[4:7], v[70:73], v[24:27], v[4:7]
	s_waitcnt lgkmcnt(0)
	v_mfma_f32_16x16x32_bf16 v[4:7], v[74:77], v[28:31], v[4:7]
	s_setprio 0
.LBB0_1361:
	s_cmp_lt_u32 s73, 10
	v_mov_b32_e32 v34, 0
	s_cselect_b64 s[18:19], -1, 0
	s_cmp_gt_u32 s73, 9
	v_mov_b32_e32 v54, 0
	v_mov_b32_e32 v55, 0
	v_mov_b32_e32 v56, 0
	v_mov_b32_e32 v57, 0
	v_mov_b32_e32 v62, 0
	v_mov_b32_e32 v63, 0
	v_mov_b32_e32 v64, 0
	v_mov_b32_e32 v65, 0
	s_cbranch_scc1 .LBB0_1363
	ds_read_b128 v[50:53], v83 offset:34816
	ds_read_b128 v[54:57], v83 offset:34880
	ds_read_b128 v[62:65], v83 offset:34944
	ds_read_b128 v[66:69], v83 offset:35008
	ds_read_b128 v[70:73], v83 offset:39168
	ds_read_b128 v[74:77], v83 offset:39232
	ds_read_b128 v[78:81], v83 offset:39296
	ds_read_b128 v[86:89], v83 offset:39360
	s_waitcnt lgkmcnt(7)
	s_setprio 1
	v_mfma_f32_16x16x32_bf16 v[50:53], v[50:53], v[16:19], 0
	s_waitcnt lgkmcnt(6)
	v_mfma_f32_16x16x32_bf16 v[50:53], v[54:57], v[20:23], v[50:53]
	s_waitcnt lgkmcnt(5)
	v_mfma_f32_16x16x32_bf16 v[50:53], v[62:65], v[24:27], v[50:53]
	s_waitcnt lgkmcnt(4)
	v_mfma_f32_16x16x32_bf16 v[62:65], v[66:69], v[28:31], v[50:53]
	s_waitcnt lgkmcnt(3)
	v_mfma_f32_16x16x32_bf16 v[50:53], v[70:73], v[16:19], 0
	s_waitcnt lgkmcnt(2)
	v_mfma_f32_16x16x32_bf16 v[50:53], v[74:77], v[20:23], v[50:53]
	s_waitcnt lgkmcnt(1)
	v_mfma_f32_16x16x32_bf16 v[50:53], v[78:81], v[24:27], v[50:53]
	s_waitcnt lgkmcnt(0)
	v_mfma_f32_16x16x32_bf16 v[54:57], v[86:89], v[28:31], v[50:53]
	s_setprio 0
.LBB0_1363:
	s_add_i32 s8, s73, -12
	s_cmp_gt_u32 s8, -11
	s_cselect_b64 s[16:17], -1, 0
	s_cmp_lt_u32 s8, -10
	v_mov_b32_e32 v35, 0
	v_mov_b32_e32 v36, 0
	v_mov_b32_e32 v37, 0
	v_mov_b32_e32 v70, 0
	v_mov_b32_e32 v71, 0
	v_mov_b32_e32 v72, 0
	v_mov_b32_e32 v73, 0
	s_cbranch_scc1 .LBB0_1365
	v_or_b32_e32 v74, 0xb0, v98
	v_mad_u32_u24 v90, v74, s33, v32
	ds_read_b128 v[34:37], v83 offset:43520
	ds_read_b128 v[50:53], v83 offset:43584
	ds_read_b128 v[66:69], v83 offset:43648
	ds_read_b128 v[70:73], v83 offset:43712
	ds_read_b128 v[74:77], v90
	ds_read_b128 v[78:81], v90 offset:64
	ds_read_b128 v[86:89], v90 offset:128
	ds_read_b128 v[90:93], v90 offset:192
	s_waitcnt lgkmcnt(7)
	s_setprio 1
	v_mfma_f32_16x16x32_bf16 v[34:37], v[34:37], v[16:19], 0
	s_waitcnt lgkmcnt(6)
	v_mfma_f32_16x16x32_bf16 v[34:37], v[50:53], v[20:23], v[34:37]
	s_waitcnt lgkmcnt(5)
	v_mfma_f32_16x16x32_bf16 v[34:37], v[66:69], v[24:27], v[34:37]
	s_waitcnt lgkmcnt(4)
	v_mfma_f32_16x16x32_bf16 v[70:73], v[70:73], v[28:31], v[34:37]
	s_waitcnt lgkmcnt(3)
	v_mfma_f32_16x16x32_bf16 v[34:37], v[74:77], v[16:19], 0
	s_waitcnt lgkmcnt(2)
	v_mfma_f32_16x16x32_bf16 v[34:37], v[78:81], v[20:23], v[34:37]
	s_waitcnt lgkmcnt(1)
	v_mfma_f32_16x16x32_bf16 v[34:37], v[86:89], v[24:27], v[34:37]
	s_waitcnt lgkmcnt(0)
	v_mfma_f32_16x16x32_bf16 v[34:37], v[90:93], v[28:31], v[34:37]
	s_setprio 0
.LBB0_1365:
	s_add_i32 s8, s73, -14
	s_cmp_gt_u32 s8, -11
	v_mov_b32_e32 v50, 0
	s_cselect_b64 s[14:15], -1, 0
	s_cmp_lt_u32 s8, -10
	v_mov_b32_e32 v66, 0
	v_mov_b32_e32 v67, 0
	v_mov_b32_e32 v68, 0
	v_mov_b32_e32 v69, 0
	v_mov_b32_e32 v74, 0
	v_mov_b32_e32 v75, 0
	v_mov_b32_e32 v76, 0
	v_mov_b32_e32 v77, 0
	s_cbranch_scc1 .LBB0_1367
	ds_read_b128 v[66:69], v83 offset:52224
	ds_read_b128 v[74:77], v83 offset:52288
	ds_read_b128 v[78:81], v83 offset:52352
	ds_read_b128 v[86:89], v83 offset:52416
	ds_read_b128 v[90:93], v83 offset:56576
	ds_read_b128 v[94:97], v83 offset:56640
	ds_read_b128 v[102:105], v83 offset:56704
	ds_read_b128 v[106:109], v83 offset:56768
	s_waitcnt lgkmcnt(7)
	s_setprio 1
	v_mfma_f32_16x16x32_bf16 v[66:69], v[66:69], v[16:19], 0
	s_waitcnt lgkmcnt(6)
	v_mfma_f32_16x16x32_bf16 v[66:69], v[74:77], v[20:23], v[66:69]
	s_waitcnt lgkmcnt(5)
	v_mfma_f32_16x16x32_bf16 v[66:69], v[78:81], v[24:27], v[66:69]
	s_waitcnt lgkmcnt(4)
	v_mfma_f32_16x16x32_bf16 v[74:77], v[86:89], v[28:31], v[66:69]
	s_waitcnt lgkmcnt(3)
	v_mfma_f32_16x16x32_bf16 v[66:69], v[90:93], v[16:19], 0
	s_waitcnt lgkmcnt(2)
	v_mfma_f32_16x16x32_bf16 v[66:69], v[94:97], v[20:23], v[66:69]
	s_waitcnt lgkmcnt(1)
	v_mfma_f32_16x16x32_bf16 v[66:69], v[102:105], v[24:27], v[66:69]
	s_waitcnt lgkmcnt(0)
	v_mfma_f32_16x16x32_bf16 v[66:69], v[106:109], v[28:31], v[66:69]
	s_setprio 0
.LBB0_1367:
	s_add_i32 s73, s73, -16
	s_cmp_gt_u32 s73, -11
	s_cselect_b64 s[12:13], -1, 0
	s_cmp_lt_u32 s73, -10
	v_mov_b32_e32 v51, 0
	v_mov_b32_e32 v52, 0
	v_mov_b32_e32 v53, 0
	v_mov_b32_e32 v78, 0
	v_mov_b32_e32 v79, 0
	v_mov_b32_e32 v80, 0
	v_mov_b32_e32 v81, 0
	s_cbranch_scc1 .LBB0_1369
	ds_read_b128 v[50:53], v83 offset:60928
	ds_read_b128 v[78:81], v83 offset:60992
	ds_read_b128 v[86:89], v83 offset:61056
	ds_read_b128 v[90:93], v83 offset:61120
	v_or_b32_e32 v83, 0xf0, v98
	v_mad_u32_u24 v32, v83, s33, v32
	ds_read_b128 v[94:97], v32
	ds_read_b128 v[102:105], v32 offset:64
	ds_read_b128 v[106:109], v32 offset:128
	ds_read_b128 v[110:113], v32 offset:192
	s_waitcnt lgkmcnt(7)
	s_setprio 1
	v_mfma_f32_16x16x32_bf16 v[50:53], v[50:53], v[16:19], 0
	s_waitcnt lgkmcnt(3)
	v_mfma_f32_16x16x32_bf16 v[16:19], v[94:97], v[16:19], 0
	v_mfma_f32_16x16x32_bf16 v[50:53], v[78:81], v[20:23], v[50:53]
	s_waitcnt lgkmcnt(2)
	v_mfma_f32_16x16x32_bf16 v[16:19], v[102:105], v[20:23], v[16:19]
	v_mfma_f32_16x16x32_bf16 v[50:53], v[86:89], v[24:27], v[50:53]
	s_waitcnt lgkmcnt(1)
	v_mfma_f32_16x16x32_bf16 v[16:19], v[106:109], v[24:27], v[16:19]
	v_mfma_f32_16x16x32_bf16 v[78:81], v[90:93], v[28:31], v[50:53]
	s_waitcnt lgkmcnt(0)
	v_mfma_f32_16x16x32_bf16 v[50:53], v[110:113], v[28:31], v[16:19]
	s_setprio 0
.LBB0_1369:
	v_readlane_b32 s8, v253, 3
	s_nop 1
	v_max_i32_e32 v16, 0x80, v82
	v_readlane_b32 s9, v253, 4
	v_lshrrev_b32_e32 v18, 2, v98
	v_add_u32_e32 v17, 0x80, v82
	v_cndmask_b32_e64 v16, v82, v16, s[8:9]
	v_and_b32_e32 v83, 12, v18
	v_sub_u32_e32 v17, v17, v16
	v_sub_u32_e32 v16, v16, v83
	v_sub_u32_e32 v18, 0, v16
	v_sub_u32_e32 v222, 1, v16
	v_sub_u32_e32 v250, 2, v16
	v_cmp_gt_u32_e32 vcc, v18, v17
	v_cmp_gt_u32_e64 s[8:9], v222, v17
	v_cmp_gt_u32_e64 s[10:11], v250, v17
	v_cndmask_b32_e32 v12, v12, v225, vcc
	v_cndmask_b32_e64 v13, v13, v225, s[8:9]
	v_cndmask_b32_e64 v14, v14, v225, s[10:11]
	v_sub_u32_e32 v18, 3, v16
	v_sub_u32_e32 v222, 16, v16
	v_sub_u32_e32 v250, 17, v16
	v_cmp_gt_u32_e32 vcc, v18, v17
	v_cmp_gt_u32_e64 s[8:9], v222, v17
	v_cmp_gt_u32_e64 s[10:11], v250, v17
	v_cndmask_b32_e32 v15, v15, v225, vcc
	v_cndmask_b32_e64 v8, v8, v225, s[8:9]
	v_cndmask_b32_e64 v9, v9, v225, s[10:11]
	v_sub_u32_e32 v18, 18, v16
	v_sub_u32_e32 v222, 19, v16
	v_sub_u32_e32 v250, 32, v16
	v_cmp_gt_u32_e32 vcc, v18, v17
	v_cmp_gt_u32_e64 s[8:9], v222, v17
	v_cmp_gt_u32_e64 s[10:11], v250, v17
	v_cndmask_b32_e32 v10, v10, v225, vcc
	v_cndmask_b32_e64 v11, v11, v225, s[8:9]
	v_cndmask_b32_e64 v19, v42, v225, s[10:11]
	v_sub_u32_e32 v18, 33, v16
	v_sub_u32_e32 v222, 34, v16
	v_sub_u32_e32 v250, 35, v16
	v_cmp_gt_u32_e32 vcc, v18, v17
	v_cmp_gt_u32_e64 s[8:9], v222, v17
	v_cmp_gt_u32_e64 s[10:11], v250, v17
	v_cndmask_b32_e32 v20, v43, v225, vcc
	v_cndmask_b32_e64 v21, v44, v225, s[8:9]
	v_cndmask_b32_e64 v22, v45, v225, s[10:11]
	v_sub_u32_e32 v18, 48, v16
	v_sub_u32_e32 v222, 49, v16
	v_sub_u32_e32 v250, 50, v16
	v_cmp_gt_u32_e32 vcc, v18, v17
	v_cmp_gt_u32_e64 s[8:9], v222, v17
	v_cmp_gt_u32_e64 s[10:11], v250, v17
	v_cndmask_b32_e32 v0, v0, v225, vcc
	v_cndmask_b32_e64 v1, v1, v225, s[8:9]
	v_cndmask_b32_e64 v2, v2, v225, s[10:11]
	v_sub_u32_e32 v18, 51, v16
	v_sub_u32_e32 v222, 64, v16
	v_sub_u32_e32 v250, 0x41, v16
	v_cmp_gt_u32_e32 vcc, v18, v17
	v_cmp_gt_u32_e64 s[8:9], v222, v17
	v_cmp_gt_u32_e64 s[10:11], v250, v17
	v_cndmask_b32_e32 v3, v3, v225, vcc
	v_cndmask_b32_e64 v23, v46, v225, s[8:9]
	v_cndmask_b32_e64 v24, v47, v225, s[10:11]
	v_sub_u32_e32 v18, 0x42, v16
	v_sub_u32_e32 v222, 0x43, v16
	v_sub_u32_e32 v250, 0x50, v16
	v_cmp_gt_u32_e32 vcc, v18, v17
	v_cmp_gt_u32_e64 s[8:9], v222, v17
	v_cmp_gt_u32_e64 s[10:11], v250, v17
	v_cndmask_b32_e32 v25, v48, v225, vcc
	v_cndmask_b32_e64 v26, v49, v225, s[8:9]
	v_cndmask_b32_e64 v27, v38, v225, s[10:11]
	v_sub_u32_e32 v18, 0x51, v16
	v_sub_u32_e32 v222, 0x52, v16
	v_sub_u32_e32 v250, 0x53, v16
	v_cmp_gt_u32_e32 vcc, v18, v17
	v_cmp_gt_u32_e64 s[8:9], v222, v17
	v_cmp_gt_u32_e64 s[10:11], v250, v17
	v_cndmask_b32_e32 v28, v39, v225, vcc
	v_cndmask_b32_e64 v29, v40, v225, s[8:9]
	v_cndmask_b32_e64 v30, v41, v225, s[10:11]
	v_sub_u32_e32 v18, 0x60, v16
	v_sub_u32_e32 v222, 0x61, v16
	v_sub_u32_e32 v250, 0x62, v16
	v_cmp_gt_u32_e32 vcc, v18, v17
	v_cmp_gt_u32_e64 s[8:9], v222, v17
	v_cmp_gt_u32_e64 s[10:11], v250, v17
	v_cndmask_b32_e32 v31, v58, v225, vcc
	v_cndmask_b32_e64 v32, v59, v225, s[8:9]
	v_cndmask_b32_e64 v39, v60, v225, s[10:11]
	v_sub_u32_e32 v18, 0x63, v16
	v_sub_u32_e32 v222, 0x70, v16
	v_sub_u32_e32 v250, 0x71, v16
	v_cmp_gt_u32_e32 vcc, v18, v17
	v_cmp_gt_u32_e64 s[8:9], v222, v17
	v_cmp_gt_u32_e64 s[10:11], v250, v17
	v_cndmask_b32_e32 v40, v61, v225, vcc
	v_cndmask_b32_e64 v4, v4, v225, s[8:9]
	v_cndmask_b32_e64 v5, v5, v225, s[10:11]
	v_sub_u32_e32 v18, 0x72, v16
	v_sub_u32_e32 v222, 0x73, v16
	v_sub_u32_e32 v250, 0x80, v16
	v_cmp_gt_u32_e32 vcc, v18, v17
	v_cmp_gt_u32_e64 s[8:9], v222, v17
	v_cmp_gt_u32_e64 s[10:11], v250, v17
	v_cndmask_b32_e32 v6, v6, v225, vcc
	v_cndmask_b32_e64 v7, v7, v225, s[8:9]
	v_cndmask_b32_e64 v41, v62, v225, s[10:11]
	v_sub_u32_e32 v18, 0x81, v16
	v_sub_u32_e32 v222, 0x82, v16
	v_sub_u32_e32 v250, 0x83, v16
	v_cmp_gt_u32_e32 vcc, v18, v17
	v_cmp_gt_u32_e64 s[8:9], v222, v17
	v_cmp_gt_u32_e64 s[10:11], v250, v17
	v_cndmask_b32_e32 v42, v63, v225, vcc
	v_cndmask_b32_e64 v43, v64, v225, s[8:9]
	v_cndmask_b32_e64 v44, v65, v225, s[10:11]
	v_sub_u32_e32 v18, 0x90, v16
	v_sub_u32_e32 v222, 0x91, v16
	v_sub_u32_e32 v250, 0x92, v16
	v_cmp_gt_u32_e32 vcc, v18, v17
	v_cmp_gt_u32_e64 s[8:9], v222, v17
	v_cmp_gt_u32_e64 s[10:11], v250, v17
	v_cndmask_b32_e32 v45, v54, v225, vcc
	v_cndmask_b32_e64 v46, v55, v225, s[8:9]
	v_cndmask_b32_e64 v47, v56, v225, s[10:11]
	v_sub_u32_e32 v18, 0x93, v16
	v_sub_u32_e32 v222, 0xa0, v16
	v_sub_u32_e32 v250, 0xa1, v16
	v_cmp_gt_u32_e32 vcc, v18, v17
	v_cmp_gt_u32_e64 s[8:9], v222, v17
	v_cmp_gt_u32_e64 s[10:11], v250, v17
	v_cndmask_b32_e32 v48, v57, v225, vcc
	v_cndmask_b32_e64 v49, v70, v225, s[8:9]
	v_cndmask_b32_e64 v54, v71, v225, s[10:11]
	v_sub_u32_e32 v18, 0xa2, v16
	v_sub_u32_e32 v222, 0xa3, v16
	v_sub_u32_e32 v250, 0xb0, v16
	v_cmp_gt_u32_e32 vcc, v18, v17
	v_cmp_gt_u32_e64 s[8:9], v222, v17
	v_cmp_gt_u32_e64 s[10:11], v250, v17
	v_cndmask_b32_e32 v55, v72, v225, vcc
	v_cndmask_b32_e64 v56, v73, v225, s[8:9]
	v_cndmask_b32_e64 v34, v34, v225, s[10:11]
	v_sub_u32_e32 v18, 0xb1, v16
	v_sub_u32_e32 v222, 0xb2, v16
	v_sub_u32_e32 v250, 0xb3, v16
	v_cmp_gt_u32_e32 vcc, v18, v17
	v_cmp_gt_u32_e64 s[8:9], v222, v17
	v_cmp_gt_u32_e64 s[10:11], v250, v17
	v_cndmask_b32_e32 v35, v35, v225, vcc
	v_cndmask_b32_e64 v57, v36, v225, s[8:9]
	v_cndmask_b32_e64 v64, v37, v225, s[10:11]
	v_sub_u32_e32 v18, 0xc0, v16
	v_sub_u32_e32 v222, 0xc1, v16
	v_sub_u32_e32 v250, 0xc2, v16
	v_cmp_gt_u32_e32 vcc, v18, v17
	v_cmp_gt_u32_e64 s[8:9], v222, v17
	v_cmp_gt_u32_e64 s[10:11], v250, v17
	v_cndmask_b32_e32 v103, v74, v225, vcc
	v_cndmask_b32_e64 v104, v75, v225, s[8:9]
	v_cndmask_b32_e64 v105, v76, v225, s[10:11]
	v_sub_u32_e32 v18, 0xc3, v16
	v_sub_u32_e32 v222, 0xd0, v16
	v_sub_u32_e32 v250, 0xd1, v16
	v_cmp_gt_u32_e32 vcc, v18, v17
	v_cmp_gt_u32_e64 s[8:9], v222, v17
	v_cmp_gt_u32_e64 s[10:11], v250, v17
	v_cndmask_b32_e32 v106, v77, v225, vcc
	v_cndmask_b32_e64 v107, v66, v225, s[8:9]
	v_cndmask_b32_e64 v108, v67, v225, s[10:11]
	v_sub_u32_e32 v18, 0xd2, v16
	v_sub_u32_e32 v222, 0xd3, v16
	v_sub_u32_e32 v250, 0xe0, v16
	v_cmp_gt_u32_e32 vcc, v18, v17
	v_cmp_gt_u32_e64 s[8:9], v222, v17
	v_cmp_gt_u32_e64 s[10:11], v250, v17
	v_cndmask_b32_e32 v109, v68, v225, vcc
	v_cndmask_b32_e64 v110, v69, v225, s[8:9]
	v_cndmask_b32_e64 v111, v78, v225, s[10:11]
	v_sub_u32_e32 v18, 0xe1, v16
	v_sub_u32_e32 v222, 0xe2, v16
	v_sub_u32_e32 v250, 0xe3, v16
	v_cmp_gt_u32_e32 vcc, v18, v17
	v_cmp_gt_u32_e64 s[8:9], v222, v17
	v_cmp_gt_u32_e64 s[10:11], v250, v17
	v_cndmask_b32_e32 v112, v79, v225, vcc
	v_cndmask_b32_e64 v113, v80, v225, s[8:9]
	v_cndmask_b32_e64 v114, v81, v225, s[10:11]
	v_sub_u32_e32 v18, 0xf0, v16
	v_sub_u32_e32 v222, 0xf1, v16
	v_sub_u32_e32 v250, 0xf2, v16
	v_cmp_gt_u32_e32 vcc, v18, v17
	v_cmp_gt_u32_e64 s[8:9], v222, v17
	v_cmp_gt_u32_e64 s[10:11], v250, v17
	v_cndmask_b32_e32 v115, v50, v225, vcc
	v_cndmask_b32_e64 v116, v51, v225, s[8:9]
	v_cndmask_b32_e64 v117, v52, v225, s[10:11]
	v_sub_u32_e32 v18, 0xf3, v16
	v_cmp_gt_u32_e32 vcc, v18, v17
	s_nop 1
	v_cndmask_b32_e32 v16, v53, v225, vcc
	v_max_f32_e32 v17, v12, v13
	v_max_f32_e32 v18, v14, v15
	s_mov_b32 s8, 0xff61b1e6
	v_max3_f32 v17, v17, v18, s8
	v_max_f32_e32 v18, v8, v9
	v_max_f32_e32 v36, v10, v11
	v_max3_f32 v17, v18, v36, v17
	v_max_f32_e32 v18, v19, v20
	v_max_f32_e32 v36, v21, v22
	v_max3_f32 v17, v18, v36, v17
	v_max_f32_e32 v18, v0, v1
	v_max_f32_e32 v36, v2, v3
	v_max3_f32 v17, v18, v36, v17
	v_max_f32_e32 v18, v23, v24
	v_max_f32_e32 v36, v25, v26
	v_max3_f32 v17, v18, v36, v17
	v_max_f32_e32 v18, v27, v28
	v_max_f32_e32 v36, v29, v30
	v_max3_f32 v17, v18, v36, v17
	v_max_f32_e32 v18, v31, v32
	v_max_f32_e32 v36, v39, v40
	v_max3_f32 v17, v18, v36, v17
	v_max_f32_e32 v18, v4, v5
	v_max_f32_e32 v36, v6, v7
	v_max3_f32 v17, v18, v36, v17
	v_max_f32_e32 v18, v41, v42
	v_max_f32_e32 v36, v43, v44
	v_max3_f32 v17, v18, v36, v17
	v_max_f32_e32 v18, v45, v46
	v_max_f32_e32 v36, v47, v48
	v_max3_f32 v17, v18, v36, v17
	v_max_f32_e32 v18, v49, v54
	v_max_f32_e32 v36, v55, v56
	v_max3_f32 v17, v18, v36, v17
	v_max_f32_e32 v18, v34, v35
	v_max_f32_e32 v36, v57, v64
	v_max3_f32 v17, v18, v36, v17
	v_max_f32_e32 v18, v103, v104
	v_max_f32_e32 v36, v105, v106
	v_max3_f32 v17, v18, v36, v17
	v_max_f32_e32 v18, v107, v108
	v_max_f32_e32 v36, v109, v110
	v_max3_f32 v17, v18, v36, v17
	v_max_f32_e32 v18, v111, v112
	v_max_f32_e32 v36, v113, v114
	v_max3_f32 v17, v18, v36, v17
	v_max_f32_e32 v18, v115, v116
	v_max_f32_e32 v36, v117, v16
	v_max3_f32 v17, v18, v36, v17
	ds_bpermute_b32 v18, v100, v17
	s_andn2_b64 vcc, exec, s[44:45]
	s_waitcnt lgkmcnt(0)
	v_max_f32_e32 v17, v17, v18
	ds_bpermute_b32 v18, v101, v17
	s_waitcnt lgkmcnt(0)
	v_max_f32_e32 v38, v17, v18
	v_sub_f32_e32 v12, v12, v38
	v_exp_f32_e32 v12, v12
	v_sub_f32_e32 v13, v13, v38
	v_exp_f32_e32 v13, v13
	v_sub_f32_e32 v14, v14, v38
	v_exp_f32_e32 v14, v14
	v_sub_f32_e32 v15, v15, v38
	v_exp_f32_e32 v15, v15
	v_sub_f32_e32 v8, v8, v38
	v_add_f32_e32 v17, 0, v12
	v_exp_f32_e32 v8, v8
	v_sub_f32_e32 v9, v9, v38
	v_add_f32_e32 v17, v13, v17
	v_exp_f32_e32 v9, v9
	v_sub_f32_e32 v10, v10, v38
	v_add_f32_e32 v17, v14, v17
	v_exp_f32_e32 v10, v10
	v_sub_f32_e32 v11, v11, v38
	v_add_f32_e32 v17, v15, v17
	v_exp_f32_e32 v11, v11
	v_sub_f32_e32 v18, v19, v38
	v_add_f32_e32 v17, v8, v17
	v_exp_f32_e32 v36, v18
	v_sub_f32_e32 v18, v20, v38
	v_add_f32_e32 v17, v9, v17
	v_exp_f32_e32 v37, v18
	v_sub_f32_e32 v18, v21, v38
	v_add_f32_e32 v17, v10, v17
	v_exp_f32_e32 v94, v18
	v_sub_f32_e32 v18, v22, v38
	v_add_f32_e32 v17, v11, v17
	v_exp_f32_e32 v95, v18
	v_sub_f32_e32 v0, v0, v38
	v_add_f32_e32 v17, v36, v17
	v_exp_f32_e32 v97, v0
	v_sub_f32_e32 v0, v1, v38
	v_add_f32_e32 v17, v37, v17
	v_exp_f32_e32 v102, v0
	v_sub_f32_e32 v0, v2, v38
	v_add_f32_e32 v17, v94, v17
	v_exp_f32_e32 v96, v0
	v_sub_f32_e32 v0, v3, v38
	v_add_f32_e32 v17, v95, v17
	v_exp_f32_e32 v99, v0
	v_sub_f32_e32 v1, v23, v38
	v_add_f32_e32 v0, v97, v17
	v_exp_f32_e32 v86, v1
	v_sub_f32_e32 v1, v24, v38
	v_add_f32_e32 v0, v102, v0
	v_exp_f32_e32 v87, v1
	v_sub_f32_e32 v1, v25, v38
	v_add_f32_e32 v0, v96, v0
	v_exp_f32_e32 v88, v1
	v_sub_f32_e32 v1, v26, v38
	v_add_f32_e32 v0, v99, v0
	v_exp_f32_e32 v89, v1
	v_sub_f32_e32 v1, v27, v38
	v_add_f32_e32 v0, v86, v0
	v_exp_f32_e32 v91, v1
	v_sub_f32_e32 v1, v28, v38
	v_add_f32_e32 v0, v87, v0
	v_exp_f32_e32 v93, v1
	v_sub_f32_e32 v1, v29, v38
	v_add_f32_e32 v0, v88, v0
	v_exp_f32_e32 v90, v1
	v_sub_f32_e32 v1, v30, v38
	v_add_f32_e32 v0, v89, v0
	v_exp_f32_e32 v92, v1
	v_sub_f32_e32 v1, v31, v38
	v_add_f32_e32 v0, v91, v0
	v_exp_f32_e32 v74, v1
	v_sub_f32_e32 v1, v32, v38
	v_add_f32_e32 v0, v93, v0
	v_exp_f32_e32 v75, v1
	v_sub_f32_e32 v1, v39, v38
	v_add_f32_e32 v0, v90, v0
	v_exp_f32_e32 v76, v1
	v_sub_f32_e32 v1, v40, v38
	v_add_f32_e32 v0, v92, v0
	v_exp_f32_e32 v77, v1
	v_sub_f32_e32 v1, v4, v38
	v_add_f32_e32 v0, v74, v0
	v_exp_f32_e32 v79, v1
	v_sub_f32_e32 v1, v5, v38
	v_add_f32_e32 v0, v75, v0
	v_exp_f32_e32 v81, v1
	v_sub_f32_e32 v1, v6, v38
	v_add_f32_e32 v0, v76, v0
	v_exp_f32_e32 v78, v1
	v_sub_f32_e32 v1, v7, v38
	v_add_f32_e32 v0, v77, v0
	v_exp_f32_e32 v80, v1
	v_sub_f32_e32 v1, v41, v38
	v_add_f32_e32 v0, v79, v0
	v_exp_f32_e32 v66, v1
	v_sub_f32_e32 v1, v42, v38
	v_add_f32_e32 v0, v81, v0
	v_exp_f32_e32 v67, v1
	v_sub_f32_e32 v1, v43, v38
	v_add_f32_e32 v0, v78, v0
	v_exp_f32_e32 v68, v1
	v_sub_f32_e32 v1, v44, v38
	v_add_f32_e32 v0, v80, v0
	v_exp_f32_e32 v69, v1
	v_sub_f32_e32 v1, v45, v38
	v_add_f32_e32 v0, v66, v0
	v_exp_f32_e32 v71, v1
	v_sub_f32_e32 v1, v46, v38
	v_add_f32_e32 v0, v67, v0
	v_exp_f32_e32 v73, v1
	v_sub_f32_e32 v1, v47, v38
	v_add_f32_e32 v0, v68, v0
	v_exp_f32_e32 v70, v1
	v_sub_f32_e32 v1, v48, v38
	v_add_f32_e32 v0, v69, v0
	v_exp_f32_e32 v72, v1
	v_sub_f32_e32 v1, v49, v38
	v_add_f32_e32 v0, v71, v0
	v_exp_f32_e32 v58, v1
	v_sub_f32_e32 v1, v54, v38
	v_add_f32_e32 v0, v73, v0
	v_exp_f32_e32 v59, v1
	v_sub_f32_e32 v1, v55, v38
	v_add_f32_e32 v0, v70, v0
	v_exp_f32_e32 v60, v1
	v_sub_f32_e32 v1, v56, v38
	v_add_f32_e32 v0, v72, v0
	v_exp_f32_e32 v61, v1
	v_sub_f32_e32 v1, v34, v38
	v_add_f32_e32 v0, v58, v0
	v_exp_f32_e32 v63, v1
	v_sub_f32_e32 v1, v35, v38
	v_add_f32_e32 v0, v59, v0
	v_exp_f32_e32 v65, v1
	v_sub_f32_e32 v1, v57, v38
	v_add_f32_e32 v0, v60, v0
	v_exp_f32_e32 v62, v1
	v_sub_f32_e32 v1, v64, v38
	v_add_f32_e32 v0, v61, v0
	v_exp_f32_e32 v64, v1
	v_sub_f32_e32 v1, v103, v38
	v_add_f32_e32 v0, v63, v0
	v_exp_f32_e32 v50, v1
	v_sub_f32_e32 v1, v104, v38
	v_add_f32_e32 v0, v65, v0
	v_exp_f32_e32 v51, v1
	v_sub_f32_e32 v1, v105, v38
	v_add_f32_e32 v0, v62, v0
	v_exp_f32_e32 v52, v1
	v_sub_f32_e32 v1, v106, v38
	v_add_f32_e32 v0, v64, v0
	v_exp_f32_e32 v53, v1
	v_sub_f32_e32 v1, v107, v38
	v_add_f32_e32 v0, v50, v0
	v_exp_f32_e32 v55, v1
	v_sub_f32_e32 v1, v108, v38
	v_add_f32_e32 v0, v51, v0
	v_exp_f32_e32 v57, v1
	v_sub_f32_e32 v1, v109, v38
	v_add_f32_e32 v0, v52, v0
	v_exp_f32_e32 v54, v1
	v_sub_f32_e32 v1, v110, v38
	v_add_f32_e32 v0, v53, v0
	v_exp_f32_e32 v56, v1
	v_sub_f32_e32 v1, v111, v38
	v_add_f32_e32 v0, v55, v0
	v_exp_f32_e32 v42, v1
	v_sub_f32_e32 v1, v112, v38
	v_add_f32_e32 v0, v57, v0
	v_exp_f32_e32 v43, v1
	v_sub_f32_e32 v1, v113, v38
	v_add_f32_e32 v0, v54, v0
	v_exp_f32_e32 v44, v1
	v_sub_f32_e32 v1, v114, v38
	v_add_f32_e32 v0, v56, v0
	v_exp_f32_e32 v45, v1
	v_sub_f32_e32 v1, v115, v38
	v_add_f32_e32 v0, v42, v0
	v_exp_f32_e32 v47, v1
	v_sub_f32_e32 v1, v116, v38
	v_add_f32_e32 v0, v43, v0
	v_exp_f32_e32 v49, v1
	v_sub_f32_e32 v1, v117, v38
	v_add_f32_e32 v0, v44, v0
	v_exp_f32_e32 v46, v1
	v_sub_f32_e32 v1, v16, v38
	v_add_f32_e32 v0, v45, v0
	v_exp_f32_e32 v48, v1
	v_add_f32_e32 v0, v47, v0
	v_add_f32_e32 v0, v49, v0
	v_add_f32_e32 v0, v46, v0
	v_add_f32_e32 v0, v48, v0
	ds_bpermute_b32 v1, v100, v0
	v_cvt_pk_bf16_f32 v2, v8, v9
	v_cvt_pk_bf16_f32 v3, v10, v11
	s_waitcnt lgkmcnt(0)
	v_add_f32_e32 v39, v0, v1
	ds_bpermute_b32 v40, v101, v39
	v_lshrrev_b32_e32 v0, 2, v85
	v_or_b32_e32 v0, v83, v0
	v_lshlrev_b32_e32 v1, 3, v98
	v_mul_u32_u24_e32 v0, 0x120, v0
	v_and_b32_e32 v1, 24, v1
	v_add3_u32 v41, s27, v0, v1
	v_cvt_pk_bf16_f32 v0, v12, v13
	v_cvt_pk_bf16_f32 v1, v14, v15
	s_cbranch_vccnz .LBB0_1371
	ds_read_b64_tr_b16 v[4:5], v41
	ds_read_b64_tr_b16 v[8:9], v41 offset:32
	ds_read_b64_tr_b16 v[12:13], v41 offset:64
	ds_read_b64_tr_b16 v[16:17], v41 offset:96
	ds_read_b64_tr_b16 v[6:7], v41 offset:4608
	ds_read_b64_tr_b16 v[10:11], v41 offset:4640
	ds_read_b64_tr_b16 v[14:15], v41 offset:4672
	ds_read_b64_tr_b16 v[18:19], v41 offset:4704
	ds_read_b64_tr_b16 v[104:105], v41 offset:128
	ds_read_b64_tr_b16 v[108:109], v41 offset:160
	ds_read_b64_tr_b16 v[112:113], v41 offset:192
	ds_read_b64_tr_b16 v[116:117], v41 offset:224
	ds_read_b64_tr_b16 v[106:107], v41 offset:4736
	ds_read_b64_tr_b16 v[110:111], v41 offset:4768
	ds_read_b64_tr_b16 v[114:115], v41 offset:4800
	ds_read_b64_tr_b16 v[118:119], v41 offset:4832
	s_waitcnt lgkmcnt(11)
	s_setprio 1
	v_mfma_f32_16x16x32_bf16 v[28:31], v[4:7], v[0:3], 0
	s_waitcnt lgkmcnt(10)
	v_mfma_f32_16x16x32_bf16 v[24:27], v[8:11], v[0:3], 0
	s_waitcnt lgkmcnt(9)
	v_mfma_f32_16x16x32_bf16 v[20:23], v[12:15], v[0:3], 0
	s_waitcnt lgkmcnt(8)
	v_mfma_f32_16x16x32_bf16 v[16:19], v[16:19], v[0:3], 0
	s_waitcnt lgkmcnt(3)
	v_mfma_f32_16x16x32_bf16 v[12:15], v[104:107], v[0:3], 0
	s_waitcnt lgkmcnt(2)
	v_mfma_f32_16x16x32_bf16 v[8:11], v[108:111], v[0:3], 0
	s_waitcnt lgkmcnt(1)
	v_mfma_f32_16x16x32_bf16 v[4:7], v[112:115], v[0:3], 0
	s_waitcnt lgkmcnt(0)
	v_mfma_f32_16x16x32_bf16 v[0:3], v[116:119], v[0:3], 0
	s_setprio 0
	s_branch .LBB0_1372

.LBB0_1372:
	s_andn2_b64 vcc, exec, s[34:35]
	v_cvt_pk_bf16_f32 v34, v36, v37
	v_cvt_pk_bf16_f32 v35, v94, v95
	v_cvt_pk_bf16_f32 v36, v97, v102
	v_cvt_pk_bf16_f32 v37, v96, v99
	s_cbranch_vccnz .LBB0_1374
	ds_read_b64_tr_b16 v[94:95], v41 offset:9216
	ds_read_b64_tr_b16 v[102:103], v41 offset:9248
	ds_read_b64_tr_b16 v[106:107], v41 offset:9280
	ds_read_b64_tr_b16 v[110:111], v41 offset:9312
	ds_read_b64_tr_b16 v[96:97], v41 offset:13824
	ds_read_b64_tr_b16 v[104:105], v41 offset:13856
	ds_read_b64_tr_b16 v[108:109], v41 offset:13888
	ds_read_b64_tr_b16 v[112:113], v41 offset:13920
	ds_read_b64_tr_b16 v[114:115], v41 offset:9344
	ds_read_b64_tr_b16 v[118:119], v41 offset:9376
	ds_read_b64_tr_b16 v[122:123], v41 offset:9408
	ds_read_b64_tr_b16 v[126:127], v41 offset:9440
	ds_read_b64_tr_b16 v[116:117], v41 offset:13952
	ds_read_b64_tr_b16 v[120:121], v41 offset:13984
	ds_read_b64_tr_b16 v[124:125], v41 offset:14016
	ds_read_b64_tr_b16 v[128:129], v41 offset:14048
	s_waitcnt lgkmcnt(11)
	s_setprio 1
	v_mfma_f32_16x16x32_bf16 v[28:31], v[94:97], v[34:37], v[28:31]
	s_waitcnt lgkmcnt(10)
	v_mfma_f32_16x16x32_bf16 v[24:27], v[102:105], v[34:37], v[24:27]
	s_waitcnt lgkmcnt(9)
	v_mfma_f32_16x16x32_bf16 v[20:23], v[106:109], v[34:37], v[20:23]
	s_waitcnt lgkmcnt(8)
	v_mfma_f32_16x16x32_bf16 v[16:19], v[110:113], v[34:37], v[16:19]
	s_waitcnt lgkmcnt(3)
	v_mfma_f32_16x16x32_bf16 v[12:15], v[114:117], v[34:37], v[12:15]
	s_waitcnt lgkmcnt(2)
	v_mfma_f32_16x16x32_bf16 v[8:11], v[118:121], v[34:37], v[8:11]
	s_waitcnt lgkmcnt(1)
	v_mfma_f32_16x16x32_bf16 v[4:7], v[122:125], v[34:37], v[4:7]
	s_waitcnt lgkmcnt(0)
	v_mfma_f32_16x16x32_bf16 v[0:3], v[126:129], v[34:37], v[0:3]
	s_setprio 0
.LBB0_1374:
	s_andn2_b64 vcc, exec, s[30:31]
	v_cvt_pk_bf16_f32 v34, v86, v87
	v_cvt_pk_bf16_f32 v35, v88, v89
	v_cvt_pk_bf16_f32 v36, v91, v93
	v_cvt_pk_bf16_f32 v37, v90, v92
	s_cbranch_vccnz .LBB0_1376
	ds_read_b64_tr_b16 v[86:87], v41 offset:18432
	ds_read_b64_tr_b16 v[90:91], v41 offset:18464
	ds_read_b64_tr_b16 v[94:95], v41 offset:18496
	ds_read_b64_tr_b16 v[102:103], v41 offset:18528
	ds_read_b64_tr_b16 v[88:89], v41 offset:23040
	ds_read_b64_tr_b16 v[92:93], v41 offset:23072
	ds_read_b64_tr_b16 v[96:97], v41 offset:23104
	ds_read_b64_tr_b16 v[104:105], v41 offset:23136
	ds_read_b64_tr_b16 v[106:107], v41 offset:18560
	ds_read_b64_tr_b16 v[110:111], v41 offset:18592
	ds_read_b64_tr_b16 v[114:115], v41 offset:18624
	ds_read_b64_tr_b16 v[118:119], v41 offset:18656
	ds_read_b64_tr_b16 v[108:109], v41 offset:23168
	ds_read_b64_tr_b16 v[112:113], v41 offset:23200
	ds_read_b64_tr_b16 v[116:117], v41 offset:23232
	ds_read_b64_tr_b16 v[120:121], v41 offset:23264
	s_waitcnt lgkmcnt(11)
	s_setprio 1
	v_mfma_f32_16x16x32_bf16 v[28:31], v[86:89], v[34:37], v[28:31]
	s_waitcnt lgkmcnt(10)
	v_mfma_f32_16x16x32_bf16 v[24:27], v[90:93], v[34:37], v[24:27]
	s_waitcnt lgkmcnt(9)
	v_mfma_f32_16x16x32_bf16 v[20:23], v[94:97], v[34:37], v[20:23]
	s_waitcnt lgkmcnt(8)
	v_mfma_f32_16x16x32_bf16 v[16:19], v[102:105], v[34:37], v[16:19]
	s_waitcnt lgkmcnt(3)
	v_mfma_f32_16x16x32_bf16 v[12:15], v[106:109], v[34:37], v[12:15]
	s_waitcnt lgkmcnt(2)
	v_mfma_f32_16x16x32_bf16 v[8:11], v[110:113], v[34:37], v[8:11]
	s_waitcnt lgkmcnt(1)
	v_mfma_f32_16x16x32_bf16 v[4:7], v[114:117], v[34:37], v[4:7]
	s_waitcnt lgkmcnt(0)
	v_mfma_f32_16x16x32_bf16 v[0:3], v[118:121], v[34:37], v[0:3]
	s_setprio 0
.LBB0_1376:
	s_andn2_b64 vcc, exec, s[20:21]
	v_cvt_pk_bf16_f32 v34, v74, v75
	v_cvt_pk_bf16_f32 v35, v76, v77
	v_cvt_pk_bf16_f32 v36, v79, v81
	v_cvt_pk_bf16_f32 v37, v78, v80
	s_cbranch_vccnz .LBB0_1378
	ds_read_b64_tr_b16 v[74:75], v41 offset:27648
	ds_read_b64_tr_b16 v[78:79], v41 offset:27680
	ds_read_b64_tr_b16 v[86:87], v41 offset:27712
	ds_read_b64_tr_b16 v[90:91], v41 offset:27744
	ds_read_b64_tr_b16 v[76:77], v41 offset:32256
	ds_read_b64_tr_b16 v[80:81], v41 offset:32288
	ds_read_b64_tr_b16 v[88:89], v41 offset:32320
	ds_read_b64_tr_b16 v[92:93], v41 offset:32352
	ds_read_b64_tr_b16 v[94:95], v41 offset:27776
	ds_read_b64_tr_b16 v[102:103], v41 offset:27808
	ds_read_b64_tr_b16 v[106:107], v41 offset:27840
	ds_read_b64_tr_b16 v[110:111], v41 offset:27872
	ds_read_b64_tr_b16 v[96:97], v41 offset:32384
	ds_read_b64_tr_b16 v[104:105], v41 offset:32416
	ds_read_b64_tr_b16 v[108:109], v41 offset:32448
	ds_read_b64_tr_b16 v[112:113], v41 offset:32480
	s_waitcnt lgkmcnt(11)
	s_setprio 1
	v_mfma_f32_16x16x32_bf16 v[28:31], v[74:77], v[34:37], v[28:31]
	s_waitcnt lgkmcnt(10)
	v_mfma_f32_16x16x32_bf16 v[24:27], v[78:81], v[34:37], v[24:27]
	s_waitcnt lgkmcnt(9)
	v_mfma_f32_16x16x32_bf16 v[20:23], v[86:89], v[34:37], v[20:23]
	s_waitcnt lgkmcnt(8)
	v_mfma_f32_16x16x32_bf16 v[16:19], v[90:93], v[34:37], v[16:19]
	s_waitcnt lgkmcnt(3)
	v_mfma_f32_16x16x32_bf16 v[12:15], v[94:97], v[34:37], v[12:15]
	s_waitcnt lgkmcnt(2)
	v_mfma_f32_16x16x32_bf16 v[8:11], v[102:105], v[34:37], v[8:11]
	s_waitcnt lgkmcnt(1)
	v_mfma_f32_16x16x32_bf16 v[4:7], v[106:109], v[34:37], v[4:7]
	s_waitcnt lgkmcnt(0)
	v_mfma_f32_16x16x32_bf16 v[0:3], v[110:113], v[34:37], v[0:3]
	s_setprio 0
.LBB0_1378:
	s_andn2_b64 vcc, exec, s[18:19]
	v_cvt_pk_bf16_f32 v34, v66, v67
	v_cvt_pk_bf16_f32 v35, v68, v69
	v_cvt_pk_bf16_f32 v36, v71, v73
	v_cvt_pk_bf16_f32 v37, v70, v72
	s_cbranch_vccnz .LBB0_1380
	ds_read_b64_tr_b16 v[66:67], v41 offset:36864
	ds_read_b64_tr_b16 v[70:71], v41 offset:36896
	ds_read_b64_tr_b16 v[74:75], v41 offset:36928
	ds_read_b64_tr_b16 v[78:79], v41 offset:36960
	ds_read_b64_tr_b16 v[68:69], v41 offset:41472
	ds_read_b64_tr_b16 v[72:73], v41 offset:41504
	ds_read_b64_tr_b16 v[76:77], v41 offset:41536
	ds_read_b64_tr_b16 v[80:81], v41 offset:41568
	ds_read_b64_tr_b16 v[86:87], v41 offset:36992
	ds_read_b64_tr_b16 v[90:91], v41 offset:37024
	ds_read_b64_tr_b16 v[94:95], v41 offset:37056
	ds_read_b64_tr_b16 v[102:103], v41 offset:37088
	ds_read_b64_tr_b16 v[88:89], v41 offset:41600
	ds_read_b64_tr_b16 v[92:93], v41 offset:41632
	ds_read_b64_tr_b16 v[96:97], v41 offset:41664
	ds_read_b64_tr_b16 v[104:105], v41 offset:41696
	s_waitcnt lgkmcnt(11)
	s_setprio 1
	v_mfma_f32_16x16x32_bf16 v[28:31], v[66:69], v[34:37], v[28:31]
	s_waitcnt lgkmcnt(10)
	v_mfma_f32_16x16x32_bf16 v[24:27], v[70:73], v[34:37], v[24:27]
	s_waitcnt lgkmcnt(9)
	v_mfma_f32_16x16x32_bf16 v[20:23], v[74:77], v[34:37], v[20:23]
	s_waitcnt lgkmcnt(8)
	v_mfma_f32_16x16x32_bf16 v[16:19], v[78:81], v[34:37], v[16:19]
	s_waitcnt lgkmcnt(3)
	v_mfma_f32_16x16x32_bf16 v[12:15], v[86:89], v[34:37], v[12:15]
	s_waitcnt lgkmcnt(2)
	v_mfma_f32_16x16x32_bf16 v[8:11], v[90:93], v[34:37], v[8:11]
	s_waitcnt lgkmcnt(1)
	v_mfma_f32_16x16x32_bf16 v[4:7], v[94:97], v[34:37], v[4:7]
	s_waitcnt lgkmcnt(0)
	v_mfma_f32_16x16x32_bf16 v[0:3], v[102:105], v[34:37], v[0:3]
	s_setprio 0
.LBB0_1380:
	s_andn2_b64 vcc, exec, s[16:17]
	v_cvt_pk_bf16_f32 v34, v58, v59
	v_cvt_pk_bf16_f32 v35, v60, v61
	v_cvt_pk_bf16_f32 v36, v63, v65
	v_cvt_pk_bf16_f32 v37, v62, v64
	s_cbranch_vccnz .LBB0_1382
	ds_read_b64_tr_b16 v[58:59], v41 offset:46080
	ds_read_b64_tr_b16 v[62:63], v41 offset:46112
	ds_read_b64_tr_b16 v[66:67], v41 offset:46144
	ds_read_b64_tr_b16 v[70:71], v41 offset:46176
	ds_read_b64_tr_b16 v[60:61], v41 offset:50688
	ds_read_b64_tr_b16 v[64:65], v41 offset:50720
	ds_read_b64_tr_b16 v[68:69], v41 offset:50752
	ds_read_b64_tr_b16 v[72:73], v41 offset:50784
	ds_read_b64_tr_b16 v[74:75], v41 offset:46208
	ds_read_b64_tr_b16 v[78:79], v41 offset:46240
	ds_read_b64_tr_b16 v[86:87], v41 offset:46272
	ds_read_b64_tr_b16 v[90:91], v41 offset:46304
	ds_read_b64_tr_b16 v[76:77], v41 offset:50816
	ds_read_b64_tr_b16 v[80:81], v41 offset:50848
	ds_read_b64_tr_b16 v[88:89], v41 offset:50880
	ds_read_b64_tr_b16 v[92:93], v41 offset:50912
	s_waitcnt lgkmcnt(11)
	s_setprio 1
	v_mfma_f32_16x16x32_bf16 v[28:31], v[58:61], v[34:37], v[28:31]
	s_waitcnt lgkmcnt(10)
	v_mfma_f32_16x16x32_bf16 v[24:27], v[62:65], v[34:37], v[24:27]
	s_waitcnt lgkmcnt(9)
	v_mfma_f32_16x16x32_bf16 v[20:23], v[66:69], v[34:37], v[20:23]
	s_waitcnt lgkmcnt(8)
	v_mfma_f32_16x16x32_bf16 v[16:19], v[70:73], v[34:37], v[16:19]
	s_waitcnt lgkmcnt(3)
	v_mfma_f32_16x16x32_bf16 v[12:15], v[74:77], v[34:37], v[12:15]
	s_waitcnt lgkmcnt(2)
	v_mfma_f32_16x16x32_bf16 v[8:11], v[78:81], v[34:37], v[8:11]
	s_waitcnt lgkmcnt(1)
	v_mfma_f32_16x16x32_bf16 v[4:7], v[86:89], v[34:37], v[4:7]
	s_waitcnt lgkmcnt(0)
	v_mfma_f32_16x16x32_bf16 v[0:3], v[90:93], v[34:37], v[0:3]
	s_setprio 0
